# GEMM K loops: fragment ds_reads issued in MFMA consumption order with counted lgkmcnt waits before each first use instead of one lgkmcnt(0)
# speedup vs baseline: 1.0060x; 1.0054x over previous
.LBB0_195:
	v_mov_b32_e32 v127, 0
	s_andn2_b64 vcc, exec, s[80:81]
	v_mov_b32_e32 v126, v127
	v_mov_b32_e32 v125, v127
	v_mov_b32_e32 v124, v127
	v_mov_b32_e32 v123, v127
	v_mov_b32_e32 v122, v127
	v_mov_b32_e32 v121, v127
	v_mov_b32_e32 v120, v127
	v_mov_b32_e32 v111, v127
	v_mov_b32_e32 v110, v127
	v_mov_b32_e32 v109, v127
	v_mov_b32_e32 v108, v127
	v_mov_b32_e32 v107, v127
	v_mov_b32_e32 v106, v127
	v_mov_b32_e32 v105, v127
	v_mov_b32_e32 v104, v127
	v_mov_b32_e32 v95, v127
	v_mov_b32_e32 v94, v127
	v_mov_b32_e32 v93, v127
	v_mov_b32_e32 v92, v127
	v_mov_b32_e32 v91, v127
	v_mov_b32_e32 v90, v127
	v_mov_b32_e32 v89, v127
	v_mov_b32_e32 v88, v127
	v_mov_b32_e32 v79, v127
	v_mov_b32_e32 v78, v127
	v_mov_b32_e32 v77, v127
	v_mov_b32_e32 v76, v127
	v_mov_b32_e32 v75, v127
	v_mov_b32_e32 v74, v127
	v_mov_b32_e32 v73, v127
	v_mov_b32_e32 v72, v127
	v_mov_b32_e32 v119, v127
	v_mov_b32_e32 v118, v127
	v_mov_b32_e32 v117, v127
	v_mov_b32_e32 v116, v127
	v_mov_b32_e32 v115, v127
	v_mov_b32_e32 v114, v127
	v_mov_b32_e32 v113, v127
	v_mov_b32_e32 v112, v127
	v_mov_b32_e32 v103, v127
	v_mov_b32_e32 v102, v127
	v_mov_b32_e32 v101, v127
	v_mov_b32_e32 v100, v127
	v_mov_b32_e32 v99, v127
	v_mov_b32_e32 v98, v127
	v_mov_b32_e32 v97, v127
	v_mov_b32_e32 v96, v127
	v_mov_b32_e32 v87, v127
	v_mov_b32_e32 v86, v127
	v_mov_b32_e32 v85, v127
	v_mov_b32_e32 v84, v127
	v_mov_b32_e32 v83, v127
	v_mov_b32_e32 v82, v127
	v_mov_b32_e32 v81, v127
	v_mov_b32_e32 v80, v127
	v_mov_b32_e32 v71, v127
	v_mov_b32_e32 v70, v127
	v_mov_b32_e32 v69, v127
	v_mov_b32_e32 v68, v127
	v_mov_b32_e32 v67, v127
	v_mov_b32_e32 v66, v127
	v_mov_b32_e32 v65, v127
	v_mov_b32_e32 v64, v127
	v_mov_b32_e32 v63, v127
	v_mov_b32_e32 v62, v127
	v_mov_b32_e32 v61, v127
	v_mov_b32_e32 v60, v127
	v_mov_b32_e32 v59, v127
	v_mov_b32_e32 v58, v127
	v_mov_b32_e32 v57, v127
	v_mov_b32_e32 v56, v127
	v_mov_b32_e32 v47, v127
	v_mov_b32_e32 v46, v127
	v_mov_b32_e32 v45, v127
	v_mov_b32_e32 v44, v127
	v_mov_b32_e32 v43, v127
	v_mov_b32_e32 v42, v127
	v_mov_b32_e32 v41, v127
	v_mov_b32_e32 v40, v127
	v_mov_b32_e32 v31, v127
	v_mov_b32_e32 v30, v127
	v_mov_b32_e32 v29, v127
	v_mov_b32_e32 v28, v127
	v_mov_b32_e32 v27, v127
	v_mov_b32_e32 v26, v127
	v_mov_b32_e32 v25, v127
	v_mov_b32_e32 v24, v127
	v_mov_b32_e32 v15, v127
	v_mov_b32_e32 v14, v127
	v_mov_b32_e32 v13, v127
	v_mov_b32_e32 v12, v127
	v_mov_b32_e32 v11, v127
	v_mov_b32_e32 v10, v127
	v_mov_b32_e32 v9, v127
	v_mov_b32_e32 v8, v127
	v_mov_b32_e32 v55, v127
	v_mov_b32_e32 v54, v127
	v_mov_b32_e32 v53, v127
	v_mov_b32_e32 v52, v127
	v_mov_b32_e32 v51, v127
	v_mov_b32_e32 v50, v127
	v_mov_b32_e32 v49, v127
	v_mov_b32_e32 v48, v127
	v_mov_b32_e32 v39, v127
	v_mov_b32_e32 v38, v127
	v_mov_b32_e32 v37, v127
	v_mov_b32_e32 v36, v127
	v_mov_b32_e32 v35, v127
	v_mov_b32_e32 v34, v127
	v_mov_b32_e32 v33, v127
	v_mov_b32_e32 v32, v127
	v_mov_b32_e32 v23, v127
	v_mov_b32_e32 v22, v127
	v_mov_b32_e32 v21, v127
	v_mov_b32_e32 v20, v127
	v_mov_b32_e32 v19, v127
	v_mov_b32_e32 v18, v127
	v_mov_b32_e32 v17, v127
	v_mov_b32_e32 v16, v127
	v_mov_b32_e32 v7, v127
	v_mov_b32_e32 v6, v127
	v_mov_b32_e32 v5, v127
	v_mov_b32_e32 v4, v127
	v_mov_b32_e32 v3, v127
	v_mov_b32_e32 v2, v127
	v_mov_b32_e32 v1, v127
	v_mov_b32_e32 v0, v127
	s_cbranch_vccnz .LBB0_198
	s_add_u32 s10, s6, 0x100
	s_addc_u32 s40, s7, 0
	s_add_u32 s6, s38, 0x80
	s_addc_u32 s7, s39, 0
	s_mov_b32 s2, 0
	s_add_i32 s41, s2, 2
	s_add_u32 s21, s6, 0x80
	s_addc_u32 s3, s7, 0
	s_add_i32 s42, 0, 0x10000
	v_add_u32_e32 v140, s42, v154
	ds_read_b128 v[142:145], v140
	ds_read_b128 v[166:169], v140 offset:2048
	ds_read_b128 v[162:165], v140 offset:1024
	ds_read_b128 v[170:173], v140 offset:3072
	s_cmp_eq_u32 s9, s2
	s_cselect_b32 s2, s68, s21
	s_cselect_b32 s3, s69, s3
	s_cselect_b32 s39, s95, s40
	s_cselect_b32 s38, s94, s10
	v_lshl_add_u64 v[226:227], s[6:7], 0, v[138:139]
	s_add_i32 m0, s79, 0xc000
	ds_read_b128 v[174:177], v155
	ds_read_b128 v[182:185], v155 offset:2048
	ds_read_b128 v[206:209], v155 offset:4096
	ds_read_b128 v[218:221], v155 offset:6144
	ds_read_b128 v[178:181], v155 offset:1024
	ds_read_b128 v[186:189], v155 offset:3072
	ds_read_b128 v[214:217], v155 offset:5120
	ds_read_b128 v[222:225], v155 offset:7168
	global_load_lds_dwordx4 v[226:227], off
	v_lshl_add_u64 v[226:227], s[6:7], 0, v[136:137]
	s_add_i32 m0, s79, 0xe000
	s_nop 0
	global_load_lds_dwordx4 v[226:227], off
	s_waitcnt lgkmcnt(8)
	s_barrier
	s_waitcnt lgkmcnt(7)
	v_mfma_f32_16x16x32_bf16 v[124:127], v[142:145], v[174:177], 0
	v_mfma_f32_16x16x32_bf16 v[120:123], v[166:169], v[174:177], 0
	s_waitcnt lgkmcnt(6)
	v_mfma_f32_16x16x32_bf16 v[108:111], v[142:145], v[182:185], 0
	v_mfma_f32_16x16x32_bf16 v[104:107], v[166:169], v[182:185], 0
	s_waitcnt lgkmcnt(5)
	v_mfma_f32_16x16x32_bf16 v[92:95], v[142:145], v[206:209], 0
	v_mfma_f32_16x16x32_bf16 v[88:91], v[166:169], v[206:209], 0
	s_waitcnt lgkmcnt(4)
	v_mfma_f32_16x16x32_bf16 v[76:79], v[142:145], v[218:221], 0
	v_mfma_f32_16x16x32_bf16 v[72:75], v[166:169], v[218:221], 0
	s_waitcnt lgkmcnt(3)
	v_mfma_f32_16x16x32_bf16 v[124:127], v[162:165], v[178:181], v[124:127]
	v_mfma_f32_16x16x32_bf16 v[120:123], v[170:173], v[178:181], v[120:123]
	s_waitcnt lgkmcnt(2)
	v_mfma_f32_16x16x32_bf16 v[108:111], v[162:165], v[186:189], v[108:111]
	v_mfma_f32_16x16x32_bf16 v[104:107], v[170:173], v[186:189], v[104:107]
	s_waitcnt lgkmcnt(1)
	v_mfma_f32_16x16x32_bf16 v[92:95], v[162:165], v[214:217], v[92:95]
	v_mfma_f32_16x16x32_bf16 v[88:91], v[170:173], v[214:217], v[88:91]
	s_waitcnt lgkmcnt(0)
	v_mfma_f32_16x16x32_bf16 v[76:79], v[162:165], v[222:225], v[76:79]
	v_mfma_f32_16x16x32_bf16 v[72:75], v[170:173], v[222:225], v[72:75]
	s_barrier
	s_add_i32 s21, 0, 0x14000
	s_add_i32 s42, s42, s54
	v_add_u32_e32 v140, s21, v154
	v_lshl_add_u64 v[242:243], s[38:39], 0, v[130:131]
	s_mov_b32 m0, s42
	ds_read_b128 v[226:229], v140
	ds_read_b128 v[234:237], v140 offset:2048
	ds_read_b128 v[230:233], v140 offset:1024
	ds_read_b128 v[238:241], v140 offset:3072
	global_load_lds_dwordx4 v[242:243], off
	v_lshl_add_u64 v[244:245], s[38:39], 0, v[128:129]
	s_add_i32 m0, s42, 0x2000
	s_nop 0
	global_load_lds_dwordx4 v[244:245], off
	s_barrier
	s_waitcnt lgkmcnt(3)
	v_mfma_f32_16x16x32_bf16 v[116:119], v[226:229], v[174:177], 0
	s_waitcnt lgkmcnt(2)
	v_mfma_f32_16x16x32_bf16 v[112:115], v[234:237], v[174:177], 0
	v_mfma_f32_16x16x32_bf16 v[100:103], v[226:229], v[182:185], 0
	v_mfma_f32_16x16x32_bf16 v[96:99], v[234:237], v[182:185], 0
	v_mfma_f32_16x16x32_bf16 v[84:87], v[226:229], v[206:209], 0
	v_mfma_f32_16x16x32_bf16 v[80:83], v[234:237], v[206:209], 0
	v_mfma_f32_16x16x32_bf16 v[68:71], v[226:229], v[218:221], 0
	v_mfma_f32_16x16x32_bf16 v[64:67], v[234:237], v[218:221], 0
	s_waitcnt lgkmcnt(1)
	v_mfma_f32_16x16x32_bf16 v[116:119], v[230:233], v[178:181], v[116:119]
	s_waitcnt lgkmcnt(0)
	v_mfma_f32_16x16x32_bf16 v[112:115], v[238:241], v[178:181], v[112:115]
	v_mfma_f32_16x16x32_bf16 v[100:103], v[230:233], v[186:189], v[100:103]
	v_mfma_f32_16x16x32_bf16 v[96:99], v[238:241], v[186:189], v[96:99]
	v_mfma_f32_16x16x32_bf16 v[84:87], v[230:233], v[214:217], v[84:87]
	v_mfma_f32_16x16x32_bf16 v[80:83], v[238:241], v[214:217], v[80:83]
	v_mfma_f32_16x16x32_bf16 v[68:71], v[230:233], v[222:225], v[68:71]
	v_mfma_f32_16x16x32_bf16 v[64:67], v[238:241], v[222:225], v[64:67]
	s_mov_b32 m0, s79
	v_lshl_add_u64 v[246:247], s[2:3], 0, v[130:131]
	s_barrier
	ds_read_b128 v[174:177], v155 offset:16384
	ds_read_b128 v[182:185], v155 offset:18432
	ds_read_b128 v[206:209], v155 offset:20480
	ds_read_b128 v[218:221], v155 offset:22528
	ds_read_b128 v[178:181], v155 offset:17408
	ds_read_b128 v[186:189], v155 offset:19456
	ds_read_b128 v[214:217], v155 offset:21504
	ds_read_b128 v[222:225], v155 offset:23552
	global_load_lds_dwordx4 v[246:247], off
	v_lshl_add_u64 v[248:249], s[2:3], 0, v[128:129]
	s_mov_b32 m0, s34
	s_nop 0
	global_load_lds_dwordx4 v[248:249], off
	s_barrier
	s_waitcnt lgkmcnt(7)
	v_mfma_f32_16x16x32_bf16 v[60:63], v[142:145], v[174:177], 0
	v_mfma_f32_16x16x32_bf16 v[56:59], v[166:169], v[174:177], 0
	s_waitcnt lgkmcnt(6)
	v_mfma_f32_16x16x32_bf16 v[44:47], v[142:145], v[182:185], 0
	v_mfma_f32_16x16x32_bf16 v[40:43], v[166:169], v[182:185], 0
	s_waitcnt lgkmcnt(5)
	v_mfma_f32_16x16x32_bf16 v[28:31], v[142:145], v[206:209], 0
	v_mfma_f32_16x16x32_bf16 v[24:27], v[166:169], v[206:209], 0
	s_waitcnt lgkmcnt(4)
	v_mfma_f32_16x16x32_bf16 v[12:15], v[142:145], v[218:221], 0
	v_mfma_f32_16x16x32_bf16 v[8:11], v[166:169], v[218:221], 0
	s_waitcnt lgkmcnt(3)
	v_mfma_f32_16x16x32_bf16 v[60:63], v[162:165], v[178:181], v[60:63]
	v_mfma_f32_16x16x32_bf16 v[56:59], v[170:173], v[178:181], v[56:59]
	s_waitcnt lgkmcnt(2)
	v_mfma_f32_16x16x32_bf16 v[44:47], v[162:165], v[186:189], v[44:47]
	v_mfma_f32_16x16x32_bf16 v[40:43], v[170:173], v[186:189], v[40:43]
	s_waitcnt lgkmcnt(1)
	v_mfma_f32_16x16x32_bf16 v[28:31], v[162:165], v[214:217], v[28:31]
	v_mfma_f32_16x16x32_bf16 v[24:27], v[170:173], v[214:217], v[24:27]
	s_waitcnt lgkmcnt(0)
	v_mfma_f32_16x16x32_bf16 v[12:15], v[162:165], v[222:225], v[12:15]
	v_mfma_f32_16x16x32_bf16 v[8:11], v[170:173], v[222:225], v[8:11]
	s_barrier
	s_add_u32 s38, s38, s88
	s_addc_u32 s39, s39, s89
	s_add_i32 s21, s21, s54
	v_lshl_add_u64 v[250:251], s[38:39], 0, v[130:131]
	s_mov_b32 m0, s21
	v_lshl_add_u64 v[252:253], s[38:39], 0, v[128:129]
	global_load_lds_dwordx4 v[250:251], off
	s_add_i32 m0, s21, 0x2000
	s_nop 0
	global_load_lds_dwordx4 v[252:253], off
	s_waitcnt vmcnt(6)
	s_barrier
	v_mfma_f32_16x16x32_bf16 v[52:55], v[226:229], v[174:177], 0
	v_mfma_f32_16x16x32_bf16 v[48:51], v[234:237], v[174:177], 0
	v_mfma_f32_16x16x32_bf16 v[36:39], v[226:229], v[182:185], 0
	v_mfma_f32_16x16x32_bf16 v[32:35], v[234:237], v[182:185], 0
	v_mfma_f32_16x16x32_bf16 v[20:23], v[226:229], v[206:209], 0
	v_mfma_f32_16x16x32_bf16 v[16:19], v[234:237], v[206:209], 0
	v_mfma_f32_16x16x32_bf16 v[4:7], v[226:229], v[218:221], 0
	v_mfma_f32_16x16x32_bf16 v[0:3], v[234:237], v[218:221], 0
	v_mfma_f32_16x16x32_bf16 v[52:55], v[230:233], v[178:181], v[52:55]
	v_mfma_f32_16x16x32_bf16 v[48:51], v[238:241], v[178:181], v[48:51]
	v_mfma_f32_16x16x32_bf16 v[36:39], v[230:233], v[186:189], v[36:39]
	v_mfma_f32_16x16x32_bf16 v[32:35], v[238:241], v[186:189], v[32:35]
	v_mfma_f32_16x16x32_bf16 v[20:23], v[230:233], v[214:217], v[20:23]
	v_mfma_f32_16x16x32_bf16 v[16:19], v[238:241], v[214:217], v[16:19]
	v_mfma_f32_16x16x32_bf16 v[4:7], v[230:233], v[222:225], v[4:7]
	v_mfma_f32_16x16x32_bf16 v[0:3], v[238:241], v[222:225], v[0:3]
	s_add_i32 s21, 0, 0x18000
	v_add_u32_e32 v140, s21, v154
	s_barrier
	ds_read_b128 v[142:145], v140
	ds_read_b128 v[166:169], v140 offset:2048
	ds_read_b128 v[162:165], v140 offset:1024
	ds_read_b128 v[170:173], v140 offset:3072
	s_add_u32 s2, s2, s88
	s_addc_u32 s3, s3, s89
	s_mov_b32 m0, s35
	v_lshl_add_u64 v[226:227], s[2:3], 0, v[130:131]
	ds_read_b128 v[174:177], v155 offset:32768
	ds_read_b128 v[182:185], v155 offset:34816
	ds_read_b128 v[206:209], v155 offset:36864
	ds_read_b128 v[218:221], v155 offset:38912
	ds_read_b128 v[178:181], v155 offset:33792
	ds_read_b128 v[186:189], v155 offset:35840
	ds_read_b128 v[214:217], v155 offset:37888
	ds_read_b128 v[222:225], v155 offset:39936
	global_load_lds_dwordx4 v[226:227], off
	v_lshl_add_u64 v[226:227], s[2:3], 0, v[128:129]
	s_mov_b32 m0, s44
	s_nop 0
	global_load_lds_dwordx4 v[226:227], off
	s_waitcnt lgkmcnt(8)
	s_barrier
	s_waitcnt lgkmcnt(7)
	v_mfma_f32_16x16x32_bf16 v[124:127], v[142:145], v[174:177], v[124:127]
	v_mfma_f32_16x16x32_bf16 v[120:123], v[166:169], v[174:177], v[120:123]
	s_waitcnt lgkmcnt(6)
	v_mfma_f32_16x16x32_bf16 v[108:111], v[142:145], v[182:185], v[108:111]
	v_mfma_f32_16x16x32_bf16 v[104:107], v[166:169], v[182:185], v[104:107]
	s_waitcnt lgkmcnt(5)
	v_mfma_f32_16x16x32_bf16 v[92:95], v[142:145], v[206:209], v[92:95]
	v_mfma_f32_16x16x32_bf16 v[88:91], v[166:169], v[206:209], v[88:91]
	s_waitcnt lgkmcnt(4)
	v_mfma_f32_16x16x32_bf16 v[76:79], v[142:145], v[218:221], v[76:79]
	v_mfma_f32_16x16x32_bf16 v[72:75], v[166:169], v[218:221], v[72:75]
	s_waitcnt lgkmcnt(3)
	v_mfma_f32_16x16x32_bf16 v[124:127], v[162:165], v[178:181], v[124:127]
	v_mfma_f32_16x16x32_bf16 v[120:123], v[170:173], v[178:181], v[120:123]
	s_waitcnt lgkmcnt(2)
	v_mfma_f32_16x16x32_bf16 v[108:111], v[162:165], v[186:189], v[108:111]
	v_mfma_f32_16x16x32_bf16 v[104:107], v[170:173], v[186:189], v[104:107]
	s_waitcnt lgkmcnt(1)
	v_mfma_f32_16x16x32_bf16 v[92:95], v[162:165], v[214:217], v[92:95]
	v_mfma_f32_16x16x32_bf16 v[88:91], v[170:173], v[214:217], v[88:91]
	s_waitcnt lgkmcnt(0)
	v_mfma_f32_16x16x32_bf16 v[76:79], v[162:165], v[222:225], v[76:79]
	v_mfma_f32_16x16x32_bf16 v[72:75], v[170:173], v[222:225], v[72:75]
	s_barrier
	s_add_i32 s2, 0, 0x1c000
	s_add_i32 s3, s21, s54
	v_add_u32_e32 v140, s2, v154
	v_lshl_add_u64 v[242:243], v[242:243], 0, s[50:51]
	s_mov_b32 m0, s3
	ds_read_b128 v[226:229], v140
	ds_read_b128 v[234:237], v140 offset:2048
	ds_read_b128 v[230:233], v140 offset:1024
	ds_read_b128 v[238:241], v140 offset:3072
	global_load_lds_dwordx4 v[242:243], off
	v_lshl_add_u64 v[242:243], v[244:245], 0, s[50:51]
	s_add_i32 m0, s3, 0x2000
	s_nop 0
	global_load_lds_dwordx4 v[242:243], off
	s_barrier
	s_waitcnt lgkmcnt(3)
	v_mfma_f32_16x16x32_bf16 v[116:119], v[226:229], v[174:177], v[116:119]
	s_waitcnt lgkmcnt(2)
	v_mfma_f32_16x16x32_bf16 v[112:115], v[234:237], v[174:177], v[112:115]
	v_mfma_f32_16x16x32_bf16 v[100:103], v[226:229], v[182:185], v[100:103]
	v_mfma_f32_16x16x32_bf16 v[96:99], v[234:237], v[182:185], v[96:99]
	v_mfma_f32_16x16x32_bf16 v[84:87], v[226:229], v[206:209], v[84:87]
	v_mfma_f32_16x16x32_bf16 v[80:83], v[234:237], v[206:209], v[80:83]
	v_mfma_f32_16x16x32_bf16 v[68:71], v[226:229], v[218:221], v[68:71]
	v_mfma_f32_16x16x32_bf16 v[64:67], v[234:237], v[218:221], v[64:67]
	s_waitcnt lgkmcnt(1)
	v_mfma_f32_16x16x32_bf16 v[116:119], v[230:233], v[178:181], v[116:119]
	s_waitcnt lgkmcnt(0)
	v_mfma_f32_16x16x32_bf16 v[112:115], v[238:241], v[178:181], v[112:115]
	v_mfma_f32_16x16x32_bf16 v[100:103], v[230:233], v[186:189], v[100:103]
	v_mfma_f32_16x16x32_bf16 v[96:99], v[238:241], v[186:189], v[96:99]
	v_mfma_f32_16x16x32_bf16 v[84:87], v[230:233], v[214:217], v[84:87]
	v_mfma_f32_16x16x32_bf16 v[80:83], v[238:241], v[214:217], v[80:83]
	v_mfma_f32_16x16x32_bf16 v[68:71], v[230:233], v[222:225], v[68:71]
	v_mfma_f32_16x16x32_bf16 v[64:67], v[238:241], v[222:225], v[64:67]
	s_mov_b32 m0, s82
	v_lshl_add_u64 v[242:243], v[246:247], 0, s[50:51]
	s_barrier
	ds_read_b128 v[174:177], v155 offset:49152
	ds_read_b128 v[182:185], v155 offset:51200
	ds_read_b128 v[206:209], v155 offset:53248
	ds_read_b128 v[218:221], v155 offset:55296
	ds_read_b128 v[178:181], v155 offset:50176
	ds_read_b128 v[186:189], v155 offset:52224
	ds_read_b128 v[214:217], v155 offset:54272
	ds_read_b128 v[222:225], v155 offset:56320
	global_load_lds_dwordx4 v[242:243], off
	v_lshl_add_u64 v[242:243], v[248:249], 0, s[50:51]
	s_mov_b32 m0, s83
	s_nop 0
	global_load_lds_dwordx4 v[242:243], off
	s_barrier
	s_waitcnt lgkmcnt(7)
	v_mfma_f32_16x16x32_bf16 v[60:63], v[142:145], v[174:177], v[60:63]
	v_mfma_f32_16x16x32_bf16 v[56:59], v[166:169], v[174:177], v[56:59]
	s_waitcnt lgkmcnt(6)
	v_mfma_f32_16x16x32_bf16 v[44:47], v[142:145], v[182:185], v[44:47]
	v_mfma_f32_16x16x32_bf16 v[40:43], v[166:169], v[182:185], v[40:43]
	s_waitcnt lgkmcnt(5)
	v_mfma_f32_16x16x32_bf16 v[28:31], v[142:145], v[206:209], v[28:31]
	v_mfma_f32_16x16x32_bf16 v[24:27], v[166:169], v[206:209], v[24:27]
	s_waitcnt lgkmcnt(4)
	v_mfma_f32_16x16x32_bf16 v[12:15], v[142:145], v[218:221], v[12:15]
	v_mfma_f32_16x16x32_bf16 v[8:11], v[166:169], v[218:221], v[8:11]
	s_waitcnt lgkmcnt(3)
	v_mfma_f32_16x16x32_bf16 v[60:63], v[162:165], v[178:181], v[60:63]
	v_mfma_f32_16x16x32_bf16 v[56:59], v[170:173], v[178:181], v[56:59]
	s_waitcnt lgkmcnt(2)
	v_mfma_f32_16x16x32_bf16 v[44:47], v[162:165], v[186:189], v[44:47]
	v_mfma_f32_16x16x32_bf16 v[40:43], v[170:173], v[186:189], v[40:43]
	s_waitcnt lgkmcnt(1)
	v_mfma_f32_16x16x32_bf16 v[28:31], v[162:165], v[214:217], v[28:31]
	v_mfma_f32_16x16x32_bf16 v[24:27], v[170:173], v[214:217], v[24:27]
	s_waitcnt lgkmcnt(0)
	v_mfma_f32_16x16x32_bf16 v[12:15], v[162:165], v[222:225], v[12:15]
	v_mfma_f32_16x16x32_bf16 v[8:11], v[170:173], v[222:225], v[8:11]
	s_barrier
	s_add_i32 s2, s2, s54
	v_lshl_add_u64 v[142:143], v[250:251], 0, s[50:51]
	s_mov_b32 m0, s2
	s_nop 0
	global_load_lds_dwordx4 v[142:143], off
	v_lshl_add_u64 v[142:143], v[252:253], 0, s[50:51]
	s_add_i32 m0, s2, 0x2000
	s_nop 0
	global_load_lds_dwordx4 v[142:143], off
	s_waitcnt vmcnt(6)
	s_barrier
	v_mfma_f32_16x16x32_bf16 v[52:55], v[226:229], v[174:177], v[52:55]
	v_mfma_f32_16x16x32_bf16 v[48:51], v[234:237], v[174:177], v[48:51]
	v_mfma_f32_16x16x32_bf16 v[36:39], v[226:229], v[182:185], v[36:39]
	v_mfma_f32_16x16x32_bf16 v[32:35], v[234:237], v[182:185], v[32:35]
	v_mfma_f32_16x16x32_bf16 v[20:23], v[226:229], v[206:209], v[20:23]
	v_mfma_f32_16x16x32_bf16 v[16:19], v[234:237], v[206:209], v[16:19]
	v_mfma_f32_16x16x32_bf16 v[4:7], v[226:229], v[218:221], v[4:7]
	v_mfma_f32_16x16x32_bf16 v[0:3], v[234:237], v[218:221], v[0:3]
	v_mfma_f32_16x16x32_bf16 v[52:55], v[230:233], v[178:181], v[52:55]
	v_mfma_f32_16x16x32_bf16 v[48:51], v[238:241], v[178:181], v[48:51]
	v_mfma_f32_16x16x32_bf16 v[36:39], v[230:233], v[186:189], v[36:39]
	v_mfma_f32_16x16x32_bf16 v[32:35], v[238:241], v[186:189], v[32:35]
	v_mfma_f32_16x16x32_bf16 v[20:23], v[230:233], v[214:217], v[20:23]
	v_mfma_f32_16x16x32_bf16 v[16:19], v[238:241], v[214:217], v[16:19]
	v_mfma_f32_16x16x32_bf16 v[4:7], v[230:233], v[222:225], v[4:7]
	v_mfma_f32_16x16x32_bf16 v[0:3], v[238:241], v[222:225], v[0:3]
	s_add_u32 s10, s10, 0x100
	s_addc_u32 s40, s40, 0
	s_add_u32 s6, s6, 0x100
	s_addc_u32 s7, s7, 0
	s_cmp_ge_i32 s41, s66
	s_mov_b32 s2, s41
	s_barrier
	s_cbranch_scc1 .Lpost_197
.LBB0_197:
	s_add_i32 s41, s2, 2
	s_add_u32 s21, s6, 0x80
	s_addc_u32 s3, s7, 0
	s_add_i32 s42, 0, 0x10000
	v_add_u32_e32 v140, s42, v154
	ds_read_b128 v[142:145], v140
	ds_read_b128 v[166:169], v140 offset:2048
	ds_read_b128 v[162:165], v140 offset:1024
	ds_read_b128 v[170:173], v140 offset:3072
	s_cmp_eq_u32 s9, s2
	s_cselect_b32 s2, s68, s21
	s_cselect_b32 s3, s69, s3
	s_cselect_b32 s39, s95, s40
	s_cselect_b32 s38, s94, s10
	v_lshl_add_u64 v[226:227], s[6:7], 0, v[138:139]
	s_add_i32 m0, s79, 0xc000
	ds_read_b128 v[174:177], v155
	ds_read_b128 v[182:185], v155 offset:2048
	ds_read_b128 v[206:209], v155 offset:4096
	ds_read_b128 v[218:221], v155 offset:6144
	ds_read_b128 v[178:181], v155 offset:1024
	ds_read_b128 v[186:189], v155 offset:3072
	ds_read_b128 v[214:217], v155 offset:5120
	ds_read_b128 v[222:225], v155 offset:7168
	global_load_lds_dwordx4 v[226:227], off
	v_lshl_add_u64 v[226:227], s[6:7], 0, v[136:137]
	s_add_i32 m0, s79, 0xe000
	s_nop 0
	global_load_lds_dwordx4 v[226:227], off
	s_waitcnt lgkmcnt(8)
	s_barrier
	s_waitcnt lgkmcnt(7)
	v_mfma_f32_16x16x32_bf16 v[124:127], v[142:145], v[174:177], v[124:127]
	v_mfma_f32_16x16x32_bf16 v[120:123], v[166:169], v[174:177], v[120:123]
	s_waitcnt lgkmcnt(6)
	v_mfma_f32_16x16x32_bf16 v[108:111], v[142:145], v[182:185], v[108:111]
	v_mfma_f32_16x16x32_bf16 v[104:107], v[166:169], v[182:185], v[104:107]
	s_waitcnt lgkmcnt(5)
	v_mfma_f32_16x16x32_bf16 v[92:95], v[142:145], v[206:209], v[92:95]
	v_mfma_f32_16x16x32_bf16 v[88:91], v[166:169], v[206:209], v[88:91]
	s_waitcnt lgkmcnt(4)
	v_mfma_f32_16x16x32_bf16 v[76:79], v[142:145], v[218:221], v[76:79]
	v_mfma_f32_16x16x32_bf16 v[72:75], v[166:169], v[218:221], v[72:75]
	s_waitcnt lgkmcnt(3)
	v_mfma_f32_16x16x32_bf16 v[124:127], v[162:165], v[178:181], v[124:127]
	v_mfma_f32_16x16x32_bf16 v[120:123], v[170:173], v[178:181], v[120:123]
	s_waitcnt lgkmcnt(2)
	v_mfma_f32_16x16x32_bf16 v[108:111], v[162:165], v[186:189], v[108:111]
	v_mfma_f32_16x16x32_bf16 v[104:107], v[170:173], v[186:189], v[104:107]
	s_waitcnt lgkmcnt(1)
	v_mfma_f32_16x16x32_bf16 v[92:95], v[162:165], v[214:217], v[92:95]
	v_mfma_f32_16x16x32_bf16 v[88:91], v[170:173], v[214:217], v[88:91]
	s_waitcnt lgkmcnt(0)
	v_mfma_f32_16x16x32_bf16 v[76:79], v[162:165], v[222:225], v[76:79]
	v_mfma_f32_16x16x32_bf16 v[72:75], v[170:173], v[222:225], v[72:75]
	s_barrier
	s_add_i32 s21, 0, 0x14000
	s_add_i32 s42, s42, s54
	v_add_u32_e32 v140, s21, v154
	v_lshl_add_u64 v[242:243], s[38:39], 0, v[130:131]
	s_mov_b32 m0, s42
	ds_read_b128 v[226:229], v140
	ds_read_b128 v[234:237], v140 offset:2048
	ds_read_b128 v[230:233], v140 offset:1024
	ds_read_b128 v[238:241], v140 offset:3072
	global_load_lds_dwordx4 v[242:243], off
	v_lshl_add_u64 v[244:245], s[38:39], 0, v[128:129]
	s_add_i32 m0, s42, 0x2000
	s_nop 0
	global_load_lds_dwordx4 v[244:245], off
	s_barrier
	s_waitcnt lgkmcnt(3)
	v_mfma_f32_16x16x32_bf16 v[116:119], v[226:229], v[174:177], v[116:119]
	s_waitcnt lgkmcnt(2)
	v_mfma_f32_16x16x32_bf16 v[112:115], v[234:237], v[174:177], v[112:115]
	v_mfma_f32_16x16x32_bf16 v[100:103], v[226:229], v[182:185], v[100:103]
	v_mfma_f32_16x16x32_bf16 v[96:99], v[234:237], v[182:185], v[96:99]
	v_mfma_f32_16x16x32_bf16 v[84:87], v[226:229], v[206:209], v[84:87]
	v_mfma_f32_16x16x32_bf16 v[80:83], v[234:237], v[206:209], v[80:83]
	v_mfma_f32_16x16x32_bf16 v[68:71], v[226:229], v[218:221], v[68:71]
	v_mfma_f32_16x16x32_bf16 v[64:67], v[234:237], v[218:221], v[64:67]
	s_waitcnt lgkmcnt(1)
	v_mfma_f32_16x16x32_bf16 v[116:119], v[230:233], v[178:181], v[116:119]
	s_waitcnt lgkmcnt(0)
	v_mfma_f32_16x16x32_bf16 v[112:115], v[238:241], v[178:181], v[112:115]
	v_mfma_f32_16x16x32_bf16 v[100:103], v[230:233], v[186:189], v[100:103]
	v_mfma_f32_16x16x32_bf16 v[96:99], v[238:241], v[186:189], v[96:99]
	v_mfma_f32_16x16x32_bf16 v[84:87], v[230:233], v[214:217], v[84:87]
	v_mfma_f32_16x16x32_bf16 v[80:83], v[238:241], v[214:217], v[80:83]
	v_mfma_f32_16x16x32_bf16 v[68:71], v[230:233], v[222:225], v[68:71]
	v_mfma_f32_16x16x32_bf16 v[64:67], v[238:241], v[222:225], v[64:67]
	s_mov_b32 m0, s79
	v_lshl_add_u64 v[246:247], s[2:3], 0, v[130:131]
	s_barrier
	ds_read_b128 v[174:177], v155 offset:16384
	ds_read_b128 v[182:185], v155 offset:18432
	ds_read_b128 v[206:209], v155 offset:20480
	ds_read_b128 v[218:221], v155 offset:22528
	ds_read_b128 v[178:181], v155 offset:17408
	ds_read_b128 v[186:189], v155 offset:19456
	ds_read_b128 v[214:217], v155 offset:21504
	ds_read_b128 v[222:225], v155 offset:23552
	global_load_lds_dwordx4 v[246:247], off
	v_lshl_add_u64 v[248:249], s[2:3], 0, v[128:129]
	s_mov_b32 m0, s34
	s_nop 0
	global_load_lds_dwordx4 v[248:249], off
	s_barrier
	s_waitcnt lgkmcnt(7)
	v_mfma_f32_16x16x32_bf16 v[60:63], v[142:145], v[174:177], v[60:63]
	v_mfma_f32_16x16x32_bf16 v[56:59], v[166:169], v[174:177], v[56:59]
	s_waitcnt lgkmcnt(6)
	v_mfma_f32_16x16x32_bf16 v[44:47], v[142:145], v[182:185], v[44:47]
	v_mfma_f32_16x16x32_bf16 v[40:43], v[166:169], v[182:185], v[40:43]
	s_waitcnt lgkmcnt(5)
	v_mfma_f32_16x16x32_bf16 v[28:31], v[142:145], v[206:209], v[28:31]
	v_mfma_f32_16x16x32_bf16 v[24:27], v[166:169], v[206:209], v[24:27]
	s_waitcnt lgkmcnt(4)
	v_mfma_f32_16x16x32_bf16 v[12:15], v[142:145], v[218:221], v[12:15]
	v_mfma_f32_16x16x32_bf16 v[8:11], v[166:169], v[218:221], v[8:11]
	s_waitcnt lgkmcnt(3)
	v_mfma_f32_16x16x32_bf16 v[60:63], v[162:165], v[178:181], v[60:63]
	v_mfma_f32_16x16x32_bf16 v[56:59], v[170:173], v[178:181], v[56:59]
	s_waitcnt lgkmcnt(2)
	v_mfma_f32_16x16x32_bf16 v[44:47], v[162:165], v[186:189], v[44:47]
	v_mfma_f32_16x16x32_bf16 v[40:43], v[170:173], v[186:189], v[40:43]
	s_waitcnt lgkmcnt(1)
	v_mfma_f32_16x16x32_bf16 v[28:31], v[162:165], v[214:217], v[28:31]
	v_mfma_f32_16x16x32_bf16 v[24:27], v[170:173], v[214:217], v[24:27]
	s_waitcnt lgkmcnt(0)
	v_mfma_f32_16x16x32_bf16 v[12:15], v[162:165], v[222:225], v[12:15]
	v_mfma_f32_16x16x32_bf16 v[8:11], v[170:173], v[222:225], v[8:11]
	s_barrier
	s_add_u32 s38, s38, s88
	s_addc_u32 s39, s39, s89
	s_add_i32 s21, s21, s54
	v_lshl_add_u64 v[250:251], s[38:39], 0, v[130:131]
	s_mov_b32 m0, s21
	v_lshl_add_u64 v[252:253], s[38:39], 0, v[128:129]
	global_load_lds_dwordx4 v[250:251], off
	s_add_i32 m0, s21, 0x2000
	s_nop 0
	global_load_lds_dwordx4 v[252:253], off
	s_waitcnt vmcnt(6)
	s_barrier
	v_mfma_f32_16x16x32_bf16 v[52:55], v[226:229], v[174:177], v[52:55]
	v_mfma_f32_16x16x32_bf16 v[48:51], v[234:237], v[174:177], v[48:51]
	v_mfma_f32_16x16x32_bf16 v[36:39], v[226:229], v[182:185], v[36:39]
	v_mfma_f32_16x16x32_bf16 v[32:35], v[234:237], v[182:185], v[32:35]
	v_mfma_f32_16x16x32_bf16 v[20:23], v[226:229], v[206:209], v[20:23]
	v_mfma_f32_16x16x32_bf16 v[16:19], v[234:237], v[206:209], v[16:19]
	v_mfma_f32_16x16x32_bf16 v[4:7], v[226:229], v[218:221], v[4:7]
	v_mfma_f32_16x16x32_bf16 v[0:3], v[234:237], v[218:221], v[0:3]
	v_mfma_f32_16x16x32_bf16 v[52:55], v[230:233], v[178:181], v[52:55]
	v_mfma_f32_16x16x32_bf16 v[48:51], v[238:241], v[178:181], v[48:51]
	v_mfma_f32_16x16x32_bf16 v[36:39], v[230:233], v[186:189], v[36:39]
	v_mfma_f32_16x16x32_bf16 v[32:35], v[238:241], v[186:189], v[32:35]
	v_mfma_f32_16x16x32_bf16 v[20:23], v[230:233], v[214:217], v[20:23]
	v_mfma_f32_16x16x32_bf16 v[16:19], v[238:241], v[214:217], v[16:19]
	v_mfma_f32_16x16x32_bf16 v[4:7], v[230:233], v[222:225], v[4:7]
	v_mfma_f32_16x16x32_bf16 v[0:3], v[238:241], v[222:225], v[0:3]
	s_add_i32 s21, 0, 0x18000
	v_add_u32_e32 v140, s21, v154
	s_barrier
	ds_read_b128 v[142:145], v140
	ds_read_b128 v[166:169], v140 offset:2048
	ds_read_b128 v[162:165], v140 offset:1024
	ds_read_b128 v[170:173], v140 offset:3072
	s_add_u32 s2, s2, s88
	s_addc_u32 s3, s3, s89
	s_mov_b32 m0, s35
	v_lshl_add_u64 v[226:227], s[2:3], 0, v[130:131]
	ds_read_b128 v[174:177], v155 offset:32768
	ds_read_b128 v[182:185], v155 offset:34816
	ds_read_b128 v[206:209], v155 offset:36864
	ds_read_b128 v[218:221], v155 offset:38912
	ds_read_b128 v[178:181], v155 offset:33792
	ds_read_b128 v[186:189], v155 offset:35840
	ds_read_b128 v[214:217], v155 offset:37888
	ds_read_b128 v[222:225], v155 offset:39936
	global_load_lds_dwordx4 v[226:227], off
	v_lshl_add_u64 v[226:227], s[2:3], 0, v[128:129]
	s_mov_b32 m0, s44
	s_nop 0
	global_load_lds_dwordx4 v[226:227], off
	s_waitcnt lgkmcnt(8)
	s_barrier
	s_waitcnt lgkmcnt(7)
	v_mfma_f32_16x16x32_bf16 v[124:127], v[142:145], v[174:177], v[124:127]
	v_mfma_f32_16x16x32_bf16 v[120:123], v[166:169], v[174:177], v[120:123]
	s_waitcnt lgkmcnt(6)
	v_mfma_f32_16x16x32_bf16 v[108:111], v[142:145], v[182:185], v[108:111]
	v_mfma_f32_16x16x32_bf16 v[104:107], v[166:169], v[182:185], v[104:107]
	s_waitcnt lgkmcnt(5)
	v_mfma_f32_16x16x32_bf16 v[92:95], v[142:145], v[206:209], v[92:95]
	v_mfma_f32_16x16x32_bf16 v[88:91], v[166:169], v[206:209], v[88:91]
	s_waitcnt lgkmcnt(4)
	v_mfma_f32_16x16x32_bf16 v[76:79], v[142:145], v[218:221], v[76:79]
	v_mfma_f32_16x16x32_bf16 v[72:75], v[166:169], v[218:221], v[72:75]
	s_waitcnt lgkmcnt(3)
	v_mfma_f32_16x16x32_bf16 v[124:127], v[162:165], v[178:181], v[124:127]
	v_mfma_f32_16x16x32_bf16 v[120:123], v[170:173], v[178:181], v[120:123]
	s_waitcnt lgkmcnt(2)
	v_mfma_f32_16x16x32_bf16 v[108:111], v[162:165], v[186:189], v[108:111]
	v_mfma_f32_16x16x32_bf16 v[104:107], v[170:173], v[186:189], v[104:107]
	s_waitcnt lgkmcnt(1)
	v_mfma_f32_16x16x32_bf16 v[92:95], v[162:165], v[214:217], v[92:95]
	v_mfma_f32_16x16x32_bf16 v[88:91], v[170:173], v[214:217], v[88:91]
	s_waitcnt lgkmcnt(0)
	v_mfma_f32_16x16x32_bf16 v[76:79], v[162:165], v[222:225], v[76:79]
	v_mfma_f32_16x16x32_bf16 v[72:75], v[170:173], v[222:225], v[72:75]
	s_barrier
	s_add_i32 s2, 0, 0x1c000
	s_add_i32 s3, s21, s54
	v_add_u32_e32 v140, s2, v154
	v_lshl_add_u64 v[242:243], v[242:243], 0, s[50:51]
	s_mov_b32 m0, s3
	ds_read_b128 v[226:229], v140
	ds_read_b128 v[234:237], v140 offset:2048
	ds_read_b128 v[230:233], v140 offset:1024
	ds_read_b128 v[238:241], v140 offset:3072
	global_load_lds_dwordx4 v[242:243], off
	v_lshl_add_u64 v[242:243], v[244:245], 0, s[50:51]
	s_add_i32 m0, s3, 0x2000
	s_nop 0
	global_load_lds_dwordx4 v[242:243], off
	s_barrier
	s_waitcnt lgkmcnt(3)
	v_mfma_f32_16x16x32_bf16 v[116:119], v[226:229], v[174:177], v[116:119]
	s_waitcnt lgkmcnt(2)
	v_mfma_f32_16x16x32_bf16 v[112:115], v[234:237], v[174:177], v[112:115]
	v_mfma_f32_16x16x32_bf16 v[100:103], v[226:229], v[182:185], v[100:103]
	v_mfma_f32_16x16x32_bf16 v[96:99], v[234:237], v[182:185], v[96:99]
	v_mfma_f32_16x16x32_bf16 v[84:87], v[226:229], v[206:209], v[84:87]
	v_mfma_f32_16x16x32_bf16 v[80:83], v[234:237], v[206:209], v[80:83]
	v_mfma_f32_16x16x32_bf16 v[68:71], v[226:229], v[218:221], v[68:71]
	v_mfma_f32_16x16x32_bf16 v[64:67], v[234:237], v[218:221], v[64:67]
	s_waitcnt lgkmcnt(1)
	v_mfma_f32_16x16x32_bf16 v[116:119], v[230:233], v[178:181], v[116:119]
	s_waitcnt lgkmcnt(0)
	v_mfma_f32_16x16x32_bf16 v[112:115], v[238:241], v[178:181], v[112:115]
	v_mfma_f32_16x16x32_bf16 v[100:103], v[230:233], v[186:189], v[100:103]
	v_mfma_f32_16x16x32_bf16 v[96:99], v[238:241], v[186:189], v[96:99]
	v_mfma_f32_16x16x32_bf16 v[84:87], v[230:233], v[214:217], v[84:87]
	v_mfma_f32_16x16x32_bf16 v[80:83], v[238:241], v[214:217], v[80:83]
	v_mfma_f32_16x16x32_bf16 v[68:71], v[230:233], v[222:225], v[68:71]
	v_mfma_f32_16x16x32_bf16 v[64:67], v[238:241], v[222:225], v[64:67]
	s_mov_b32 m0, s82
	v_lshl_add_u64 v[242:243], v[246:247], 0, s[50:51]
	s_barrier
	ds_read_b128 v[174:177], v155 offset:49152
	ds_read_b128 v[182:185], v155 offset:51200
	ds_read_b128 v[206:209], v155 offset:53248
	ds_read_b128 v[218:221], v155 offset:55296
	ds_read_b128 v[178:181], v155 offset:50176
	ds_read_b128 v[186:189], v155 offset:52224
	ds_read_b128 v[214:217], v155 offset:54272
	ds_read_b128 v[222:225], v155 offset:56320
	global_load_lds_dwordx4 v[242:243], off
	v_lshl_add_u64 v[242:243], v[248:249], 0, s[50:51]
	s_mov_b32 m0, s83
	s_nop 0
	global_load_lds_dwordx4 v[242:243], off
	s_barrier
	s_waitcnt lgkmcnt(7)
	v_mfma_f32_16x16x32_bf16 v[60:63], v[142:145], v[174:177], v[60:63]
	v_mfma_f32_16x16x32_bf16 v[56:59], v[166:169], v[174:177], v[56:59]
	s_waitcnt lgkmcnt(6)
	v_mfma_f32_16x16x32_bf16 v[44:47], v[142:145], v[182:185], v[44:47]
	v_mfma_f32_16x16x32_bf16 v[40:43], v[166:169], v[182:185], v[40:43]
	s_waitcnt lgkmcnt(5)
	v_mfma_f32_16x16x32_bf16 v[28:31], v[142:145], v[206:209], v[28:31]
	v_mfma_f32_16x16x32_bf16 v[24:27], v[166:169], v[206:209], v[24:27]
	s_waitcnt lgkmcnt(4)
	v_mfma_f32_16x16x32_bf16 v[12:15], v[142:145], v[218:221], v[12:15]
	v_mfma_f32_16x16x32_bf16 v[8:11], v[166:169], v[218:221], v[8:11]
	s_waitcnt lgkmcnt(3)
	v_mfma_f32_16x16x32_bf16 v[60:63], v[162:165], v[178:181], v[60:63]
	v_mfma_f32_16x16x32_bf16 v[56:59], v[170:173], v[178:181], v[56:59]
	s_waitcnt lgkmcnt(2)
	v_mfma_f32_16x16x32_bf16 v[44:47], v[162:165], v[186:189], v[44:47]
	v_mfma_f32_16x16x32_bf16 v[40:43], v[170:173], v[186:189], v[40:43]
	s_waitcnt lgkmcnt(1)
	v_mfma_f32_16x16x32_bf16 v[28:31], v[162:165], v[214:217], v[28:31]
	v_mfma_f32_16x16x32_bf16 v[24:27], v[170:173], v[214:217], v[24:27]
	s_waitcnt lgkmcnt(0)
	v_mfma_f32_16x16x32_bf16 v[12:15], v[162:165], v[222:225], v[12:15]
	v_mfma_f32_16x16x32_bf16 v[8:11], v[170:173], v[222:225], v[8:11]
	s_barrier
	s_add_i32 s2, s2, s54
	v_lshl_add_u64 v[142:143], v[250:251], 0, s[50:51]
	s_mov_b32 m0, s2
	s_nop 0
	global_load_lds_dwordx4 v[142:143], off
	v_lshl_add_u64 v[142:143], v[252:253], 0, s[50:51]
	s_add_i32 m0, s2, 0x2000
	s_nop 0
	global_load_lds_dwordx4 v[142:143], off
	s_waitcnt vmcnt(6)
	s_barrier
	v_mfma_f32_16x16x32_bf16 v[52:55], v[226:229], v[174:177], v[52:55]
	v_mfma_f32_16x16x32_bf16 v[48:51], v[234:237], v[174:177], v[48:51]
	v_mfma_f32_16x16x32_bf16 v[36:39], v[226:229], v[182:185], v[36:39]
	v_mfma_f32_16x16x32_bf16 v[32:35], v[234:237], v[182:185], v[32:35]
	v_mfma_f32_16x16x32_bf16 v[20:23], v[226:229], v[206:209], v[20:23]
	v_mfma_f32_16x16x32_bf16 v[16:19], v[234:237], v[206:209], v[16:19]
	v_mfma_f32_16x16x32_bf16 v[4:7], v[226:229], v[218:221], v[4:7]
	v_mfma_f32_16x16x32_bf16 v[0:3], v[234:237], v[218:221], v[0:3]
	v_mfma_f32_16x16x32_bf16 v[52:55], v[230:233], v[178:181], v[52:55]
	v_mfma_f32_16x16x32_bf16 v[48:51], v[238:241], v[178:181], v[48:51]
	v_mfma_f32_16x16x32_bf16 v[36:39], v[230:233], v[186:189], v[36:39]
	v_mfma_f32_16x16x32_bf16 v[32:35], v[238:241], v[186:189], v[32:35]
	v_mfma_f32_16x16x32_bf16 v[20:23], v[230:233], v[214:217], v[20:23]
	v_mfma_f32_16x16x32_bf16 v[16:19], v[238:241], v[214:217], v[16:19]
	v_mfma_f32_16x16x32_bf16 v[4:7], v[230:233], v[222:225], v[4:7]
	v_mfma_f32_16x16x32_bf16 v[0:3], v[238:241], v[222:225], v[0:3]
	s_add_u32 s10, s10, 0x100
	s_addc_u32 s40, s40, 0
	s_add_u32 s6, s6, 0x100
	s_addc_u32 s7, s7, 0
	s_cmp_ge_i32 s41, s66
	s_mov_b32 s2, s41
	s_barrier
	s_cbranch_scc0 .LBB0_197

.LBB0_270:
	v_lshl_add_u64 v[0:1], s[40:41], 0, v[156:157]
	v_mov_b32_e32 v129, v157
	v_lshl_add_u64 v[4:5], s[2:3], 0, v[156:157]
	v_lshl_add_u64 v[6:7], s[2:3], 0, v[128:129]
	s_lshl_b32 s2, s19, 5
	s_add_i32 m0, s25, 0x18000
	v_lshl_add_u64 v[0:1], v[0:1], 0, s[50:51]
	s_and_b32 s19, s2, 0x60
	s_waitcnt vmcnt(4)
	s_barrier
	global_load_lds_dwordx4 v[0:1], off
	s_add_i32 m0, s25, 0x1a000
	v_lshl_add_u64 v[2:3], s[40:41], 0, v[128:129]
	s_add_u32 s2, s26, 0x1a4a4080
	v_lshl_add_u64 v[0:1], v[2:3], 0, s[50:51]
	s_addc_u32 s3, s27, 0
	s_add_i32 s45, s25, 0x8000
	global_load_lds_dwordx4 v[0:1], off
	v_lshl_add_u64 v[0:1], s[2:3], 0, v[156:157]
	s_mov_b32 m0, s45
	s_add_i32 s48, s25, 0xa000
	global_load_lds_dwordx4 v[0:1], off
	v_lshl_add_u64 v[0:1], s[2:3], 0, v[128:129]
	s_mov_b32 m0, s48
	v_mov_b32_e32 v127, 0
	global_load_lds_dwordx4 v[0:1], off
	s_add_i32 m0, s25, 0x1c000
	v_lshl_add_u64 v[0:1], v[4:5], 0, s[50:51]
	global_load_lds_dwordx4 v[0:1], off
	v_lshl_add_u64 v[0:1], v[6:7], 0, s[50:51]
	s_add_i32 m0, s25, 0x1e000
	v_lshl_or_b32 v134, s42, 6, v149
	global_load_lds_dwordx4 v[0:1], off
	s_waitcnt vmcnt(6)
	s_cmp_lt_i32 s6, 64
	v_mov_b32_e32 v126, v127
	v_mov_b32_e32 v125, v127
	v_mov_b32_e32 v124, v127
	v_mov_b32_e32 v123, v127
	v_mov_b32_e32 v122, v127
	v_mov_b32_e32 v121, v127
	v_mov_b32_e32 v120, v127
	v_mov_b32_e32 v111, v127
	v_mov_b32_e32 v110, v127
	v_mov_b32_e32 v109, v127
	v_mov_b32_e32 v108, v127
	v_mov_b32_e32 v107, v127
	v_mov_b32_e32 v106, v127
	v_mov_b32_e32 v105, v127
	v_mov_b32_e32 v104, v127
	v_mov_b32_e32 v95, v127
	v_mov_b32_e32 v94, v127
	v_mov_b32_e32 v93, v127
	v_mov_b32_e32 v92, v127
	v_mov_b32_e32 v91, v127
	v_mov_b32_e32 v90, v127
	v_mov_b32_e32 v89, v127
	v_mov_b32_e32 v88, v127
	v_mov_b32_e32 v79, v127
	v_mov_b32_e32 v78, v127
	v_mov_b32_e32 v77, v127
	v_mov_b32_e32 v76, v127
	v_mov_b32_e32 v75, v127
	v_mov_b32_e32 v74, v127
	v_mov_b32_e32 v73, v127
	v_mov_b32_e32 v72, v127
	v_mov_b32_e32 v119, v127
	v_mov_b32_e32 v118, v127
	v_mov_b32_e32 v117, v127
	v_mov_b32_e32 v116, v127
	v_mov_b32_e32 v115, v127
	v_mov_b32_e32 v114, v127
	v_mov_b32_e32 v113, v127
	v_mov_b32_e32 v112, v127
	v_mov_b32_e32 v103, v127
	v_mov_b32_e32 v102, v127
	v_mov_b32_e32 v101, v127
	v_mov_b32_e32 v100, v127
	v_mov_b32_e32 v99, v127
	v_mov_b32_e32 v98, v127
	v_mov_b32_e32 v97, v127
	v_mov_b32_e32 v96, v127
	v_mov_b32_e32 v87, v127
	v_mov_b32_e32 v86, v127
	v_mov_b32_e32 v85, v127
	v_mov_b32_e32 v84, v127
	v_mov_b32_e32 v83, v127
	v_mov_b32_e32 v82, v127
	v_mov_b32_e32 v81, v127
	v_mov_b32_e32 v80, v127
	v_mov_b32_e32 v71, v127
	v_mov_b32_e32 v70, v127
	v_mov_b32_e32 v69, v127
	v_mov_b32_e32 v68, v127
	v_mov_b32_e32 v67, v127
	v_mov_b32_e32 v66, v127
	v_mov_b32_e32 v65, v127
	v_mov_b32_e32 v64, v127
	v_mov_b32_e32 v63, v127
	v_mov_b32_e32 v62, v127
	v_mov_b32_e32 v61, v127
	v_mov_b32_e32 v60, v127
	v_mov_b32_e32 v59, v127
	v_mov_b32_e32 v58, v127
	v_mov_b32_e32 v57, v127
	v_mov_b32_e32 v56, v127
	v_mov_b32_e32 v47, v127
	v_mov_b32_e32 v46, v127
	v_mov_b32_e32 v45, v127
	v_mov_b32_e32 v44, v127
	v_mov_b32_e32 v43, v127
	v_mov_b32_e32 v42, v127
	v_mov_b32_e32 v41, v127
	v_mov_b32_e32 v40, v127
	v_mov_b32_e32 v31, v127
	v_mov_b32_e32 v30, v127
	v_mov_b32_e32 v29, v127
	v_mov_b32_e32 v28, v127
	v_mov_b32_e32 v27, v127
	v_mov_b32_e32 v26, v127
	v_mov_b32_e32 v25, v127
	v_mov_b32_e32 v24, v127
	v_mov_b32_e32 v15, v127
	v_mov_b32_e32 v14, v127
	v_mov_b32_e32 v13, v127
	v_mov_b32_e32 v12, v127
	v_mov_b32_e32 v11, v127
	v_mov_b32_e32 v10, v127
	v_mov_b32_e32 v9, v127
	v_mov_b32_e32 v8, v127
	v_mov_b32_e32 v55, v127
	v_mov_b32_e32 v54, v127
	v_mov_b32_e32 v53, v127
	v_mov_b32_e32 v52, v127
	v_mov_b32_e32 v51, v127
	v_mov_b32_e32 v50, v127
	v_mov_b32_e32 v49, v127
	v_mov_b32_e32 v48, v127
	v_mov_b32_e32 v39, v127
	v_mov_b32_e32 v38, v127
	v_mov_b32_e32 v37, v127
	v_mov_b32_e32 v36, v127
	v_mov_b32_e32 v35, v127
	v_mov_b32_e32 v34, v127
	v_mov_b32_e32 v33, v127
	v_mov_b32_e32 v32, v127
	v_mov_b32_e32 v23, v127
	v_mov_b32_e32 v22, v127
	v_mov_b32_e32 v21, v127
	v_mov_b32_e32 v20, v127
	v_mov_b32_e32 v19, v127
	v_mov_b32_e32 v18, v127
	v_mov_b32_e32 v17, v127
	v_mov_b32_e32 v16, v127
	v_mov_b32_e32 v7, v127
	v_mov_b32_e32 v6, v127
	v_mov_b32_e32 v5, v127
	v_mov_b32_e32 v4, v127
	v_mov_b32_e32 v3, v127
	v_mov_b32_e32 v2, v127
	v_mov_b32_e32 v1, v127
	v_mov_b32_e32 v0, v127
	s_barrier
	s_cbranch_scc1 .LBB0_273
	s_lshr_b32 s2, s7, 26
	s_add_i32 s2, s6, s2
	s_ashr_i32 s49, s2, 6
	v_lshlrev_b32_e32 v0, 6, v134
	s_movk_i32 s2, 0x3c0
	v_lshlrev_b32_e32 v1, 2, v134
	s_add_i32 s53, s49, -2
	v_and_or_b32 v0, v0, s2, v147
	s_lshl_b32 s2, s42, 13
	v_and_b32_e32 v1, 32, v1
	v_bitop3_b32 v2, v0, s2, v1 bitop3:0xde
	s_add_u32 s2, s26, s36
	v_add_u32_e32 v0, v132, v133
	s_addc_u32 s3, s27, s37
	v_add_lshl_u32 v0, v0, v146, 1
	v_mov_b32_e32 v1, v157
	v_lshl_add_u64 v[132:133], s[2:3], 0, v[0:1]
	v_lshl_or_b32 v135, s19, 7, v148
	v_lshl_add_u64 v[130:131], s[2:3], 0, v[128:129]
	s_mov_b32 s2, 0
	s_mov_b64 s[6:7], 0x1a4a4080
	v_add_u32_e32 v136, 0, v2
	s_add_i32 s54, s2, 2
	s_add_u32 s3, s6, 0xe5b5c080
	s_addc_u32 s21, s7, -1
	s_cmp_lg_u32 s53, s2
	s_cselect_b32 s42, s3, 0
	s_cselect_b32 s21, s21, 0
	s_add_u32 s2, s38, s42
	s_addc_u32 s3, s39, s21
	s_add_i32 s55, 0, 0x10000
	v_add_u32_e32 v137, s55, v135
	ds_read_b128 v[142:145], v137
	ds_read_b128 v[150:153], v137 offset:2048
	ds_read_b128 v[146:149], v137 offset:1024
	ds_read_b128 v[162:165], v137 offset:3072
	s_add_u32 s42, s40, s42
	s_addc_u32 s43, s41, s21
	v_lshl_add_u64 v[138:139], v[132:133], 0, s[6:7]
	s_add_i32 m0, s25, 0xc000
	ds_read_b128 v[166:169], v136
	ds_read_b128 v[174:177], v136 offset:2048
	ds_read_b128 v[182:185], v136 offset:4096
	ds_read_b128 v[206:209], v136 offset:6144
	ds_read_b128 v[170:173], v136 offset:1024
	ds_read_b128 v[178:181], v136 offset:3072
	ds_read_b128 v[186:189], v136 offset:5120
	ds_read_b128 v[214:217], v136 offset:7168
	global_load_lds_dwordx4 v[138:139], off
	v_lshl_add_u64 v[138:139], v[130:131], 0, s[6:7]
	s_add_i32 m0, s25, 0xe000
	s_nop 0
	global_load_lds_dwordx4 v[138:139], off
	s_waitcnt lgkmcnt(8)
	s_barrier
	s_waitcnt lgkmcnt(7)
	v_mfma_f32_16x16x32_bf16 v[124:127], v[142:145], v[166:169], 0
	v_mfma_f32_16x16x32_bf16 v[120:123], v[150:153], v[166:169], 0
	s_waitcnt lgkmcnt(6)
	v_mfma_f32_16x16x32_bf16 v[108:111], v[142:145], v[174:177], 0
	v_mfma_f32_16x16x32_bf16 v[104:107], v[150:153], v[174:177], 0
	s_waitcnt lgkmcnt(5)
	v_mfma_f32_16x16x32_bf16 v[92:95], v[142:145], v[182:185], 0
	v_mfma_f32_16x16x32_bf16 v[88:91], v[150:153], v[182:185], 0
	s_waitcnt lgkmcnt(4)
	v_mfma_f32_16x16x32_bf16 v[76:79], v[142:145], v[206:209], 0
	v_mfma_f32_16x16x32_bf16 v[72:75], v[150:153], v[206:209], 0
	s_waitcnt lgkmcnt(3)
	v_mfma_f32_16x16x32_bf16 v[124:127], v[146:149], v[170:173], v[124:127]
	v_mfma_f32_16x16x32_bf16 v[120:123], v[162:165], v[170:173], v[120:123]
	s_waitcnt lgkmcnt(2)
	v_mfma_f32_16x16x32_bf16 v[108:111], v[146:149], v[178:181], v[108:111]
	v_mfma_f32_16x16x32_bf16 v[104:107], v[162:165], v[178:181], v[104:107]
	s_waitcnt lgkmcnt(1)
	v_mfma_f32_16x16x32_bf16 v[92:95], v[146:149], v[186:189], v[92:95]
	v_mfma_f32_16x16x32_bf16 v[88:91], v[162:165], v[186:189], v[88:91]
	s_waitcnt lgkmcnt(0)
	v_mfma_f32_16x16x32_bf16 v[76:79], v[146:149], v[214:217], v[76:79]
	v_mfma_f32_16x16x32_bf16 v[72:75], v[162:165], v[214:217], v[72:75]
	s_barrier
	s_add_i32 s21, 0, 0x14000
	s_add_i32 s55, s55, s24
	v_add_u32_e32 v137, s21, v135
	v_lshl_add_u64 v[138:139], s[42:43], 0, v[156:157]
	s_mov_b32 m0, s55
	ds_read_b128 v[218:221], v137
	ds_read_b128 v[226:229], v137 offset:2048
	ds_read_b128 v[222:225], v137 offset:1024
	ds_read_b128 v[230:233], v137 offset:3072
	global_load_lds_dwordx4 v[138:139], off
	v_lshl_add_u64 v[154:155], s[42:43], 0, v[128:129]
	s_add_i32 m0, s55, 0x2000
	s_nop 0
	global_load_lds_dwordx4 v[154:155], off
	s_barrier
	s_waitcnt lgkmcnt(3)
	v_mfma_f32_16x16x32_bf16 v[116:119], v[218:221], v[166:169], 0
	s_waitcnt lgkmcnt(2)
	v_mfma_f32_16x16x32_bf16 v[112:115], v[226:229], v[166:169], 0
	v_mfma_f32_16x16x32_bf16 v[100:103], v[218:221], v[174:177], 0
	v_mfma_f32_16x16x32_bf16 v[96:99], v[226:229], v[174:177], 0
	v_mfma_f32_16x16x32_bf16 v[84:87], v[218:221], v[182:185], 0
	v_mfma_f32_16x16x32_bf16 v[80:83], v[226:229], v[182:185], 0
	v_mfma_f32_16x16x32_bf16 v[68:71], v[218:221], v[206:209], 0
	v_mfma_f32_16x16x32_bf16 v[64:67], v[226:229], v[206:209], 0
	s_waitcnt lgkmcnt(1)
	v_mfma_f32_16x16x32_bf16 v[116:119], v[222:225], v[170:173], v[116:119]
	s_waitcnt lgkmcnt(0)
	v_mfma_f32_16x16x32_bf16 v[112:115], v[230:233], v[170:173], v[112:115]
	v_mfma_f32_16x16x32_bf16 v[100:103], v[222:225], v[178:181], v[100:103]
	v_mfma_f32_16x16x32_bf16 v[96:99], v[230:233], v[178:181], v[96:99]
	v_mfma_f32_16x16x32_bf16 v[84:87], v[222:225], v[186:189], v[84:87]
	v_mfma_f32_16x16x32_bf16 v[80:83], v[230:233], v[186:189], v[80:83]
	v_mfma_f32_16x16x32_bf16 v[68:71], v[222:225], v[214:217], v[68:71]
	v_mfma_f32_16x16x32_bf16 v[64:67], v[230:233], v[214:217], v[64:67]
	s_mov_b32 m0, s25
	v_lshl_add_u64 v[234:235], s[2:3], 0, v[156:157]
	s_barrier
	ds_read_b128 v[166:169], v136 offset:16384
	ds_read_b128 v[174:177], v136 offset:18432
	ds_read_b128 v[182:185], v136 offset:20480
	ds_read_b128 v[206:209], v136 offset:22528
	ds_read_b128 v[170:173], v136 offset:17408
	ds_read_b128 v[178:181], v136 offset:19456
	ds_read_b128 v[186:189], v136 offset:21504
	ds_read_b128 v[214:217], v136 offset:23552
	global_load_lds_dwordx4 v[234:235], off
	v_lshl_add_u64 v[236:237], s[2:3], 0, v[128:129]
	s_mov_b32 m0, s34
	s_nop 0
	global_load_lds_dwordx4 v[236:237], off
	s_barrier
	s_waitcnt lgkmcnt(7)
	v_mfma_f32_16x16x32_bf16 v[60:63], v[142:145], v[166:169], 0
	v_mfma_f32_16x16x32_bf16 v[56:59], v[150:153], v[166:169], 0
	s_waitcnt lgkmcnt(6)
	v_mfma_f32_16x16x32_bf16 v[44:47], v[142:145], v[174:177], 0
	v_mfma_f32_16x16x32_bf16 v[40:43], v[150:153], v[174:177], 0
	s_waitcnt lgkmcnt(5)
	v_mfma_f32_16x16x32_bf16 v[28:31], v[142:145], v[182:185], 0
	v_mfma_f32_16x16x32_bf16 v[24:27], v[150:153], v[182:185], 0
	s_waitcnt lgkmcnt(4)
	v_mfma_f32_16x16x32_bf16 v[12:15], v[142:145], v[206:209], 0
	v_mfma_f32_16x16x32_bf16 v[8:11], v[150:153], v[206:209], 0
	s_waitcnt lgkmcnt(3)
	v_mfma_f32_16x16x32_bf16 v[60:63], v[146:149], v[170:173], v[60:63]
	v_mfma_f32_16x16x32_bf16 v[56:59], v[162:165], v[170:173], v[56:59]
	s_waitcnt lgkmcnt(2)
	v_mfma_f32_16x16x32_bf16 v[44:47], v[146:149], v[178:181], v[44:47]
	v_mfma_f32_16x16x32_bf16 v[40:43], v[162:165], v[178:181], v[40:43]
	s_waitcnt lgkmcnt(1)
	v_mfma_f32_16x16x32_bf16 v[28:31], v[146:149], v[186:189], v[28:31]
	v_mfma_f32_16x16x32_bf16 v[24:27], v[162:165], v[186:189], v[24:27]
	s_waitcnt lgkmcnt(0)
	v_mfma_f32_16x16x32_bf16 v[12:15], v[146:149], v[214:217], v[12:15]
	v_mfma_f32_16x16x32_bf16 v[8:11], v[162:165], v[214:217], v[8:11]
	s_barrier
	s_add_u32 s42, s42, s36
	s_addc_u32 s43, s43, s37
	s_add_i32 s21, s21, s24
	v_lshl_add_u64 v[238:239], s[42:43], 0, v[156:157]
	s_mov_b32 m0, s21
	v_lshl_add_u64 v[240:241], s[42:43], 0, v[128:129]
	global_load_lds_dwordx4 v[238:239], off
	s_add_i32 m0, s21, 0x2000
	s_nop 0
	global_load_lds_dwordx4 v[240:241], off
	s_waitcnt vmcnt(6)
	s_barrier
	v_mfma_f32_16x16x32_bf16 v[52:55], v[218:221], v[166:169], 0
	v_mfma_f32_16x16x32_bf16 v[48:51], v[226:229], v[166:169], 0
	v_mfma_f32_16x16x32_bf16 v[36:39], v[218:221], v[174:177], 0
	v_mfma_f32_16x16x32_bf16 v[32:35], v[226:229], v[174:177], 0
	v_mfma_f32_16x16x32_bf16 v[20:23], v[218:221], v[182:185], 0
	v_mfma_f32_16x16x32_bf16 v[16:19], v[226:229], v[182:185], 0
	v_mfma_f32_16x16x32_bf16 v[4:7], v[218:221], v[206:209], 0
	v_mfma_f32_16x16x32_bf16 v[0:3], v[226:229], v[206:209], 0
	v_mfma_f32_16x16x32_bf16 v[52:55], v[222:225], v[170:173], v[52:55]
	v_mfma_f32_16x16x32_bf16 v[48:51], v[230:233], v[170:173], v[48:51]
	v_mfma_f32_16x16x32_bf16 v[36:39], v[222:225], v[178:181], v[36:39]
	v_mfma_f32_16x16x32_bf16 v[32:35], v[230:233], v[178:181], v[32:35]
	v_mfma_f32_16x16x32_bf16 v[20:23], v[222:225], v[186:189], v[20:23]
	v_mfma_f32_16x16x32_bf16 v[16:19], v[230:233], v[186:189], v[16:19]
	v_mfma_f32_16x16x32_bf16 v[4:7], v[222:225], v[214:217], v[4:7]
	v_mfma_f32_16x16x32_bf16 v[0:3], v[230:233], v[214:217], v[0:3]
	s_add_i32 s21, 0, 0x18000
	v_add_u32_e32 v137, s21, v135
	s_barrier
	ds_read_b128 v[142:145], v137
	ds_read_b128 v[150:153], v137 offset:2048
	ds_read_b128 v[146:149], v137 offset:1024
	ds_read_b128 v[162:165], v137 offset:3072
	s_add_u32 s2, s2, s36
	s_addc_u32 s3, s3, s37
	s_mov_b32 m0, s35
	v_lshl_add_u64 v[218:219], s[2:3], 0, v[156:157]
	ds_read_b128 v[166:169], v136 offset:32768
	ds_read_b128 v[174:177], v136 offset:34816
	ds_read_b128 v[182:185], v136 offset:36864
	ds_read_b128 v[206:209], v136 offset:38912
	ds_read_b128 v[170:173], v136 offset:33792
	ds_read_b128 v[178:181], v136 offset:35840
	ds_read_b128 v[186:189], v136 offset:37888
	ds_read_b128 v[214:217], v136 offset:39936
	global_load_lds_dwordx4 v[218:219], off
	v_lshl_add_u64 v[218:219], s[2:3], 0, v[128:129]
	s_mov_b32 m0, s44
	s_nop 0
	global_load_lds_dwordx4 v[218:219], off
	s_waitcnt lgkmcnt(8)
	s_barrier
	s_waitcnt lgkmcnt(7)
	v_mfma_f32_16x16x32_bf16 v[124:127], v[142:145], v[166:169], v[124:127]
	v_mfma_f32_16x16x32_bf16 v[120:123], v[150:153], v[166:169], v[120:123]
	s_waitcnt lgkmcnt(6)
	v_mfma_f32_16x16x32_bf16 v[108:111], v[142:145], v[174:177], v[108:111]
	v_mfma_f32_16x16x32_bf16 v[104:107], v[150:153], v[174:177], v[104:107]
	s_waitcnt lgkmcnt(5)
	v_mfma_f32_16x16x32_bf16 v[92:95], v[142:145], v[182:185], v[92:95]
	v_mfma_f32_16x16x32_bf16 v[88:91], v[150:153], v[182:185], v[88:91]
	s_waitcnt lgkmcnt(4)
	v_mfma_f32_16x16x32_bf16 v[76:79], v[142:145], v[206:209], v[76:79]
	v_mfma_f32_16x16x32_bf16 v[72:75], v[150:153], v[206:209], v[72:75]
	s_waitcnt lgkmcnt(3)
	v_mfma_f32_16x16x32_bf16 v[124:127], v[146:149], v[170:173], v[124:127]
	v_mfma_f32_16x16x32_bf16 v[120:123], v[162:165], v[170:173], v[120:123]
	s_waitcnt lgkmcnt(2)
	v_mfma_f32_16x16x32_bf16 v[108:111], v[146:149], v[178:181], v[108:111]
	v_mfma_f32_16x16x32_bf16 v[104:107], v[162:165], v[178:181], v[104:107]
	s_waitcnt lgkmcnt(1)
	v_mfma_f32_16x16x32_bf16 v[92:95], v[146:149], v[186:189], v[92:95]
	v_mfma_f32_16x16x32_bf16 v[88:91], v[162:165], v[186:189], v[88:91]
	s_waitcnt lgkmcnt(0)
	v_mfma_f32_16x16x32_bf16 v[76:79], v[146:149], v[214:217], v[76:79]
	v_mfma_f32_16x16x32_bf16 v[72:75], v[162:165], v[214:217], v[72:75]
	s_barrier
	s_add_i32 s2, 0, 0x1c000
	s_add_i32 s3, s21, s24
	v_add_u32_e32 v137, s2, v135
	v_lshl_add_u64 v[138:139], v[138:139], 0, s[50:51]
	s_mov_b32 m0, s3
	ds_read_b128 v[218:221], v137
	ds_read_b128 v[226:229], v137 offset:2048
	ds_read_b128 v[222:225], v137 offset:1024
	ds_read_b128 v[230:233], v137 offset:3072
	global_load_lds_dwordx4 v[138:139], off
	v_lshl_add_u64 v[138:139], v[154:155], 0, s[50:51]
	s_add_i32 m0, s3, 0x2000
	s_nop 0
	global_load_lds_dwordx4 v[138:139], off
	s_barrier
	s_waitcnt lgkmcnt(3)
	v_mfma_f32_16x16x32_bf16 v[116:119], v[218:221], v[166:169], v[116:119]
	s_waitcnt lgkmcnt(2)
	v_mfma_f32_16x16x32_bf16 v[112:115], v[226:229], v[166:169], v[112:115]
	v_mfma_f32_16x16x32_bf16 v[100:103], v[218:221], v[174:177], v[100:103]
	v_mfma_f32_16x16x32_bf16 v[96:99], v[226:229], v[174:177], v[96:99]
	v_mfma_f32_16x16x32_bf16 v[84:87], v[218:221], v[182:185], v[84:87]
	v_mfma_f32_16x16x32_bf16 v[80:83], v[226:229], v[182:185], v[80:83]
	v_mfma_f32_16x16x32_bf16 v[68:71], v[218:221], v[206:209], v[68:71]
	v_mfma_f32_16x16x32_bf16 v[64:67], v[226:229], v[206:209], v[64:67]
	s_waitcnt lgkmcnt(1)
	v_mfma_f32_16x16x32_bf16 v[116:119], v[222:225], v[170:173], v[116:119]
	s_waitcnt lgkmcnt(0)
	v_mfma_f32_16x16x32_bf16 v[112:115], v[230:233], v[170:173], v[112:115]
	v_mfma_f32_16x16x32_bf16 v[100:103], v[222:225], v[178:181], v[100:103]
	v_mfma_f32_16x16x32_bf16 v[96:99], v[230:233], v[178:181], v[96:99]
	v_mfma_f32_16x16x32_bf16 v[84:87], v[222:225], v[186:189], v[84:87]
	v_mfma_f32_16x16x32_bf16 v[80:83], v[230:233], v[186:189], v[80:83]
	v_mfma_f32_16x16x32_bf16 v[68:71], v[222:225], v[214:217], v[68:71]
	v_mfma_f32_16x16x32_bf16 v[64:67], v[230:233], v[214:217], v[64:67]
	s_mov_b32 m0, s45
	v_lshl_add_u64 v[138:139], v[234:235], 0, s[50:51]
	s_barrier
	ds_read_b128 v[166:169], v136 offset:49152
	ds_read_b128 v[174:177], v136 offset:51200
	ds_read_b128 v[182:185], v136 offset:53248
	ds_read_b128 v[206:209], v136 offset:55296
	ds_read_b128 v[170:173], v136 offset:50176
	ds_read_b128 v[178:181], v136 offset:52224
	ds_read_b128 v[186:189], v136 offset:54272
	ds_read_b128 v[214:217], v136 offset:56320
	global_load_lds_dwordx4 v[138:139], off
	v_lshl_add_u64 v[138:139], v[236:237], 0, s[50:51]
	s_mov_b32 m0, s48
	s_nop 0
	global_load_lds_dwordx4 v[138:139], off
	s_barrier
	s_waitcnt lgkmcnt(7)
	v_mfma_f32_16x16x32_bf16 v[60:63], v[142:145], v[166:169], v[60:63]
	v_mfma_f32_16x16x32_bf16 v[56:59], v[150:153], v[166:169], v[56:59]
	s_waitcnt lgkmcnt(6)
	v_mfma_f32_16x16x32_bf16 v[44:47], v[142:145], v[174:177], v[44:47]
	v_mfma_f32_16x16x32_bf16 v[40:43], v[150:153], v[174:177], v[40:43]
	s_waitcnt lgkmcnt(5)
	v_mfma_f32_16x16x32_bf16 v[28:31], v[142:145], v[182:185], v[28:31]
	v_mfma_f32_16x16x32_bf16 v[24:27], v[150:153], v[182:185], v[24:27]
	s_waitcnt lgkmcnt(4)
	v_mfma_f32_16x16x32_bf16 v[12:15], v[142:145], v[206:209], v[12:15]
	v_mfma_f32_16x16x32_bf16 v[8:11], v[150:153], v[206:209], v[8:11]
	s_waitcnt lgkmcnt(3)
	v_mfma_f32_16x16x32_bf16 v[60:63], v[146:149], v[170:173], v[60:63]
	v_mfma_f32_16x16x32_bf16 v[56:59], v[162:165], v[170:173], v[56:59]
	s_waitcnt lgkmcnt(2)
	v_mfma_f32_16x16x32_bf16 v[44:47], v[146:149], v[178:181], v[44:47]
	v_mfma_f32_16x16x32_bf16 v[40:43], v[162:165], v[178:181], v[40:43]
	s_waitcnt lgkmcnt(1)
	v_mfma_f32_16x16x32_bf16 v[28:31], v[146:149], v[186:189], v[28:31]
	v_mfma_f32_16x16x32_bf16 v[24:27], v[162:165], v[186:189], v[24:27]
	s_waitcnt lgkmcnt(0)
	v_mfma_f32_16x16x32_bf16 v[12:15], v[146:149], v[214:217], v[12:15]
	v_mfma_f32_16x16x32_bf16 v[8:11], v[162:165], v[214:217], v[8:11]
	s_barrier
	s_add_i32 s2, s2, s24
	v_lshl_add_u64 v[138:139], v[238:239], 0, s[50:51]
	s_mov_b32 m0, s2
	s_nop 0
	global_load_lds_dwordx4 v[138:139], off
	v_lshl_add_u64 v[138:139], v[240:241], 0, s[50:51]
	s_add_i32 m0, s2, 0x2000
	s_nop 0
	global_load_lds_dwordx4 v[138:139], off
	s_waitcnt vmcnt(6)
	s_barrier
	v_mfma_f32_16x16x32_bf16 v[52:55], v[218:221], v[166:169], v[52:55]
	v_mfma_f32_16x16x32_bf16 v[48:51], v[226:229], v[166:169], v[48:51]
	v_mfma_f32_16x16x32_bf16 v[36:39], v[218:221], v[174:177], v[36:39]
	v_mfma_f32_16x16x32_bf16 v[32:35], v[226:229], v[174:177], v[32:35]
	v_mfma_f32_16x16x32_bf16 v[20:23], v[218:221], v[182:185], v[20:23]
	v_mfma_f32_16x16x32_bf16 v[16:19], v[226:229], v[182:185], v[16:19]
	v_mfma_f32_16x16x32_bf16 v[4:7], v[218:221], v[206:209], v[4:7]
	v_mfma_f32_16x16x32_bf16 v[0:3], v[226:229], v[206:209], v[0:3]
	v_mfma_f32_16x16x32_bf16 v[52:55], v[222:225], v[170:173], v[52:55]
	v_mfma_f32_16x16x32_bf16 v[48:51], v[230:233], v[170:173], v[48:51]
	v_mfma_f32_16x16x32_bf16 v[36:39], v[222:225], v[178:181], v[36:39]
	v_mfma_f32_16x16x32_bf16 v[32:35], v[230:233], v[178:181], v[32:35]
	v_mfma_f32_16x16x32_bf16 v[20:23], v[222:225], v[186:189], v[20:23]
	v_mfma_f32_16x16x32_bf16 v[16:19], v[230:233], v[186:189], v[16:19]
	v_mfma_f32_16x16x32_bf16 v[4:7], v[222:225], v[214:217], v[4:7]
	v_mfma_f32_16x16x32_bf16 v[0:3], v[230:233], v[214:217], v[0:3]
	s_add_u32 s6, s6, 0x100
	s_addc_u32 s7, s7, 0
	s_cmp_ge_i32 s54, s49
	s_mov_b32 s2, s54
	s_barrier
	s_cbranch_scc1 .Lpost_272
.LBB0_272:
	s_add_i32 s54, s2, 2
	s_add_u32 s3, s6, 0xe5b5c080
	s_addc_u32 s21, s7, -1
	s_cmp_lg_u32 s53, s2
	s_cselect_b32 s42, s3, 0
	s_cselect_b32 s21, s21, 0
	s_add_u32 s2, s38, s42
	s_addc_u32 s3, s39, s21
	s_add_i32 s55, 0, 0x10000
	v_add_u32_e32 v137, s55, v135
	ds_read_b128 v[142:145], v137
	ds_read_b128 v[150:153], v137 offset:2048
	ds_read_b128 v[146:149], v137 offset:1024
	ds_read_b128 v[162:165], v137 offset:3072
	s_add_u32 s42, s40, s42
	s_addc_u32 s43, s41, s21
	v_lshl_add_u64 v[138:139], v[132:133], 0, s[6:7]
	s_add_i32 m0, s25, 0xc000
	ds_read_b128 v[166:169], v136
	ds_read_b128 v[174:177], v136 offset:2048
	ds_read_b128 v[182:185], v136 offset:4096
	ds_read_b128 v[206:209], v136 offset:6144
	ds_read_b128 v[170:173], v136 offset:1024
	ds_read_b128 v[178:181], v136 offset:3072
	ds_read_b128 v[186:189], v136 offset:5120
	ds_read_b128 v[214:217], v136 offset:7168
	global_load_lds_dwordx4 v[138:139], off
	v_lshl_add_u64 v[138:139], v[130:131], 0, s[6:7]
	s_add_i32 m0, s25, 0xe000
	s_nop 0
	global_load_lds_dwordx4 v[138:139], off
	s_waitcnt lgkmcnt(8)
	s_barrier
	s_waitcnt lgkmcnt(7)
	v_mfma_f32_16x16x32_bf16 v[124:127], v[142:145], v[166:169], v[124:127]
	v_mfma_f32_16x16x32_bf16 v[120:123], v[150:153], v[166:169], v[120:123]
	s_waitcnt lgkmcnt(6)
	v_mfma_f32_16x16x32_bf16 v[108:111], v[142:145], v[174:177], v[108:111]
	v_mfma_f32_16x16x32_bf16 v[104:107], v[150:153], v[174:177], v[104:107]
	s_waitcnt lgkmcnt(5)
	v_mfma_f32_16x16x32_bf16 v[92:95], v[142:145], v[182:185], v[92:95]
	v_mfma_f32_16x16x32_bf16 v[88:91], v[150:153], v[182:185], v[88:91]
	s_waitcnt lgkmcnt(4)
	v_mfma_f32_16x16x32_bf16 v[76:79], v[142:145], v[206:209], v[76:79]
	v_mfma_f32_16x16x32_bf16 v[72:75], v[150:153], v[206:209], v[72:75]
	s_waitcnt lgkmcnt(3)
	v_mfma_f32_16x16x32_bf16 v[124:127], v[146:149], v[170:173], v[124:127]
	v_mfma_f32_16x16x32_bf16 v[120:123], v[162:165], v[170:173], v[120:123]
	s_waitcnt lgkmcnt(2)
	v_mfma_f32_16x16x32_bf16 v[108:111], v[146:149], v[178:181], v[108:111]
	v_mfma_f32_16x16x32_bf16 v[104:107], v[162:165], v[178:181], v[104:107]
	s_waitcnt lgkmcnt(1)
	v_mfma_f32_16x16x32_bf16 v[92:95], v[146:149], v[186:189], v[92:95]
	v_mfma_f32_16x16x32_bf16 v[88:91], v[162:165], v[186:189], v[88:91]
	s_waitcnt lgkmcnt(0)
	v_mfma_f32_16x16x32_bf16 v[76:79], v[146:149], v[214:217], v[76:79]
	v_mfma_f32_16x16x32_bf16 v[72:75], v[162:165], v[214:217], v[72:75]
	s_barrier
	s_add_i32 s21, 0, 0x14000
	s_add_i32 s55, s55, s24
	v_add_u32_e32 v137, s21, v135
	v_lshl_add_u64 v[138:139], s[42:43], 0, v[156:157]
	s_mov_b32 m0, s55
	ds_read_b128 v[218:221], v137
	ds_read_b128 v[226:229], v137 offset:2048
	ds_read_b128 v[222:225], v137 offset:1024
	ds_read_b128 v[230:233], v137 offset:3072
	global_load_lds_dwordx4 v[138:139], off
	v_lshl_add_u64 v[154:155], s[42:43], 0, v[128:129]
	s_add_i32 m0, s55, 0x2000
	s_nop 0
	global_load_lds_dwordx4 v[154:155], off
	s_barrier
	s_waitcnt lgkmcnt(3)
	v_mfma_f32_16x16x32_bf16 v[116:119], v[218:221], v[166:169], v[116:119]
	s_waitcnt lgkmcnt(2)
	v_mfma_f32_16x16x32_bf16 v[112:115], v[226:229], v[166:169], v[112:115]
	v_mfma_f32_16x16x32_bf16 v[100:103], v[218:221], v[174:177], v[100:103]
	v_mfma_f32_16x16x32_bf16 v[96:99], v[226:229], v[174:177], v[96:99]
	v_mfma_f32_16x16x32_bf16 v[84:87], v[218:221], v[182:185], v[84:87]
	v_mfma_f32_16x16x32_bf16 v[80:83], v[226:229], v[182:185], v[80:83]
	v_mfma_f32_16x16x32_bf16 v[68:71], v[218:221], v[206:209], v[68:71]
	v_mfma_f32_16x16x32_bf16 v[64:67], v[226:229], v[206:209], v[64:67]
	s_waitcnt lgkmcnt(1)
	v_mfma_f32_16x16x32_bf16 v[116:119], v[222:225], v[170:173], v[116:119]
	s_waitcnt lgkmcnt(0)
	v_mfma_f32_16x16x32_bf16 v[112:115], v[230:233], v[170:173], v[112:115]
	v_mfma_f32_16x16x32_bf16 v[100:103], v[222:225], v[178:181], v[100:103]
	v_mfma_f32_16x16x32_bf16 v[96:99], v[230:233], v[178:181], v[96:99]
	v_mfma_f32_16x16x32_bf16 v[84:87], v[222:225], v[186:189], v[84:87]
	v_mfma_f32_16x16x32_bf16 v[80:83], v[230:233], v[186:189], v[80:83]
	v_mfma_f32_16x16x32_bf16 v[68:71], v[222:225], v[214:217], v[68:71]
	v_mfma_f32_16x16x32_bf16 v[64:67], v[230:233], v[214:217], v[64:67]
	s_mov_b32 m0, s25
	v_lshl_add_u64 v[234:235], s[2:3], 0, v[156:157]
	s_barrier
	ds_read_b128 v[166:169], v136 offset:16384
	ds_read_b128 v[174:177], v136 offset:18432
	ds_read_b128 v[182:185], v136 offset:20480
	ds_read_b128 v[206:209], v136 offset:22528
	ds_read_b128 v[170:173], v136 offset:17408
	ds_read_b128 v[178:181], v136 offset:19456
	ds_read_b128 v[186:189], v136 offset:21504
	ds_read_b128 v[214:217], v136 offset:23552
	global_load_lds_dwordx4 v[234:235], off
	v_lshl_add_u64 v[236:237], s[2:3], 0, v[128:129]
	s_mov_b32 m0, s34
	s_nop 0
	global_load_lds_dwordx4 v[236:237], off
	s_barrier
	s_waitcnt lgkmcnt(7)
	v_mfma_f32_16x16x32_bf16 v[60:63], v[142:145], v[166:169], v[60:63]
	v_mfma_f32_16x16x32_bf16 v[56:59], v[150:153], v[166:169], v[56:59]
	s_waitcnt lgkmcnt(6)
	v_mfma_f32_16x16x32_bf16 v[44:47], v[142:145], v[174:177], v[44:47]
	v_mfma_f32_16x16x32_bf16 v[40:43], v[150:153], v[174:177], v[40:43]
	s_waitcnt lgkmcnt(5)
	v_mfma_f32_16x16x32_bf16 v[28:31], v[142:145], v[182:185], v[28:31]
	v_mfma_f32_16x16x32_bf16 v[24:27], v[150:153], v[182:185], v[24:27]
	s_waitcnt lgkmcnt(4)
	v_mfma_f32_16x16x32_bf16 v[12:15], v[142:145], v[206:209], v[12:15]
	v_mfma_f32_16x16x32_bf16 v[8:11], v[150:153], v[206:209], v[8:11]
	s_waitcnt lgkmcnt(3)
	v_mfma_f32_16x16x32_bf16 v[60:63], v[146:149], v[170:173], v[60:63]
	v_mfma_f32_16x16x32_bf16 v[56:59], v[162:165], v[170:173], v[56:59]
	s_waitcnt lgkmcnt(2)
	v_mfma_f32_16x16x32_bf16 v[44:47], v[146:149], v[178:181], v[44:47]
	v_mfma_f32_16x16x32_bf16 v[40:43], v[162:165], v[178:181], v[40:43]
	s_waitcnt lgkmcnt(1)
	v_mfma_f32_16x16x32_bf16 v[28:31], v[146:149], v[186:189], v[28:31]
	v_mfma_f32_16x16x32_bf16 v[24:27], v[162:165], v[186:189], v[24:27]
	s_waitcnt lgkmcnt(0)
	v_mfma_f32_16x16x32_bf16 v[12:15], v[146:149], v[214:217], v[12:15]
	v_mfma_f32_16x16x32_bf16 v[8:11], v[162:165], v[214:217], v[8:11]
	s_barrier
	s_add_u32 s42, s42, s36
	s_addc_u32 s43, s43, s37
	s_add_i32 s21, s21, s24
	v_lshl_add_u64 v[238:239], s[42:43], 0, v[156:157]
	s_mov_b32 m0, s21
	v_lshl_add_u64 v[240:241], s[42:43], 0, v[128:129]
	global_load_lds_dwordx4 v[238:239], off
	s_add_i32 m0, s21, 0x2000
	s_nop 0
	global_load_lds_dwordx4 v[240:241], off
	s_waitcnt vmcnt(6)
	s_barrier
	v_mfma_f32_16x16x32_bf16 v[52:55], v[218:221], v[166:169], v[52:55]
	v_mfma_f32_16x16x32_bf16 v[48:51], v[226:229], v[166:169], v[48:51]
	v_mfma_f32_16x16x32_bf16 v[36:39], v[218:221], v[174:177], v[36:39]
	v_mfma_f32_16x16x32_bf16 v[32:35], v[226:229], v[174:177], v[32:35]
	v_mfma_f32_16x16x32_bf16 v[20:23], v[218:221], v[182:185], v[20:23]
	v_mfma_f32_16x16x32_bf16 v[16:19], v[226:229], v[182:185], v[16:19]
	v_mfma_f32_16x16x32_bf16 v[4:7], v[218:221], v[206:209], v[4:7]
	v_mfma_f32_16x16x32_bf16 v[0:3], v[226:229], v[206:209], v[0:3]
	v_mfma_f32_16x16x32_bf16 v[52:55], v[222:225], v[170:173], v[52:55]
	v_mfma_f32_16x16x32_bf16 v[48:51], v[230:233], v[170:173], v[48:51]
	v_mfma_f32_16x16x32_bf16 v[36:39], v[222:225], v[178:181], v[36:39]
	v_mfma_f32_16x16x32_bf16 v[32:35], v[230:233], v[178:181], v[32:35]
	v_mfma_f32_16x16x32_bf16 v[20:23], v[222:225], v[186:189], v[20:23]
	v_mfma_f32_16x16x32_bf16 v[16:19], v[230:233], v[186:189], v[16:19]
	v_mfma_f32_16x16x32_bf16 v[4:7], v[222:225], v[214:217], v[4:7]
	v_mfma_f32_16x16x32_bf16 v[0:3], v[230:233], v[214:217], v[0:3]
	s_add_i32 s21, 0, 0x18000
	v_add_u32_e32 v137, s21, v135
	s_barrier
	ds_read_b128 v[142:145], v137
	ds_read_b128 v[150:153], v137 offset:2048
	ds_read_b128 v[146:149], v137 offset:1024
	ds_read_b128 v[162:165], v137 offset:3072
	s_add_u32 s2, s2, s36
	s_addc_u32 s3, s3, s37
	s_mov_b32 m0, s35
	v_lshl_add_u64 v[218:219], s[2:3], 0, v[156:157]
	ds_read_b128 v[166:169], v136 offset:32768
	ds_read_b128 v[174:177], v136 offset:34816
	ds_read_b128 v[182:185], v136 offset:36864
	ds_read_b128 v[206:209], v136 offset:38912
	ds_read_b128 v[170:173], v136 offset:33792
	ds_read_b128 v[178:181], v136 offset:35840
	ds_read_b128 v[186:189], v136 offset:37888
	ds_read_b128 v[214:217], v136 offset:39936
	global_load_lds_dwordx4 v[218:219], off
	v_lshl_add_u64 v[218:219], s[2:3], 0, v[128:129]
	s_mov_b32 m0, s44
	s_nop 0
	global_load_lds_dwordx4 v[218:219], off
	s_waitcnt lgkmcnt(8)
	s_barrier
	s_waitcnt lgkmcnt(7)
	v_mfma_f32_16x16x32_bf16 v[124:127], v[142:145], v[166:169], v[124:127]
	v_mfma_f32_16x16x32_bf16 v[120:123], v[150:153], v[166:169], v[120:123]
	s_waitcnt lgkmcnt(6)
	v_mfma_f32_16x16x32_bf16 v[108:111], v[142:145], v[174:177], v[108:111]
	v_mfma_f32_16x16x32_bf16 v[104:107], v[150:153], v[174:177], v[104:107]
	s_waitcnt lgkmcnt(5)
	v_mfma_f32_16x16x32_bf16 v[92:95], v[142:145], v[182:185], v[92:95]
	v_mfma_f32_16x16x32_bf16 v[88:91], v[150:153], v[182:185], v[88:91]
	s_waitcnt lgkmcnt(4)
	v_mfma_f32_16x16x32_bf16 v[76:79], v[142:145], v[206:209], v[76:79]
	v_mfma_f32_16x16x32_bf16 v[72:75], v[150:153], v[206:209], v[72:75]
	s_waitcnt lgkmcnt(3)
	v_mfma_f32_16x16x32_bf16 v[124:127], v[146:149], v[170:173], v[124:127]
	v_mfma_f32_16x16x32_bf16 v[120:123], v[162:165], v[170:173], v[120:123]
	s_waitcnt lgkmcnt(2)
	v_mfma_f32_16x16x32_bf16 v[108:111], v[146:149], v[178:181], v[108:111]
	v_mfma_f32_16x16x32_bf16 v[104:107], v[162:165], v[178:181], v[104:107]
	s_waitcnt lgkmcnt(1)
	v_mfma_f32_16x16x32_bf16 v[92:95], v[146:149], v[186:189], v[92:95]
	v_mfma_f32_16x16x32_bf16 v[88:91], v[162:165], v[186:189], v[88:91]
	s_waitcnt lgkmcnt(0)
	v_mfma_f32_16x16x32_bf16 v[76:79], v[146:149], v[214:217], v[76:79]
	v_mfma_f32_16x16x32_bf16 v[72:75], v[162:165], v[214:217], v[72:75]
	s_barrier
	s_add_i32 s2, 0, 0x1c000
	s_add_i32 s3, s21, s24
	v_add_u32_e32 v137, s2, v135
	v_lshl_add_u64 v[138:139], v[138:139], 0, s[50:51]
	s_mov_b32 m0, s3
	ds_read_b128 v[218:221], v137
	ds_read_b128 v[226:229], v137 offset:2048
	ds_read_b128 v[222:225], v137 offset:1024
	ds_read_b128 v[230:233], v137 offset:3072
	global_load_lds_dwordx4 v[138:139], off
	v_lshl_add_u64 v[138:139], v[154:155], 0, s[50:51]
	s_add_i32 m0, s3, 0x2000
	s_nop 0
	global_load_lds_dwordx4 v[138:139], off
	s_barrier
	s_waitcnt lgkmcnt(3)
	v_mfma_f32_16x16x32_bf16 v[116:119], v[218:221], v[166:169], v[116:119]
	s_waitcnt lgkmcnt(2)
	v_mfma_f32_16x16x32_bf16 v[112:115], v[226:229], v[166:169], v[112:115]
	v_mfma_f32_16x16x32_bf16 v[100:103], v[218:221], v[174:177], v[100:103]
	v_mfma_f32_16x16x32_bf16 v[96:99], v[226:229], v[174:177], v[96:99]
	v_mfma_f32_16x16x32_bf16 v[84:87], v[218:221], v[182:185], v[84:87]
	v_mfma_f32_16x16x32_bf16 v[80:83], v[226:229], v[182:185], v[80:83]
	v_mfma_f32_16x16x32_bf16 v[68:71], v[218:221], v[206:209], v[68:71]
	v_mfma_f32_16x16x32_bf16 v[64:67], v[226:229], v[206:209], v[64:67]
	s_waitcnt lgkmcnt(1)
	v_mfma_f32_16x16x32_bf16 v[116:119], v[222:225], v[170:173], v[116:119]
	s_waitcnt lgkmcnt(0)
	v_mfma_f32_16x16x32_bf16 v[112:115], v[230:233], v[170:173], v[112:115]
	v_mfma_f32_16x16x32_bf16 v[100:103], v[222:225], v[178:181], v[100:103]
	v_mfma_f32_16x16x32_bf16 v[96:99], v[230:233], v[178:181], v[96:99]
	v_mfma_f32_16x16x32_bf16 v[84:87], v[222:225], v[186:189], v[84:87]
	v_mfma_f32_16x16x32_bf16 v[80:83], v[230:233], v[186:189], v[80:83]
	v_mfma_f32_16x16x32_bf16 v[68:71], v[222:225], v[214:217], v[68:71]
	v_mfma_f32_16x16x32_bf16 v[64:67], v[230:233], v[214:217], v[64:67]
	s_mov_b32 m0, s45
	v_lshl_add_u64 v[138:139], v[234:235], 0, s[50:51]
	s_barrier
	ds_read_b128 v[166:169], v136 offset:49152
	ds_read_b128 v[174:177], v136 offset:51200
	ds_read_b128 v[182:185], v136 offset:53248
	ds_read_b128 v[206:209], v136 offset:55296
	ds_read_b128 v[170:173], v136 offset:50176
	ds_read_b128 v[178:181], v136 offset:52224
	ds_read_b128 v[186:189], v136 offset:54272
	ds_read_b128 v[214:217], v136 offset:56320
	global_load_lds_dwordx4 v[138:139], off
	v_lshl_add_u64 v[138:139], v[236:237], 0, s[50:51]
	s_mov_b32 m0, s48
	s_nop 0
	global_load_lds_dwordx4 v[138:139], off
	s_barrier
	s_waitcnt lgkmcnt(7)
	v_mfma_f32_16x16x32_bf16 v[60:63], v[142:145], v[166:169], v[60:63]
	v_mfma_f32_16x16x32_bf16 v[56:59], v[150:153], v[166:169], v[56:59]
	s_waitcnt lgkmcnt(6)
	v_mfma_f32_16x16x32_bf16 v[44:47], v[142:145], v[174:177], v[44:47]
	v_mfma_f32_16x16x32_bf16 v[40:43], v[150:153], v[174:177], v[40:43]
	s_waitcnt lgkmcnt(5)
	v_mfma_f32_16x16x32_bf16 v[28:31], v[142:145], v[182:185], v[28:31]
	v_mfma_f32_16x16x32_bf16 v[24:27], v[150:153], v[182:185], v[24:27]
	s_waitcnt lgkmcnt(4)
	v_mfma_f32_16x16x32_bf16 v[12:15], v[142:145], v[206:209], v[12:15]
	v_mfma_f32_16x16x32_bf16 v[8:11], v[150:153], v[206:209], v[8:11]
	s_waitcnt lgkmcnt(3)
	v_mfma_f32_16x16x32_bf16 v[60:63], v[146:149], v[170:173], v[60:63]
	v_mfma_f32_16x16x32_bf16 v[56:59], v[162:165], v[170:173], v[56:59]
	s_waitcnt lgkmcnt(2)
	v_mfma_f32_16x16x32_bf16 v[44:47], v[146:149], v[178:181], v[44:47]
	v_mfma_f32_16x16x32_bf16 v[40:43], v[162:165], v[178:181], v[40:43]
	s_waitcnt lgkmcnt(1)
	v_mfma_f32_16x16x32_bf16 v[28:31], v[146:149], v[186:189], v[28:31]
	v_mfma_f32_16x16x32_bf16 v[24:27], v[162:165], v[186:189], v[24:27]
	s_waitcnt lgkmcnt(0)
	v_mfma_f32_16x16x32_bf16 v[12:15], v[146:149], v[214:217], v[12:15]
	v_mfma_f32_16x16x32_bf16 v[8:11], v[162:165], v[214:217], v[8:11]
	s_barrier
	s_add_i32 s2, s2, s24
	v_lshl_add_u64 v[138:139], v[238:239], 0, s[50:51]
	s_mov_b32 m0, s2
	s_nop 0
	global_load_lds_dwordx4 v[138:139], off
	v_lshl_add_u64 v[138:139], v[240:241], 0, s[50:51]
	s_add_i32 m0, s2, 0x2000
	s_nop 0
	global_load_lds_dwordx4 v[138:139], off
	s_waitcnt vmcnt(6)
	s_barrier
	v_mfma_f32_16x16x32_bf16 v[52:55], v[218:221], v[166:169], v[52:55]
	v_mfma_f32_16x16x32_bf16 v[48:51], v[226:229], v[166:169], v[48:51]
	v_mfma_f32_16x16x32_bf16 v[36:39], v[218:221], v[174:177], v[36:39]
	v_mfma_f32_16x16x32_bf16 v[32:35], v[226:229], v[174:177], v[32:35]
	v_mfma_f32_16x16x32_bf16 v[20:23], v[218:221], v[182:185], v[20:23]
	v_mfma_f32_16x16x32_bf16 v[16:19], v[226:229], v[182:185], v[16:19]
	v_mfma_f32_16x16x32_bf16 v[4:7], v[218:221], v[206:209], v[4:7]
	v_mfma_f32_16x16x32_bf16 v[0:3], v[226:229], v[206:209], v[0:3]
	v_mfma_f32_16x16x32_bf16 v[52:55], v[222:225], v[170:173], v[52:55]
	v_mfma_f32_16x16x32_bf16 v[48:51], v[230:233], v[170:173], v[48:51]
	v_mfma_f32_16x16x32_bf16 v[36:39], v[222:225], v[178:181], v[36:39]
	v_mfma_f32_16x16x32_bf16 v[32:35], v[230:233], v[178:181], v[32:35]
	v_mfma_f32_16x16x32_bf16 v[20:23], v[222:225], v[186:189], v[20:23]
	v_mfma_f32_16x16x32_bf16 v[16:19], v[230:233], v[186:189], v[16:19]
	v_mfma_f32_16x16x32_bf16 v[4:7], v[222:225], v[214:217], v[4:7]
	v_mfma_f32_16x16x32_bf16 v[0:3], v[230:233], v[214:217], v[0:3]
	s_add_u32 s6, s6, 0x100
	s_addc_u32 s7, s7, 0
	s_cmp_ge_i32 s54, s49
	s_mov_b32 s2, s54
	s_barrier
	s_cbranch_scc0 .LBB0_272

.LBB0_285:
	v_bfe_u32 v14, v160, 4, 2
	v_and_b32_e32 v131, 15, v160
	v_lshlrev_b32_e32 v130, 4, v14
	v_lshlrev_b32_e32 v15, 2, v160
	v_lshl_or_b32 v14, v131, 6, v130
	s_lshl_b32 s21, s44, 13
	v_and_b32_e32 v15, 32, v15
	v_bitop3_b32 v16, v14, s21, v15 bitop3:0xde
	s_lshl_b32 s21, s45, 5
	s_lshl_b32 s35, s44, 6
	s_and_b32 s44, s21, 0x60
	s_add_i32 m0, s19, 0x18000
	v_lshl_add_u64 v[6:7], v[6:7], 0, s[50:51]
	s_lshl_b32 s21, s44, 7
	s_waitcnt vmcnt(4)
	s_barrier
	global_load_lds_dwordx4 v[6:7], off
	v_lshl_add_u64 v[4:5], v[4:5], 0, s[50:51]
	s_add_i32 m0, s19, 0x1a000
	s_add_i32 s45, s19, 0x8000
	s_add_i32 s53, s19, 0xa000
	global_load_lds_dwordx4 v[4:5], off
	v_lshl_add_u64 v[2:3], v[2:3], 0, s[50:51]
	s_mov_b32 m0, s45
	s_add_u32 s54, s42, 0x80080
	global_load_lds_dwordx4 v[2:3], off
	v_lshl_add_u64 v[0:1], v[0:1], 0, s[50:51]
	s_mov_b32 m0, s53
	s_addc_u32 s55, s43, 0
	global_load_lds_dwordx4 v[0:1], off
	s_add_i32 m0, s19, 0x1c000
	v_lshl_add_u64 v[0:1], s[54:55], 0, v[156:157]
	global_load_lds_dwordx4 v[0:1], off
	v_lshl_add_u64 v[0:1], s[54:55], 0, v[128:129]
	s_add_i32 m0, s19, 0x1e000
	s_add_u32 s2, s6, s2
	global_load_lds_dwordx4 v[0:1], off
	s_addc_u32 s3, s7, s3
	v_lshlrev_b32_e32 v0, 15, v11
	v_and_b32_e32 v0, 0xffff0000, v0
	s_add_u32 s2, s26, s2
	v_lshl_add_u32 v0, v12, 12, v0
	v_and_b32_e32 v1, 1, v11
	s_addc_u32 s3, s27, s3
	v_lshl_or_b32 v0, v1, 6, v0
	s_add_u32 s2, s2, 0x19524080
	v_lshl_add_u32 v0, v13, 1, v0
	v_mov_b32_e32 v1, v157
	s_addc_u32 s3, s3, 0
	v_lshl_add_u64 v[132:133], s[2:3], 0, v[0:1]
	v_lshlrev_b32_e32 v0, 15, v8
	v_and_b32_e32 v0, 0xffff0000, v0
	v_lshl_add_u32 v0, v9, 12, v0
	v_and_b32_e32 v1, 1, v8
	v_lshl_or_b32 v0, v1, 6, v0
	s_waitcnt vmcnt(6)
	v_lshl_add_u32 v0, v10, 1, v0
	v_mov_b32_e32 v1, v157
	v_lshl_add_u64 v[134:135], s[2:3], 0, v[0:1]
	v_bitop3_b32 v136, s21, v14, v15 bitop3:0xf6
	s_mov_b32 s54, -2
	s_mov_b64 s[6:7], 0
	v_add_u32_e32 v137, 0, v16
	s_barrier
	s_add_u32 s60, s6, 0x100
	s_addc_u32 s61, s7, 0
	s_cmp_lg_u32 s54, 28
	s_cselect_b32 s55, s60, 0
	s_cselect_b32 s21, s61, 0
	s_add_u32 s2, s48, s55
	s_addc_u32 s3, s49, s21
	s_add_i32 s66, 0, 0x10000
	v_add_u32_e32 v150, s66, v136
	ds_read_b128 v[138:141], v150
	ds_read_b128 v[146:149], v150 offset:2048
	ds_read_b128 v[142:145], v150 offset:1024
	ds_read_b128 v[150:153], v150 offset:3072
	s_add_u32 s62, s42, s55
	s_addc_u32 s63, s43, s21
	v_lshl_add_u64 v[154:155], v[134:135], 0, s[6:7]
	s_add_i32 m0, s19, 0xc000
	ds_read_b128 v[162:165], v137
	ds_read_b128 v[170:173], v137 offset:2048
	ds_read_b128 v[178:181], v137 offset:4096
	ds_read_b128 v[186:189], v137 offset:6144
	ds_read_b128 v[166:169], v137 offset:1024
	ds_read_b128 v[174:177], v137 offset:3072
	ds_read_b128 v[182:185], v137 offset:5120
	ds_read_b128 v[206:209], v137 offset:7168
	global_load_lds_dwordx4 v[154:155], off
	v_lshl_add_u64 v[154:155], v[132:133], 0, s[6:7]
	s_add_i32 m0, s19, 0xe000
	s_nop 0
	global_load_lds_dwordx4 v[154:155], off
	s_waitcnt lgkmcnt(8)
	s_barrier
	s_waitcnt lgkmcnt(7)
	v_mfma_f32_16x16x32_bf16 v[124:127], v[138:141], v[162:165], 0
	v_mfma_f32_16x16x32_bf16 v[120:123], v[146:149], v[162:165], 0
	s_waitcnt lgkmcnt(6)
	v_mfma_f32_16x16x32_bf16 v[116:119], v[138:141], v[170:173], 0
	v_mfma_f32_16x16x32_bf16 v[112:115], v[146:149], v[170:173], 0
	s_waitcnt lgkmcnt(5)
	v_mfma_f32_16x16x32_bf16 v[108:111], v[138:141], v[178:181], 0
	v_mfma_f32_16x16x32_bf16 v[100:103], v[146:149], v[178:181], 0
	s_waitcnt lgkmcnt(4)
	v_mfma_f32_16x16x32_bf16 v[92:95], v[138:141], v[186:189], 0
	v_mfma_f32_16x16x32_bf16 v[84:87], v[146:149], v[186:189], 0
	s_waitcnt lgkmcnt(3)
	v_mfma_f32_16x16x32_bf16 v[124:127], v[142:145], v[166:169], v[124:127]
	v_mfma_f32_16x16x32_bf16 v[120:123], v[150:153], v[166:169], v[120:123]
	s_waitcnt lgkmcnt(2)
	v_mfma_f32_16x16x32_bf16 v[116:119], v[142:145], v[174:177], v[116:119]
	v_mfma_f32_16x16x32_bf16 v[112:115], v[150:153], v[174:177], v[112:115]
	s_waitcnt lgkmcnt(1)
	v_mfma_f32_16x16x32_bf16 v[108:111], v[142:145], v[182:185], v[108:111]
	v_mfma_f32_16x16x32_bf16 v[100:103], v[150:153], v[182:185], v[100:103]
	s_waitcnt lgkmcnt(0)
	v_mfma_f32_16x16x32_bf16 v[92:95], v[142:145], v[206:209], v[92:95]
	v_mfma_f32_16x16x32_bf16 v[84:87], v[150:153], v[206:209], v[84:87]
	s_barrier
	s_add_i32 s21, 0, 0x14000
	v_add_u32_e32 v154, s21, v136
	s_add_i32 s6, s66, s10
	ds_read_b128 v[214:217], v154
	ds_read_b128 v[222:225], v154 offset:2048
	ds_read_b128 v[218:221], v154 offset:1024
	ds_read_b128 v[226:229], v154 offset:3072
	v_lshl_add_u64 v[154:155], s[62:63], 0, v[156:157]
	s_mov_b32 m0, s6
	v_lshl_add_u64 v[230:231], s[62:63], 0, v[128:129]
	global_load_lds_dwordx4 v[154:155], off
	s_add_i32 m0, s6, 0x2000
	s_nop 0
	global_load_lds_dwordx4 v[230:231], off
	s_barrier
	s_waitcnt lgkmcnt(3)
	v_mfma_f32_16x16x32_bf16 v[104:107], v[214:217], v[162:165], 0
	s_waitcnt lgkmcnt(2)
	v_mfma_f32_16x16x32_bf16 v[96:99], v[222:225], v[162:165], 0
	v_mfma_f32_16x16x32_bf16 v[88:91], v[214:217], v[170:173], 0
	v_mfma_f32_16x16x32_bf16 v[80:83], v[222:225], v[170:173], 0
	v_mfma_f32_16x16x32_bf16 v[76:79], v[214:217], v[178:181], 0
	v_mfma_f32_16x16x32_bf16 v[72:75], v[222:225], v[178:181], 0
	v_mfma_f32_16x16x32_bf16 v[68:71], v[214:217], v[186:189], 0
	v_mfma_f32_16x16x32_bf16 v[64:67], v[222:225], v[186:189], 0
	s_waitcnt lgkmcnt(1)
	v_mfma_f32_16x16x32_bf16 v[104:107], v[218:221], v[166:169], v[104:107]
	s_waitcnt lgkmcnt(0)
	v_mfma_f32_16x16x32_bf16 v[96:99], v[226:229], v[166:169], v[96:99]
	v_mfma_f32_16x16x32_bf16 v[88:91], v[218:221], v[174:177], v[88:91]
	v_mfma_f32_16x16x32_bf16 v[80:83], v[226:229], v[174:177], v[80:83]
	v_mfma_f32_16x16x32_bf16 v[76:79], v[218:221], v[182:185], v[76:79]
	v_mfma_f32_16x16x32_bf16 v[72:75], v[226:229], v[182:185], v[72:75]
	v_mfma_f32_16x16x32_bf16 v[68:71], v[218:221], v[206:209], v[68:71]
	v_mfma_f32_16x16x32_bf16 v[64:67], v[226:229], v[206:209], v[64:67]
	s_mov_b32 m0, s19
	v_lshl_add_u64 v[232:233], s[2:3], 0, v[156:157]
	s_barrier
	ds_read_b128 v[162:165], v137 offset:16384
	ds_read_b128 v[170:173], v137 offset:18432
	ds_read_b128 v[178:181], v137 offset:20480
	ds_read_b128 v[186:189], v137 offset:22528
	ds_read_b128 v[166:169], v137 offset:17408
	ds_read_b128 v[174:177], v137 offset:19456
	ds_read_b128 v[182:185], v137 offset:21504
	ds_read_b128 v[206:209], v137 offset:23552
	global_load_lds_dwordx4 v[232:233], off
	v_lshl_add_u64 v[234:235], s[2:3], 0, v[128:129]
	s_mov_b32 m0, s24
	s_nop 0
	global_load_lds_dwordx4 v[234:235], off
	s_barrier
	s_waitcnt lgkmcnt(7)
	v_mfma_f32_16x16x32_bf16 v[60:63], v[138:141], v[162:165], 0
	v_mfma_f32_16x16x32_bf16 v[56:59], v[146:149], v[162:165], 0
	s_waitcnt lgkmcnt(6)
	v_mfma_f32_16x16x32_bf16 v[52:55], v[138:141], v[170:173], 0
	v_mfma_f32_16x16x32_bf16 v[48:51], v[146:149], v[170:173], 0
	s_waitcnt lgkmcnt(5)
	v_mfma_f32_16x16x32_bf16 v[40:43], v[138:141], v[178:181], 0
	v_mfma_f32_16x16x32_bf16 v[32:35], v[146:149], v[178:181], 0
	s_waitcnt lgkmcnt(4)
	v_mfma_f32_16x16x32_bf16 v[24:27], v[138:141], v[186:189], 0
	v_mfma_f32_16x16x32_bf16 v[16:19], v[146:149], v[186:189], 0
	s_waitcnt lgkmcnt(3)
	v_mfma_f32_16x16x32_bf16 v[60:63], v[142:145], v[166:169], v[60:63]
	v_mfma_f32_16x16x32_bf16 v[56:59], v[150:153], v[166:169], v[56:59]
	s_waitcnt lgkmcnt(2)
	v_mfma_f32_16x16x32_bf16 v[52:55], v[142:145], v[174:177], v[52:55]
	v_mfma_f32_16x16x32_bf16 v[48:51], v[150:153], v[174:177], v[48:51]
	s_waitcnt lgkmcnt(1)
	v_mfma_f32_16x16x32_bf16 v[40:43], v[142:145], v[182:185], v[40:43]
	v_mfma_f32_16x16x32_bf16 v[32:35], v[150:153], v[182:185], v[32:35]
	s_waitcnt lgkmcnt(0)
	v_mfma_f32_16x16x32_bf16 v[24:27], v[142:145], v[206:209], v[24:27]
	v_mfma_f32_16x16x32_bf16 v[16:19], v[150:153], v[206:209], v[16:19]
	s_barrier
	s_add_u32 s6, s62, 0x80000
	s_addc_u32 s7, s63, 0
	s_add_i32 s21, s21, s10
	v_lshl_add_u64 v[138:139], s[6:7], 0, v[156:157]
	s_mov_b32 m0, s21
	s_nop 0
	global_load_lds_dwordx4 v[138:139], off
	v_lshl_add_u64 v[138:139], s[6:7], 0, v[128:129]
	s_add_i32 m0, s21, 0x2000
	s_nop 0
	global_load_lds_dwordx4 v[138:139], off
	s_waitcnt vmcnt(6)
	s_barrier
	v_mfma_f32_16x16x32_bf16 v[44:47], v[214:217], v[162:165], 0
	v_mfma_f32_16x16x32_bf16 v[36:39], v[222:225], v[162:165], 0
	v_mfma_f32_16x16x32_bf16 v[28:31], v[214:217], v[170:173], 0
	v_mfma_f32_16x16x32_bf16 v[20:23], v[222:225], v[170:173], 0
	v_mfma_f32_16x16x32_bf16 v[12:15], v[214:217], v[178:181], 0
	v_mfma_f32_16x16x32_bf16 v[8:11], v[222:225], v[178:181], 0
	v_mfma_f32_16x16x32_bf16 v[4:7], v[214:217], v[186:189], 0
	v_mfma_f32_16x16x32_bf16 v[0:3], v[222:225], v[186:189], 0
	v_mfma_f32_16x16x32_bf16 v[44:47], v[218:221], v[166:169], v[44:47]
	v_mfma_f32_16x16x32_bf16 v[36:39], v[226:229], v[166:169], v[36:39]
	v_mfma_f32_16x16x32_bf16 v[28:31], v[218:221], v[174:177], v[28:31]
	v_mfma_f32_16x16x32_bf16 v[20:23], v[226:229], v[174:177], v[20:23]
	v_mfma_f32_16x16x32_bf16 v[12:15], v[218:221], v[182:185], v[12:15]
	v_mfma_f32_16x16x32_bf16 v[8:11], v[226:229], v[182:185], v[8:11]
	v_mfma_f32_16x16x32_bf16 v[4:7], v[218:221], v[206:209], v[4:7]
	v_mfma_f32_16x16x32_bf16 v[0:3], v[226:229], v[206:209], v[0:3]
	s_add_i32 s6, 0, 0x18000
	v_add_u32_e32 v150, s6, v136
	s_barrier
	ds_read_b128 v[138:141], v150
	ds_read_b128 v[146:149], v150 offset:2048
	ds_read_b128 v[142:145], v150 offset:1024
	ds_read_b128 v[150:153], v150 offset:3072
	s_add_u32 s2, s2, 0x80000
	s_addc_u32 s3, s3, 0
	s_mov_b32 m0, s25
	v_lshl_add_u64 v[214:215], s[2:3], 0, v[156:157]
	ds_read_b128 v[162:165], v137 offset:32768
	ds_read_b128 v[170:173], v137 offset:34816
	ds_read_b128 v[178:181], v137 offset:36864
	ds_read_b128 v[186:189], v137 offset:38912
	ds_read_b128 v[166:169], v137 offset:33792
	ds_read_b128 v[174:177], v137 offset:35840
	ds_read_b128 v[182:185], v137 offset:37888
	ds_read_b128 v[206:209], v137 offset:39936
	global_load_lds_dwordx4 v[214:215], off
	v_lshl_add_u64 v[214:215], s[2:3], 0, v[128:129]
	s_mov_b32 m0, s34
	s_nop 0
	global_load_lds_dwordx4 v[214:215], off
	s_waitcnt lgkmcnt(8)
	s_barrier
	s_waitcnt lgkmcnt(7)
	v_mfma_f32_16x16x32_bf16 v[124:127], v[138:141], v[162:165], v[124:127]
	v_mfma_f32_16x16x32_bf16 v[120:123], v[146:149], v[162:165], v[120:123]
	s_waitcnt lgkmcnt(6)
	v_mfma_f32_16x16x32_bf16 v[116:119], v[138:141], v[170:173], v[116:119]
	v_mfma_f32_16x16x32_bf16 v[112:115], v[146:149], v[170:173], v[112:115]
	s_waitcnt lgkmcnt(5)
	v_mfma_f32_16x16x32_bf16 v[108:111], v[138:141], v[178:181], v[108:111]
	v_mfma_f32_16x16x32_bf16 v[100:103], v[146:149], v[178:181], v[100:103]
	s_waitcnt lgkmcnt(4)
	v_mfma_f32_16x16x32_bf16 v[92:95], v[138:141], v[186:189], v[92:95]
	v_mfma_f32_16x16x32_bf16 v[84:87], v[146:149], v[186:189], v[84:87]
	s_waitcnt lgkmcnt(3)
	v_mfma_f32_16x16x32_bf16 v[124:127], v[142:145], v[166:169], v[124:127]
	v_mfma_f32_16x16x32_bf16 v[120:123], v[150:153], v[166:169], v[120:123]
	s_waitcnt lgkmcnt(2)
	v_mfma_f32_16x16x32_bf16 v[116:119], v[142:145], v[174:177], v[116:119]
	v_mfma_f32_16x16x32_bf16 v[112:115], v[150:153], v[174:177], v[112:115]
	s_waitcnt lgkmcnt(1)
	v_mfma_f32_16x16x32_bf16 v[108:111], v[142:145], v[182:185], v[108:111]
	v_mfma_f32_16x16x32_bf16 v[100:103], v[150:153], v[182:185], v[100:103]
	s_waitcnt lgkmcnt(0)
	v_mfma_f32_16x16x32_bf16 v[92:95], v[142:145], v[206:209], v[92:95]
	v_mfma_f32_16x16x32_bf16 v[84:87], v[150:153], v[206:209], v[84:87]
	s_barrier
	s_add_i32 s7, 0, 0x1c000
	s_add_i32 s2, s6, s10
	v_add_u32_e32 v161, s7, v136
	v_lshl_add_u64 v[154:155], v[154:155], 0, s[50:51]
	s_mov_b32 m0, s2
	ds_read_b128 v[214:217], v161
	ds_read_b128 v[222:225], v161 offset:2048
	ds_read_b128 v[218:221], v161 offset:1024
	ds_read_b128 v[226:229], v161 offset:3072
	global_load_lds_dwordx4 v[154:155], off
	v_lshl_add_u64 v[154:155], v[230:231], 0, s[50:51]
	s_add_i32 m0, s2, 0x2000
	s_nop 0
	global_load_lds_dwordx4 v[154:155], off
	s_barrier
	s_waitcnt lgkmcnt(3)
	v_mfma_f32_16x16x32_bf16 v[104:107], v[214:217], v[162:165], v[104:107]
	s_waitcnt lgkmcnt(2)
	v_mfma_f32_16x16x32_bf16 v[96:99], v[222:225], v[162:165], v[96:99]
	v_mfma_f32_16x16x32_bf16 v[88:91], v[214:217], v[170:173], v[88:91]
	v_mfma_f32_16x16x32_bf16 v[80:83], v[222:225], v[170:173], v[80:83]
	v_mfma_f32_16x16x32_bf16 v[76:79], v[214:217], v[178:181], v[76:79]
	v_mfma_f32_16x16x32_bf16 v[72:75], v[222:225], v[178:181], v[72:75]
	v_mfma_f32_16x16x32_bf16 v[68:71], v[214:217], v[186:189], v[68:71]
	v_mfma_f32_16x16x32_bf16 v[64:67], v[222:225], v[186:189], v[64:67]
	s_waitcnt lgkmcnt(1)
	v_mfma_f32_16x16x32_bf16 v[104:107], v[218:221], v[166:169], v[104:107]
	s_waitcnt lgkmcnt(0)
	v_mfma_f32_16x16x32_bf16 v[96:99], v[226:229], v[166:169], v[96:99]
	v_mfma_f32_16x16x32_bf16 v[88:91], v[218:221], v[174:177], v[88:91]
	v_mfma_f32_16x16x32_bf16 v[80:83], v[226:229], v[174:177], v[80:83]
	v_mfma_f32_16x16x32_bf16 v[76:79], v[218:221], v[182:185], v[76:79]
	v_mfma_f32_16x16x32_bf16 v[72:75], v[226:229], v[182:185], v[72:75]
	v_mfma_f32_16x16x32_bf16 v[68:71], v[218:221], v[206:209], v[68:71]
	v_mfma_f32_16x16x32_bf16 v[64:67], v[226:229], v[206:209], v[64:67]
	s_mov_b32 m0, s45
	v_lshl_add_u64 v[154:155], v[232:233], 0, s[50:51]
	s_barrier
	ds_read_b128 v[162:165], v137 offset:49152
	ds_read_b128 v[170:173], v137 offset:51200
	ds_read_b128 v[178:181], v137 offset:53248
	ds_read_b128 v[186:189], v137 offset:55296
	ds_read_b128 v[166:169], v137 offset:50176
	ds_read_b128 v[174:177], v137 offset:52224
	ds_read_b128 v[182:185], v137 offset:54272
	ds_read_b128 v[206:209], v137 offset:56320
	global_load_lds_dwordx4 v[154:155], off
	v_lshl_add_u64 v[154:155], v[234:235], 0, s[50:51]
	s_mov_b32 m0, s53
	s_nop 0
	global_load_lds_dwordx4 v[154:155], off
	s_barrier
	s_waitcnt lgkmcnt(7)
	v_mfma_f32_16x16x32_bf16 v[60:63], v[138:141], v[162:165], v[60:63]
	v_mfma_f32_16x16x32_bf16 v[56:59], v[146:149], v[162:165], v[56:59]
	s_waitcnt lgkmcnt(6)
	v_mfma_f32_16x16x32_bf16 v[52:55], v[138:141], v[170:173], v[52:55]
	v_mfma_f32_16x16x32_bf16 v[48:51], v[146:149], v[170:173], v[48:51]
	s_waitcnt lgkmcnt(5)
	v_mfma_f32_16x16x32_bf16 v[40:43], v[138:141], v[178:181], v[40:43]
	v_mfma_f32_16x16x32_bf16 v[32:35], v[146:149], v[178:181], v[32:35]
	s_waitcnt lgkmcnt(4)
	v_mfma_f32_16x16x32_bf16 v[24:27], v[138:141], v[186:189], v[24:27]
	v_mfma_f32_16x16x32_bf16 v[16:19], v[146:149], v[186:189], v[16:19]
	s_waitcnt lgkmcnt(3)
	v_mfma_f32_16x16x32_bf16 v[60:63], v[142:145], v[166:169], v[60:63]
	v_mfma_f32_16x16x32_bf16 v[56:59], v[150:153], v[166:169], v[56:59]
	s_waitcnt lgkmcnt(2)
	v_mfma_f32_16x16x32_bf16 v[52:55], v[142:145], v[174:177], v[52:55]
	v_mfma_f32_16x16x32_bf16 v[48:51], v[150:153], v[174:177], v[48:51]
	s_waitcnt lgkmcnt(1)
	v_mfma_f32_16x16x32_bf16 v[40:43], v[142:145], v[182:185], v[40:43]
	v_mfma_f32_16x16x32_bf16 v[32:35], v[150:153], v[182:185], v[32:35]
	s_waitcnt lgkmcnt(0)
	v_mfma_f32_16x16x32_bf16 v[24:27], v[142:145], v[206:209], v[24:27]
	v_mfma_f32_16x16x32_bf16 v[16:19], v[150:153], v[206:209], v[16:19]
	s_barrier
	s_add_u32 s2, s62, 0x80080
	s_addc_u32 s3, s63, 0
	s_add_i32 s6, s7, s10
	v_lshl_add_u64 v[138:139], s[2:3], 0, v[156:157]
	s_mov_b32 m0, s6
	s_nop 0
	global_load_lds_dwordx4 v[138:139], off
	v_lshl_add_u64 v[138:139], s[2:3], 0, v[128:129]
	s_add_i32 m0, s6, 0x2000
	s_nop 0
	global_load_lds_dwordx4 v[138:139], off
	s_waitcnt vmcnt(6)
	s_barrier
	v_mfma_f32_16x16x32_bf16 v[44:47], v[214:217], v[162:165], v[44:47]
	v_mfma_f32_16x16x32_bf16 v[36:39], v[222:225], v[162:165], v[36:39]
	v_mfma_f32_16x16x32_bf16 v[28:31], v[214:217], v[170:173], v[28:31]
	v_mfma_f32_16x16x32_bf16 v[20:23], v[222:225], v[170:173], v[20:23]
	v_mfma_f32_16x16x32_bf16 v[12:15], v[214:217], v[178:181], v[12:15]
	v_mfma_f32_16x16x32_bf16 v[8:11], v[222:225], v[178:181], v[8:11]
	v_mfma_f32_16x16x32_bf16 v[4:7], v[214:217], v[186:189], v[4:7]
	v_mfma_f32_16x16x32_bf16 v[0:3], v[222:225], v[186:189], v[0:3]
	v_mfma_f32_16x16x32_bf16 v[44:47], v[218:221], v[166:169], v[44:47]
	v_mfma_f32_16x16x32_bf16 v[36:39], v[226:229], v[166:169], v[36:39]
	v_mfma_f32_16x16x32_bf16 v[28:31], v[218:221], v[174:177], v[28:31]
	v_mfma_f32_16x16x32_bf16 v[20:23], v[226:229], v[174:177], v[20:23]
	v_mfma_f32_16x16x32_bf16 v[12:15], v[218:221], v[182:185], v[12:15]
	v_mfma_f32_16x16x32_bf16 v[8:11], v[226:229], v[182:185], v[8:11]
	v_mfma_f32_16x16x32_bf16 v[4:7], v[218:221], v[206:209], v[4:7]
	v_mfma_f32_16x16x32_bf16 v[0:3], v[226:229], v[206:209], v[0:3]
	s_add_i32 s54, s54, 2
	s_cmp_gt_u32 s54, 29
	s_mov_b64 s[6:7], s[60:61]
	s_barrier
	s_cbranch_scc1 .Lpost_286
.LBB0_286:
	s_add_u32 s60, s6, 0x100
	s_addc_u32 s61, s7, 0
	s_cmp_lg_u32 s54, 28
	s_cselect_b32 s55, s60, 0
	s_cselect_b32 s21, s61, 0
	s_add_u32 s2, s48, s55
	s_addc_u32 s3, s49, s21
	s_add_i32 s66, 0, 0x10000
	v_add_u32_e32 v150, s66, v136
	ds_read_b128 v[138:141], v150
	ds_read_b128 v[146:149], v150 offset:2048
	ds_read_b128 v[142:145], v150 offset:1024
	ds_read_b128 v[150:153], v150 offset:3072
	s_add_u32 s62, s42, s55
	s_addc_u32 s63, s43, s21
	v_lshl_add_u64 v[154:155], v[134:135], 0, s[6:7]
	s_add_i32 m0, s19, 0xc000
	ds_read_b128 v[162:165], v137
	ds_read_b128 v[170:173], v137 offset:2048
	ds_read_b128 v[178:181], v137 offset:4096
	ds_read_b128 v[186:189], v137 offset:6144
	ds_read_b128 v[166:169], v137 offset:1024
	ds_read_b128 v[174:177], v137 offset:3072
	ds_read_b128 v[182:185], v137 offset:5120
	ds_read_b128 v[206:209], v137 offset:7168
	global_load_lds_dwordx4 v[154:155], off
	v_lshl_add_u64 v[154:155], v[132:133], 0, s[6:7]
	s_add_i32 m0, s19, 0xe000
	s_nop 0
	global_load_lds_dwordx4 v[154:155], off
	s_waitcnt lgkmcnt(8)
	s_barrier
	s_waitcnt lgkmcnt(7)
	v_mfma_f32_16x16x32_bf16 v[124:127], v[138:141], v[162:165], v[124:127]
	v_mfma_f32_16x16x32_bf16 v[120:123], v[146:149], v[162:165], v[120:123]
	s_waitcnt lgkmcnt(6)
	v_mfma_f32_16x16x32_bf16 v[116:119], v[138:141], v[170:173], v[116:119]
	v_mfma_f32_16x16x32_bf16 v[112:115], v[146:149], v[170:173], v[112:115]
	s_waitcnt lgkmcnt(5)
	v_mfma_f32_16x16x32_bf16 v[108:111], v[138:141], v[178:181], v[108:111]
	v_mfma_f32_16x16x32_bf16 v[100:103], v[146:149], v[178:181], v[100:103]
	s_waitcnt lgkmcnt(4)
	v_mfma_f32_16x16x32_bf16 v[92:95], v[138:141], v[186:189], v[92:95]
	v_mfma_f32_16x16x32_bf16 v[84:87], v[146:149], v[186:189], v[84:87]
	s_waitcnt lgkmcnt(3)
	v_mfma_f32_16x16x32_bf16 v[124:127], v[142:145], v[166:169], v[124:127]
	v_mfma_f32_16x16x32_bf16 v[120:123], v[150:153], v[166:169], v[120:123]
	s_waitcnt lgkmcnt(2)
	v_mfma_f32_16x16x32_bf16 v[116:119], v[142:145], v[174:177], v[116:119]
	v_mfma_f32_16x16x32_bf16 v[112:115], v[150:153], v[174:177], v[112:115]
	s_waitcnt lgkmcnt(1)
	v_mfma_f32_16x16x32_bf16 v[108:111], v[142:145], v[182:185], v[108:111]
	v_mfma_f32_16x16x32_bf16 v[100:103], v[150:153], v[182:185], v[100:103]
	s_waitcnt lgkmcnt(0)
	v_mfma_f32_16x16x32_bf16 v[92:95], v[142:145], v[206:209], v[92:95]
	v_mfma_f32_16x16x32_bf16 v[84:87], v[150:153], v[206:209], v[84:87]
	s_barrier
	s_add_i32 s21, 0, 0x14000
	v_add_u32_e32 v154, s21, v136
	s_add_i32 s6, s66, s10
	ds_read_b128 v[214:217], v154
	ds_read_b128 v[222:225], v154 offset:2048
	ds_read_b128 v[218:221], v154 offset:1024
	ds_read_b128 v[226:229], v154 offset:3072
	v_lshl_add_u64 v[154:155], s[62:63], 0, v[156:157]
	s_mov_b32 m0, s6
	v_lshl_add_u64 v[230:231], s[62:63], 0, v[128:129]
	global_load_lds_dwordx4 v[154:155], off
	s_add_i32 m0, s6, 0x2000
	s_nop 0
	global_load_lds_dwordx4 v[230:231], off
	s_barrier
	s_waitcnt lgkmcnt(3)
	v_mfma_f32_16x16x32_bf16 v[104:107], v[214:217], v[162:165], v[104:107]
	s_waitcnt lgkmcnt(2)
	v_mfma_f32_16x16x32_bf16 v[96:99], v[222:225], v[162:165], v[96:99]
	v_mfma_f32_16x16x32_bf16 v[88:91], v[214:217], v[170:173], v[88:91]
	v_mfma_f32_16x16x32_bf16 v[80:83], v[222:225], v[170:173], v[80:83]
	v_mfma_f32_16x16x32_bf16 v[76:79], v[214:217], v[178:181], v[76:79]
	v_mfma_f32_16x16x32_bf16 v[72:75], v[222:225], v[178:181], v[72:75]
	v_mfma_f32_16x16x32_bf16 v[68:71], v[214:217], v[186:189], v[68:71]
	v_mfma_f32_16x16x32_bf16 v[64:67], v[222:225], v[186:189], v[64:67]
	s_waitcnt lgkmcnt(1)
	v_mfma_f32_16x16x32_bf16 v[104:107], v[218:221], v[166:169], v[104:107]
	s_waitcnt lgkmcnt(0)
	v_mfma_f32_16x16x32_bf16 v[96:99], v[226:229], v[166:169], v[96:99]
	v_mfma_f32_16x16x32_bf16 v[88:91], v[218:221], v[174:177], v[88:91]
	v_mfma_f32_16x16x32_bf16 v[80:83], v[226:229], v[174:177], v[80:83]
	v_mfma_f32_16x16x32_bf16 v[76:79], v[218:221], v[182:185], v[76:79]
	v_mfma_f32_16x16x32_bf16 v[72:75], v[226:229], v[182:185], v[72:75]
	v_mfma_f32_16x16x32_bf16 v[68:71], v[218:221], v[206:209], v[68:71]
	v_mfma_f32_16x16x32_bf16 v[64:67], v[226:229], v[206:209], v[64:67]
	s_mov_b32 m0, s19
	v_lshl_add_u64 v[232:233], s[2:3], 0, v[156:157]
	s_barrier
	ds_read_b128 v[162:165], v137 offset:16384
	ds_read_b128 v[170:173], v137 offset:18432
	ds_read_b128 v[178:181], v137 offset:20480
	ds_read_b128 v[186:189], v137 offset:22528
	ds_read_b128 v[166:169], v137 offset:17408
	ds_read_b128 v[174:177], v137 offset:19456
	ds_read_b128 v[182:185], v137 offset:21504
	ds_read_b128 v[206:209], v137 offset:23552
	global_load_lds_dwordx4 v[232:233], off
	v_lshl_add_u64 v[234:235], s[2:3], 0, v[128:129]
	s_mov_b32 m0, s24
	s_nop 0
	global_load_lds_dwordx4 v[234:235], off
	s_barrier
	s_waitcnt lgkmcnt(7)
	v_mfma_f32_16x16x32_bf16 v[60:63], v[138:141], v[162:165], v[60:63]
	v_mfma_f32_16x16x32_bf16 v[56:59], v[146:149], v[162:165], v[56:59]
	s_waitcnt lgkmcnt(6)
	v_mfma_f32_16x16x32_bf16 v[52:55], v[138:141], v[170:173], v[52:55]
	v_mfma_f32_16x16x32_bf16 v[48:51], v[146:149], v[170:173], v[48:51]
	s_waitcnt lgkmcnt(5)
	v_mfma_f32_16x16x32_bf16 v[40:43], v[138:141], v[178:181], v[40:43]
	v_mfma_f32_16x16x32_bf16 v[32:35], v[146:149], v[178:181], v[32:35]
	s_waitcnt lgkmcnt(4)
	v_mfma_f32_16x16x32_bf16 v[24:27], v[138:141], v[186:189], v[24:27]
	v_mfma_f32_16x16x32_bf16 v[16:19], v[146:149], v[186:189], v[16:19]
	s_waitcnt lgkmcnt(3)
	v_mfma_f32_16x16x32_bf16 v[60:63], v[142:145], v[166:169], v[60:63]
	v_mfma_f32_16x16x32_bf16 v[56:59], v[150:153], v[166:169], v[56:59]
	s_waitcnt lgkmcnt(2)
	v_mfma_f32_16x16x32_bf16 v[52:55], v[142:145], v[174:177], v[52:55]
	v_mfma_f32_16x16x32_bf16 v[48:51], v[150:153], v[174:177], v[48:51]
	s_waitcnt lgkmcnt(1)
	v_mfma_f32_16x16x32_bf16 v[40:43], v[142:145], v[182:185], v[40:43]
	v_mfma_f32_16x16x32_bf16 v[32:35], v[150:153], v[182:185], v[32:35]
	s_waitcnt lgkmcnt(0)
	v_mfma_f32_16x16x32_bf16 v[24:27], v[142:145], v[206:209], v[24:27]
	v_mfma_f32_16x16x32_bf16 v[16:19], v[150:153], v[206:209], v[16:19]
	s_barrier
	s_add_u32 s6, s62, 0x80000
	s_addc_u32 s7, s63, 0
	s_add_i32 s21, s21, s10
	v_lshl_add_u64 v[138:139], s[6:7], 0, v[156:157]
	s_mov_b32 m0, s21
	s_nop 0
	global_load_lds_dwordx4 v[138:139], off
	v_lshl_add_u64 v[138:139], s[6:7], 0, v[128:129]
	s_add_i32 m0, s21, 0x2000
	s_nop 0
	global_load_lds_dwordx4 v[138:139], off
	s_waitcnt vmcnt(6)
	s_barrier
	v_mfma_f32_16x16x32_bf16 v[44:47], v[214:217], v[162:165], v[44:47]
	v_mfma_f32_16x16x32_bf16 v[36:39], v[222:225], v[162:165], v[36:39]
	v_mfma_f32_16x16x32_bf16 v[28:31], v[214:217], v[170:173], v[28:31]
	v_mfma_f32_16x16x32_bf16 v[20:23], v[222:225], v[170:173], v[20:23]
	v_mfma_f32_16x16x32_bf16 v[12:15], v[214:217], v[178:181], v[12:15]
	v_mfma_f32_16x16x32_bf16 v[8:11], v[222:225], v[178:181], v[8:11]
	v_mfma_f32_16x16x32_bf16 v[4:7], v[214:217], v[186:189], v[4:7]
	v_mfma_f32_16x16x32_bf16 v[0:3], v[222:225], v[186:189], v[0:3]
	v_mfma_f32_16x16x32_bf16 v[44:47], v[218:221], v[166:169], v[44:47]
	v_mfma_f32_16x16x32_bf16 v[36:39], v[226:229], v[166:169], v[36:39]
	v_mfma_f32_16x16x32_bf16 v[28:31], v[218:221], v[174:177], v[28:31]
	v_mfma_f32_16x16x32_bf16 v[20:23], v[226:229], v[174:177], v[20:23]
	v_mfma_f32_16x16x32_bf16 v[12:15], v[218:221], v[182:185], v[12:15]
	v_mfma_f32_16x16x32_bf16 v[8:11], v[226:229], v[182:185], v[8:11]
	v_mfma_f32_16x16x32_bf16 v[4:7], v[218:221], v[206:209], v[4:7]
	v_mfma_f32_16x16x32_bf16 v[0:3], v[226:229], v[206:209], v[0:3]
	s_add_i32 s6, 0, 0x18000
	v_add_u32_e32 v150, s6, v136
	s_barrier
	ds_read_b128 v[138:141], v150
	ds_read_b128 v[146:149], v150 offset:2048
	ds_read_b128 v[142:145], v150 offset:1024
	ds_read_b128 v[150:153], v150 offset:3072
	s_add_u32 s2, s2, 0x80000
	s_addc_u32 s3, s3, 0
	s_mov_b32 m0, s25
	v_lshl_add_u64 v[214:215], s[2:3], 0, v[156:157]
	ds_read_b128 v[162:165], v137 offset:32768
	ds_read_b128 v[170:173], v137 offset:34816
	ds_read_b128 v[178:181], v137 offset:36864
	ds_read_b128 v[186:189], v137 offset:38912
	ds_read_b128 v[166:169], v137 offset:33792
	ds_read_b128 v[174:177], v137 offset:35840
	ds_read_b128 v[182:185], v137 offset:37888
	ds_read_b128 v[206:209], v137 offset:39936
	global_load_lds_dwordx4 v[214:215], off
	v_lshl_add_u64 v[214:215], s[2:3], 0, v[128:129]
	s_mov_b32 m0, s34
	s_nop 0
	global_load_lds_dwordx4 v[214:215], off
	s_waitcnt lgkmcnt(8)
	s_barrier
	s_waitcnt lgkmcnt(7)
	v_mfma_f32_16x16x32_bf16 v[124:127], v[138:141], v[162:165], v[124:127]
	v_mfma_f32_16x16x32_bf16 v[120:123], v[146:149], v[162:165], v[120:123]
	s_waitcnt lgkmcnt(6)
	v_mfma_f32_16x16x32_bf16 v[116:119], v[138:141], v[170:173], v[116:119]
	v_mfma_f32_16x16x32_bf16 v[112:115], v[146:149], v[170:173], v[112:115]
	s_waitcnt lgkmcnt(5)
	v_mfma_f32_16x16x32_bf16 v[108:111], v[138:141], v[178:181], v[108:111]
	v_mfma_f32_16x16x32_bf16 v[100:103], v[146:149], v[178:181], v[100:103]
	s_waitcnt lgkmcnt(4)
	v_mfma_f32_16x16x32_bf16 v[92:95], v[138:141], v[186:189], v[92:95]
	v_mfma_f32_16x16x32_bf16 v[84:87], v[146:149], v[186:189], v[84:87]
	s_waitcnt lgkmcnt(3)
	v_mfma_f32_16x16x32_bf16 v[124:127], v[142:145], v[166:169], v[124:127]
	v_mfma_f32_16x16x32_bf16 v[120:123], v[150:153], v[166:169], v[120:123]
	s_waitcnt lgkmcnt(2)
	v_mfma_f32_16x16x32_bf16 v[116:119], v[142:145], v[174:177], v[116:119]
	v_mfma_f32_16x16x32_bf16 v[112:115], v[150:153], v[174:177], v[112:115]
	s_waitcnt lgkmcnt(1)
	v_mfma_f32_16x16x32_bf16 v[108:111], v[142:145], v[182:185], v[108:111]
	v_mfma_f32_16x16x32_bf16 v[100:103], v[150:153], v[182:185], v[100:103]
	s_waitcnt lgkmcnt(0)
	v_mfma_f32_16x16x32_bf16 v[92:95], v[142:145], v[206:209], v[92:95]
	v_mfma_f32_16x16x32_bf16 v[84:87], v[150:153], v[206:209], v[84:87]
	s_barrier
	s_add_i32 s7, 0, 0x1c000
	s_add_i32 s2, s6, s10
	v_add_u32_e32 v161, s7, v136
	v_lshl_add_u64 v[154:155], v[154:155], 0, s[50:51]
	s_mov_b32 m0, s2
	ds_read_b128 v[214:217], v161
	ds_read_b128 v[222:225], v161 offset:2048
	ds_read_b128 v[218:221], v161 offset:1024
	ds_read_b128 v[226:229], v161 offset:3072
	global_load_lds_dwordx4 v[154:155], off
	v_lshl_add_u64 v[154:155], v[230:231], 0, s[50:51]
	s_add_i32 m0, s2, 0x2000
	s_nop 0
	global_load_lds_dwordx4 v[154:155], off
	s_barrier
	s_waitcnt lgkmcnt(3)
	v_mfma_f32_16x16x32_bf16 v[104:107], v[214:217], v[162:165], v[104:107]
	s_waitcnt lgkmcnt(2)
	v_mfma_f32_16x16x32_bf16 v[96:99], v[222:225], v[162:165], v[96:99]
	v_mfma_f32_16x16x32_bf16 v[88:91], v[214:217], v[170:173], v[88:91]
	v_mfma_f32_16x16x32_bf16 v[80:83], v[222:225], v[170:173], v[80:83]
	v_mfma_f32_16x16x32_bf16 v[76:79], v[214:217], v[178:181], v[76:79]
	v_mfma_f32_16x16x32_bf16 v[72:75], v[222:225], v[178:181], v[72:75]
	v_mfma_f32_16x16x32_bf16 v[68:71], v[214:217], v[186:189], v[68:71]
	v_mfma_f32_16x16x32_bf16 v[64:67], v[222:225], v[186:189], v[64:67]
	s_waitcnt lgkmcnt(1)
	v_mfma_f32_16x16x32_bf16 v[104:107], v[218:221], v[166:169], v[104:107]
	s_waitcnt lgkmcnt(0)
	v_mfma_f32_16x16x32_bf16 v[96:99], v[226:229], v[166:169], v[96:99]
	v_mfma_f32_16x16x32_bf16 v[88:91], v[218:221], v[174:177], v[88:91]
	v_mfma_f32_16x16x32_bf16 v[80:83], v[226:229], v[174:177], v[80:83]
	v_mfma_f32_16x16x32_bf16 v[76:79], v[218:221], v[182:185], v[76:79]
	v_mfma_f32_16x16x32_bf16 v[72:75], v[226:229], v[182:185], v[72:75]
	v_mfma_f32_16x16x32_bf16 v[68:71], v[218:221], v[206:209], v[68:71]
	v_mfma_f32_16x16x32_bf16 v[64:67], v[226:229], v[206:209], v[64:67]
	s_mov_b32 m0, s45
	v_lshl_add_u64 v[154:155], v[232:233], 0, s[50:51]
	s_barrier
	ds_read_b128 v[162:165], v137 offset:49152
	ds_read_b128 v[170:173], v137 offset:51200
	ds_read_b128 v[178:181], v137 offset:53248
	ds_read_b128 v[186:189], v137 offset:55296
	ds_read_b128 v[166:169], v137 offset:50176
	ds_read_b128 v[174:177], v137 offset:52224
	ds_read_b128 v[182:185], v137 offset:54272
	ds_read_b128 v[206:209], v137 offset:56320
	global_load_lds_dwordx4 v[154:155], off
	v_lshl_add_u64 v[154:155], v[234:235], 0, s[50:51]
	s_mov_b32 m0, s53
	s_nop 0
	global_load_lds_dwordx4 v[154:155], off
	s_barrier
	s_waitcnt lgkmcnt(7)
	v_mfma_f32_16x16x32_bf16 v[60:63], v[138:141], v[162:165], v[60:63]
	v_mfma_f32_16x16x32_bf16 v[56:59], v[146:149], v[162:165], v[56:59]
	s_waitcnt lgkmcnt(6)
	v_mfma_f32_16x16x32_bf16 v[52:55], v[138:141], v[170:173], v[52:55]
	v_mfma_f32_16x16x32_bf16 v[48:51], v[146:149], v[170:173], v[48:51]
	s_waitcnt lgkmcnt(5)
	v_mfma_f32_16x16x32_bf16 v[40:43], v[138:141], v[178:181], v[40:43]
	v_mfma_f32_16x16x32_bf16 v[32:35], v[146:149], v[178:181], v[32:35]
	s_waitcnt lgkmcnt(4)
	v_mfma_f32_16x16x32_bf16 v[24:27], v[138:141], v[186:189], v[24:27]
	v_mfma_f32_16x16x32_bf16 v[16:19], v[146:149], v[186:189], v[16:19]
	s_waitcnt lgkmcnt(3)
	v_mfma_f32_16x16x32_bf16 v[60:63], v[142:145], v[166:169], v[60:63]
	v_mfma_f32_16x16x32_bf16 v[56:59], v[150:153], v[166:169], v[56:59]
	s_waitcnt lgkmcnt(2)
	v_mfma_f32_16x16x32_bf16 v[52:55], v[142:145], v[174:177], v[52:55]
	v_mfma_f32_16x16x32_bf16 v[48:51], v[150:153], v[174:177], v[48:51]
	s_waitcnt lgkmcnt(1)
	v_mfma_f32_16x16x32_bf16 v[40:43], v[142:145], v[182:185], v[40:43]
	v_mfma_f32_16x16x32_bf16 v[32:35], v[150:153], v[182:185], v[32:35]
	s_waitcnt lgkmcnt(0)
	v_mfma_f32_16x16x32_bf16 v[24:27], v[142:145], v[206:209], v[24:27]
	v_mfma_f32_16x16x32_bf16 v[16:19], v[150:153], v[206:209], v[16:19]
	s_barrier
	s_add_u32 s2, s62, 0x80080
	s_addc_u32 s3, s63, 0
	s_add_i32 s6, s7, s10
	v_lshl_add_u64 v[138:139], s[2:3], 0, v[156:157]
	s_mov_b32 m0, s6
	s_nop 0
	global_load_lds_dwordx4 v[138:139], off
	v_lshl_add_u64 v[138:139], s[2:3], 0, v[128:129]
	s_add_i32 m0, s6, 0x2000
	s_nop 0
	global_load_lds_dwordx4 v[138:139], off
	s_waitcnt vmcnt(6)
	s_barrier
	v_mfma_f32_16x16x32_bf16 v[44:47], v[214:217], v[162:165], v[44:47]
	v_mfma_f32_16x16x32_bf16 v[36:39], v[222:225], v[162:165], v[36:39]
	v_mfma_f32_16x16x32_bf16 v[28:31], v[214:217], v[170:173], v[28:31]
	v_mfma_f32_16x16x32_bf16 v[20:23], v[222:225], v[170:173], v[20:23]
	v_mfma_f32_16x16x32_bf16 v[12:15], v[214:217], v[178:181], v[12:15]
	v_mfma_f32_16x16x32_bf16 v[8:11], v[222:225], v[178:181], v[8:11]
	v_mfma_f32_16x16x32_bf16 v[4:7], v[214:217], v[186:189], v[4:7]
	v_mfma_f32_16x16x32_bf16 v[0:3], v[222:225], v[186:189], v[0:3]
	v_mfma_f32_16x16x32_bf16 v[44:47], v[218:221], v[166:169], v[44:47]
	v_mfma_f32_16x16x32_bf16 v[36:39], v[226:229], v[166:169], v[36:39]
	v_mfma_f32_16x16x32_bf16 v[28:31], v[218:221], v[174:177], v[28:31]
	v_mfma_f32_16x16x32_bf16 v[20:23], v[226:229], v[174:177], v[20:23]
	v_mfma_f32_16x16x32_bf16 v[12:15], v[218:221], v[182:185], v[12:15]
	v_mfma_f32_16x16x32_bf16 v[8:11], v[226:229], v[182:185], v[8:11]
	v_mfma_f32_16x16x32_bf16 v[4:7], v[218:221], v[206:209], v[4:7]
	v_mfma_f32_16x16x32_bf16 v[0:3], v[226:229], v[206:209], v[0:3]
	s_add_i32 s54, s54, 2
	s_cmp_gt_u32 s54, 29
	s_mov_b64 s[6:7], s[60:61]
	s_barrier
	s_cbranch_scc0 .LBB0_286

.LBB0_325:
	s_add_i32 s83, s83, 1
	s_mul_i32 s6, s83, s18
	s_add_i32 s10, s6, s20
	s_cmpk_lt_i32 s10, 0x3b8
	s_cselect_b64 s[6:7], -1, 0
	s_cmpk_gt_i32 s10, 0x3b7
	s_cselect_b64 s[68:69], -1, 0
	s_and_b64 s[24:25], s[6:7], exec
	s_cselect_b32 s10, s10, 0
	s_ashr_i32 s21, s10, 31
	s_lshr_b32 s21, s21, 29
	s_add_i32 s21, s10, s21
	s_ashr_i32 s24, s21, 3
	s_and_b32 s21, s21, -8
	s_sub_i32 s10, s10, s21
	s_cmp_lt_i32 s10, 0
	s_movk_i32 s21, 0x78
	s_cselect_b32 s21, s21, 0x77
	s_mul_i32 s10, s21, s10
	s_add_i32 s21, s10, s24
	s_mul_hi_i32 s10, s21, 0x92492493
	s_add_i32 s10, s10, s21
	s_lshr_b32 s24, s10, 31
	s_ashr_i32 s10, s10, 4
	s_add_i32 s25, s10, s24
	s_lshl_b32 s37, s25, 2
	s_sub_i32 s10, 0x88, s37
	s_min_i32 s44, s10, 4
	s_abs_i32 s45, s44
	v_cvt_f32_u32_e32 v0, s45
	s_sub_i32 s46, 0, s45
	s_mul_i32 s25, s25, 28
	s_sub_i32 s21, s21, s25
	v_rcp_iflag_f32_e32 v0, v0
	s_mov_b32 s24, s36
	s_abs_i32 s36, s21
	s_xor_b32 s25, s21, s44
	v_mul_f32_e32 v0, 0x4f7ffffe, v0
	v_cvt_u32_f32_e32 v0, v0
	s_mov_b64 s[42:43], s[48:49]
	s_ashr_i32 s25, s25, 31
	s_mov_b32 s10, s66
	v_readfirstlane_b32 s47, v0
	s_mul_i32 s46, s46, s47
	s_mul_hi_u32 s46, s47, s46
	s_add_i32 s47, s47, s46
	s_mul_hi_u32 s46, s36, s47
	s_mul_i32 s47, s46, s45
	s_sub_i32 s36, s36, s47
	s_add_i32 s47, s46, 1
	s_sub_i32 s48, s36, s45
	s_cmp_ge_u32 s36, s45
	s_cselect_b32 s46, s47, s46
	s_cselect_b32 s36, s48, s36
	s_add_i32 s47, s46, 1
	s_cmp_ge_u32 s36, s45
	s_cselect_b32 s36, s47, s46
	s_xor_b32 s36, s36, s25
	s_sub_i32 s66, s36, s25
	s_mul_i32 s25, s66, s44
	s_sub_i32 s21, s21, s25
	s_add_i32 s36, s37, s21
	s_ashr_i32 s37, s36, 31
	s_lshl_b64 s[44:45], s[36:37], 19
	s_mov_b64 s[2:3], s[62:63]
	s_add_u32 s62, s58, s44
	s_addc_u32 s63, s59, s45
	s_and_b64 s[44:45], s[6:7], exec
	s_cselect_b32 s25, s63, s3
	s_cselect_b32 s37, s62, s2
	s_ashr_i32 s67, s66, 31
	s_lshl_b64 s[44:45], s[66:67], 19
	s_add_u32 s48, s19, s44
	s_addc_u32 s49, s34, s45
	s_and_b64 s[6:7], s[6:7], exec
	s_cselect_b32 s44, s49, s43
	s_cselect_b32 s45, s48, s42
	s_add_u32 s46, s42, 0x100
	s_addc_u32 s47, s43, 0
	s_add_u32 s6, s2, 0x40080
	s_addc_u32 s7, s3, 0
	s_mov_b32 s60, -2
	s_add_u32 s2, s6, 0xfffc0080
	s_addc_u32 s3, s7, -1
	s_add_i32 s21, 0, 0x10000
	v_add_u32_e32 v154, s21, v141
	ds_read_b128 v[136:139], v154
	ds_read_b128 v[162:165], v154 offset:2048
	ds_read_b128 v[150:153], v154 offset:1024
	ds_read_b128 v[166:169], v154 offset:3072
	s_cmp_eq_u32 s60, 12
	s_cselect_b32 s3, s25, s3
	s_cselect_b32 s2, s37, s2
	s_cselect_b32 s43, s44, s47
	s_cselect_b32 s42, s45, s46
	v_lshl_add_u64 v[154:155], s[6:7], 0, v[134:135]
	s_add_i32 m0, s53, 0xc000
	ds_read_b128 v[170:173], v149
	ds_read_b128 v[178:181], v149 offset:2048
	ds_read_b128 v[186:189], v149 offset:4096
	ds_read_b128 v[214:217], v149 offset:6144
	ds_read_b128 v[174:177], v149 offset:1024
	ds_read_b128 v[182:185], v149 offset:3072
	ds_read_b128 v[206:209], v149 offset:5120
	ds_read_b128 v[218:221], v149 offset:7168
	global_load_lds_dwordx4 v[154:155], off
	v_lshl_add_u64 v[154:155], s[6:7], 0, v[132:133]
	s_add_i32 m0, s53, 0xe000
	s_nop 0
	global_load_lds_dwordx4 v[154:155], off
	s_waitcnt lgkmcnt(8)
	s_barrier
	s_waitcnt lgkmcnt(7)
	v_mfma_f32_16x16x32_bf16 v[124:127], v[136:139], v[170:173], 0
	v_mfma_f32_16x16x32_bf16 v[120:123], v[162:165], v[170:173], 0
	s_waitcnt lgkmcnt(6)
	v_mfma_f32_16x16x32_bf16 v[108:111], v[136:139], v[178:181], 0
	v_mfma_f32_16x16x32_bf16 v[104:107], v[162:165], v[178:181], 0
	s_waitcnt lgkmcnt(5)
	v_mfma_f32_16x16x32_bf16 v[92:95], v[136:139], v[186:189], 0
	v_mfma_f32_16x16x32_bf16 v[88:91], v[162:165], v[186:189], 0
	s_waitcnt lgkmcnt(4)
	v_mfma_f32_16x16x32_bf16 v[76:79], v[136:139], v[214:217], 0
	v_mfma_f32_16x16x32_bf16 v[72:75], v[162:165], v[214:217], 0
	s_waitcnt lgkmcnt(3)
	v_mfma_f32_16x16x32_bf16 v[124:127], v[150:153], v[174:177], v[124:127]
	v_mfma_f32_16x16x32_bf16 v[120:123], v[166:169], v[174:177], v[120:123]
	s_waitcnt lgkmcnt(2)
	v_mfma_f32_16x16x32_bf16 v[108:111], v[150:153], v[182:185], v[108:111]
	v_mfma_f32_16x16x32_bf16 v[104:107], v[166:169], v[182:185], v[104:107]
	s_waitcnt lgkmcnt(1)
	v_mfma_f32_16x16x32_bf16 v[92:95], v[150:153], v[206:209], v[92:95]
	v_mfma_f32_16x16x32_bf16 v[88:91], v[166:169], v[206:209], v[88:91]
	s_waitcnt lgkmcnt(0)
	v_mfma_f32_16x16x32_bf16 v[76:79], v[150:153], v[218:221], v[76:79]
	v_mfma_f32_16x16x32_bf16 v[72:75], v[166:169], v[218:221], v[72:75]
	s_barrier
	s_add_i32 s61, 0, 0x14000
	v_add_u32_e32 v154, s61, v141
	s_add_i32 s21, s21, s35
	ds_read_b128 v[222:225], v154
	ds_read_b128 v[230:233], v154 offset:2048
	ds_read_b128 v[226:229], v154 offset:1024
	ds_read_b128 v[234:237], v154 offset:3072
	v_lshl_add_u64 v[154:155], s[42:43], 0, v[130:131]
	s_mov_b32 m0, s21
	v_lshl_add_u64 v[238:239], s[42:43], 0, v[128:129]
	global_load_lds_dwordx4 v[154:155], off
	s_add_i32 m0, s21, 0x2000
	s_nop 0
	global_load_lds_dwordx4 v[238:239], off
	s_barrier
	s_waitcnt lgkmcnt(3)
	v_mfma_f32_16x16x32_bf16 v[116:119], v[222:225], v[170:173], 0
	s_waitcnt lgkmcnt(2)
	v_mfma_f32_16x16x32_bf16 v[112:115], v[230:233], v[170:173], 0
	v_mfma_f32_16x16x32_bf16 v[100:103], v[222:225], v[178:181], 0
	v_mfma_f32_16x16x32_bf16 v[96:99], v[230:233], v[178:181], 0
	v_mfma_f32_16x16x32_bf16 v[84:87], v[222:225], v[186:189], 0
	v_mfma_f32_16x16x32_bf16 v[80:83], v[230:233], v[186:189], 0
	v_mfma_f32_16x16x32_bf16 v[68:71], v[222:225], v[214:217], 0
	v_mfma_f32_16x16x32_bf16 v[64:67], v[230:233], v[214:217], 0
	s_waitcnt lgkmcnt(1)
	v_mfma_f32_16x16x32_bf16 v[116:119], v[226:229], v[174:177], v[116:119]
	s_waitcnt lgkmcnt(0)
	v_mfma_f32_16x16x32_bf16 v[112:115], v[234:237], v[174:177], v[112:115]
	v_mfma_f32_16x16x32_bf16 v[100:103], v[226:229], v[182:185], v[100:103]
	v_mfma_f32_16x16x32_bf16 v[96:99], v[234:237], v[182:185], v[96:99]
	v_mfma_f32_16x16x32_bf16 v[84:87], v[226:229], v[206:209], v[84:87]
	v_mfma_f32_16x16x32_bf16 v[80:83], v[234:237], v[206:209], v[80:83]
	v_mfma_f32_16x16x32_bf16 v[68:71], v[226:229], v[218:221], v[68:71]
	v_mfma_f32_16x16x32_bf16 v[64:67], v[234:237], v[218:221], v[64:67]
	s_mov_b32 m0, s53
	v_lshl_add_u64 v[240:241], s[2:3], 0, v[130:131]
	s_barrier
	ds_read_b128 v[170:173], v149 offset:16384
	ds_read_b128 v[178:181], v149 offset:18432
	ds_read_b128 v[186:189], v149 offset:20480
	ds_read_b128 v[214:217], v149 offset:22528
	ds_read_b128 v[174:177], v149 offset:17408
	ds_read_b128 v[182:185], v149 offset:19456
	ds_read_b128 v[206:209], v149 offset:21504
	ds_read_b128 v[218:221], v149 offset:23552
	global_load_lds_dwordx4 v[240:241], off
	v_lshl_add_u64 v[242:243], s[2:3], 0, v[128:129]
	s_mov_b32 m0, s54
	s_nop 0
	global_load_lds_dwordx4 v[242:243], off
	s_barrier
	s_waitcnt lgkmcnt(7)
	v_mfma_f32_16x16x32_bf16 v[60:63], v[136:139], v[170:173], 0
	v_mfma_f32_16x16x32_bf16 v[56:59], v[162:165], v[170:173], 0
	s_waitcnt lgkmcnt(6)
	v_mfma_f32_16x16x32_bf16 v[44:47], v[136:139], v[178:181], 0
	v_mfma_f32_16x16x32_bf16 v[40:43], v[162:165], v[178:181], 0
	s_waitcnt lgkmcnt(5)
	v_mfma_f32_16x16x32_bf16 v[28:31], v[136:139], v[186:189], 0
	v_mfma_f32_16x16x32_bf16 v[24:27], v[162:165], v[186:189], 0
	s_waitcnt lgkmcnt(4)
	v_mfma_f32_16x16x32_bf16 v[12:15], v[136:139], v[214:217], 0
	v_mfma_f32_16x16x32_bf16 v[8:11], v[162:165], v[214:217], 0
	s_waitcnt lgkmcnt(3)
	v_mfma_f32_16x16x32_bf16 v[60:63], v[150:153], v[174:177], v[60:63]
	v_mfma_f32_16x16x32_bf16 v[56:59], v[166:169], v[174:177], v[56:59]
	s_waitcnt lgkmcnt(2)
	v_mfma_f32_16x16x32_bf16 v[44:47], v[150:153], v[182:185], v[44:47]
	v_mfma_f32_16x16x32_bf16 v[40:43], v[166:169], v[182:185], v[40:43]
	s_waitcnt lgkmcnt(1)
	v_mfma_f32_16x16x32_bf16 v[28:31], v[150:153], v[206:209], v[28:31]
	v_mfma_f32_16x16x32_bf16 v[24:27], v[166:169], v[206:209], v[24:27]
	s_waitcnt lgkmcnt(0)
	v_mfma_f32_16x16x32_bf16 v[12:15], v[150:153], v[218:221], v[12:15]
	v_mfma_f32_16x16x32_bf16 v[8:11], v[166:169], v[218:221], v[8:11]
	s_barrier
	s_add_u32 s80, s42, 0x40000
	s_addc_u32 s81, s43, 0
	s_add_i32 s21, s61, s35
	v_lshl_add_u64 v[136:137], s[80:81], 0, v[130:131]
	s_mov_b32 m0, s21
	s_nop 0
	global_load_lds_dwordx4 v[136:137], off
	v_lshl_add_u64 v[136:137], s[80:81], 0, v[128:129]
	s_add_i32 m0, s21, 0x2000
	s_nop 0
	global_load_lds_dwordx4 v[136:137], off
	s_waitcnt vmcnt(6)
	s_barrier
	v_mfma_f32_16x16x32_bf16 v[52:55], v[222:225], v[170:173], 0
	v_mfma_f32_16x16x32_bf16 v[48:51], v[230:233], v[170:173], 0
	v_mfma_f32_16x16x32_bf16 v[36:39], v[222:225], v[178:181], 0
	v_mfma_f32_16x16x32_bf16 v[32:35], v[230:233], v[178:181], 0
	v_mfma_f32_16x16x32_bf16 v[20:23], v[222:225], v[186:189], 0
	v_mfma_f32_16x16x32_bf16 v[16:19], v[230:233], v[186:189], 0
	v_mfma_f32_16x16x32_bf16 v[4:7], v[222:225], v[214:217], 0
	v_mfma_f32_16x16x32_bf16 v[0:3], v[230:233], v[214:217], 0
	v_mfma_f32_16x16x32_bf16 v[52:55], v[226:229], v[174:177], v[52:55]
	v_mfma_f32_16x16x32_bf16 v[48:51], v[234:237], v[174:177], v[48:51]
	v_mfma_f32_16x16x32_bf16 v[36:39], v[226:229], v[182:185], v[36:39]
	v_mfma_f32_16x16x32_bf16 v[32:35], v[234:237], v[182:185], v[32:35]
	v_mfma_f32_16x16x32_bf16 v[20:23], v[226:229], v[206:209], v[20:23]
	v_mfma_f32_16x16x32_bf16 v[16:19], v[234:237], v[206:209], v[16:19]
	v_mfma_f32_16x16x32_bf16 v[4:7], v[226:229], v[218:221], v[4:7]
	v_mfma_f32_16x16x32_bf16 v[0:3], v[234:237], v[218:221], v[0:3]
	s_add_i32 s21, 0, 0x18000
	v_add_u32_e32 v156, s21, v141
	s_barrier
	ds_read_b128 v[136:139], v156
	ds_read_b128 v[162:165], v156 offset:2048
	ds_read_b128 v[150:153], v156 offset:1024
	ds_read_b128 v[166:169], v156 offset:3072
	s_add_u32 s2, s2, 0x40000
	s_addc_u32 s3, s3, 0
	s_mov_b32 m0, s55
	v_lshl_add_u64 v[222:223], s[2:3], 0, v[130:131]
	ds_read_b128 v[170:173], v149 offset:32768
	ds_read_b128 v[178:181], v149 offset:34816
	ds_read_b128 v[186:189], v149 offset:36864
	ds_read_b128 v[214:217], v149 offset:38912
	ds_read_b128 v[174:177], v149 offset:33792
	ds_read_b128 v[182:185], v149 offset:35840
	ds_read_b128 v[206:209], v149 offset:37888
	ds_read_b128 v[218:221], v149 offset:39936
	global_load_lds_dwordx4 v[222:223], off
	v_lshl_add_u64 v[222:223], s[2:3], 0, v[128:129]
	s_mov_b32 m0, s78
	s_nop 0
	global_load_lds_dwordx4 v[222:223], off
	s_waitcnt lgkmcnt(8)
	s_barrier
	s_waitcnt lgkmcnt(7)
	v_mfma_f32_16x16x32_bf16 v[124:127], v[136:139], v[170:173], v[124:127]
	v_mfma_f32_16x16x32_bf16 v[120:123], v[162:165], v[170:173], v[120:123]
	s_waitcnt lgkmcnt(6)
	v_mfma_f32_16x16x32_bf16 v[108:111], v[136:139], v[178:181], v[108:111]
	v_mfma_f32_16x16x32_bf16 v[104:107], v[162:165], v[178:181], v[104:107]
	s_waitcnt lgkmcnt(5)
	v_mfma_f32_16x16x32_bf16 v[92:95], v[136:139], v[186:189], v[92:95]
	v_mfma_f32_16x16x32_bf16 v[88:91], v[162:165], v[186:189], v[88:91]
	s_waitcnt lgkmcnt(4)
	v_mfma_f32_16x16x32_bf16 v[76:79], v[136:139], v[214:217], v[76:79]
	v_mfma_f32_16x16x32_bf16 v[72:75], v[162:165], v[214:217], v[72:75]
	s_waitcnt lgkmcnt(3)
	v_mfma_f32_16x16x32_bf16 v[124:127], v[150:153], v[174:177], v[124:127]
	v_mfma_f32_16x16x32_bf16 v[120:123], v[166:169], v[174:177], v[120:123]
	s_waitcnt lgkmcnt(2)
	v_mfma_f32_16x16x32_bf16 v[108:111], v[150:153], v[182:185], v[108:111]
	v_mfma_f32_16x16x32_bf16 v[104:107], v[166:169], v[182:185], v[104:107]
	s_waitcnt lgkmcnt(1)
	v_mfma_f32_16x16x32_bf16 v[92:95], v[150:153], v[206:209], v[92:95]
	v_mfma_f32_16x16x32_bf16 v[88:91], v[166:169], v[206:209], v[88:91]
	s_waitcnt lgkmcnt(0)
	v_mfma_f32_16x16x32_bf16 v[76:79], v[150:153], v[218:221], v[76:79]
	v_mfma_f32_16x16x32_bf16 v[72:75], v[166:169], v[218:221], v[72:75]
	s_barrier
	s_add_i32 s61, 0, 0x1c000
	s_add_i32 s2, s21, s35
	v_add_u32_e32 v156, s61, v141
	v_lshl_add_u64 v[154:155], v[154:155], 0, s[50:51]
	s_mov_b32 m0, s2
	ds_read_b128 v[222:225], v156
	ds_read_b128 v[230:233], v156 offset:2048
	ds_read_b128 v[226:229], v156 offset:1024
	ds_read_b128 v[234:237], v156 offset:3072
	global_load_lds_dwordx4 v[154:155], off
	v_lshl_add_u64 v[154:155], v[238:239], 0, s[50:51]
	s_add_i32 m0, s2, 0x2000
	s_nop 0
	global_load_lds_dwordx4 v[154:155], off
	s_barrier
	s_waitcnt lgkmcnt(3)
	v_mfma_f32_16x16x32_bf16 v[116:119], v[222:225], v[170:173], v[116:119]
	s_waitcnt lgkmcnt(2)
	v_mfma_f32_16x16x32_bf16 v[112:115], v[230:233], v[170:173], v[112:115]
	v_mfma_f32_16x16x32_bf16 v[100:103], v[222:225], v[178:181], v[100:103]
	v_mfma_f32_16x16x32_bf16 v[96:99], v[230:233], v[178:181], v[96:99]
	v_mfma_f32_16x16x32_bf16 v[84:87], v[222:225], v[186:189], v[84:87]
	v_mfma_f32_16x16x32_bf16 v[80:83], v[230:233], v[186:189], v[80:83]
	v_mfma_f32_16x16x32_bf16 v[68:71], v[222:225], v[214:217], v[68:71]
	v_mfma_f32_16x16x32_bf16 v[64:67], v[230:233], v[214:217], v[64:67]
	s_waitcnt lgkmcnt(1)
	v_mfma_f32_16x16x32_bf16 v[116:119], v[226:229], v[174:177], v[116:119]
	s_waitcnt lgkmcnt(0)
	v_mfma_f32_16x16x32_bf16 v[112:115], v[234:237], v[174:177], v[112:115]
	v_mfma_f32_16x16x32_bf16 v[100:103], v[226:229], v[182:185], v[100:103]
	v_mfma_f32_16x16x32_bf16 v[96:99], v[234:237], v[182:185], v[96:99]
	v_mfma_f32_16x16x32_bf16 v[84:87], v[226:229], v[206:209], v[84:87]
	v_mfma_f32_16x16x32_bf16 v[80:83], v[234:237], v[206:209], v[80:83]
	v_mfma_f32_16x16x32_bf16 v[68:71], v[226:229], v[218:221], v[68:71]
	v_mfma_f32_16x16x32_bf16 v[64:67], v[234:237], v[218:221], v[64:67]
	s_mov_b32 m0, s79
	v_lshl_add_u64 v[154:155], v[240:241], 0, s[50:51]
	s_barrier
	ds_read_b128 v[170:173], v149 offset:49152
	ds_read_b128 v[178:181], v149 offset:51200
	ds_read_b128 v[186:189], v149 offset:53248
	ds_read_b128 v[214:217], v149 offset:55296
	ds_read_b128 v[174:177], v149 offset:50176
	ds_read_b128 v[182:185], v149 offset:52224
	ds_read_b128 v[206:209], v149 offset:54272
	ds_read_b128 v[218:221], v149 offset:56320
	global_load_lds_dwordx4 v[154:155], off
	v_lshl_add_u64 v[154:155], v[242:243], 0, s[50:51]
	s_mov_b32 m0, s82
	s_nop 0
	global_load_lds_dwordx4 v[154:155], off
	s_barrier
	s_waitcnt lgkmcnt(7)
	v_mfma_f32_16x16x32_bf16 v[60:63], v[136:139], v[170:173], v[60:63]
	v_mfma_f32_16x16x32_bf16 v[56:59], v[162:165], v[170:173], v[56:59]
	s_waitcnt lgkmcnt(6)
	v_mfma_f32_16x16x32_bf16 v[44:47], v[136:139], v[178:181], v[44:47]
	v_mfma_f32_16x16x32_bf16 v[40:43], v[162:165], v[178:181], v[40:43]
	s_waitcnt lgkmcnt(5)
	v_mfma_f32_16x16x32_bf16 v[28:31], v[136:139], v[186:189], v[28:31]
	v_mfma_f32_16x16x32_bf16 v[24:27], v[162:165], v[186:189], v[24:27]
	s_waitcnt lgkmcnt(4)
	v_mfma_f32_16x16x32_bf16 v[12:15], v[136:139], v[214:217], v[12:15]
	v_mfma_f32_16x16x32_bf16 v[8:11], v[162:165], v[214:217], v[8:11]
	s_waitcnt lgkmcnt(3)
	v_mfma_f32_16x16x32_bf16 v[60:63], v[150:153], v[174:177], v[60:63]
	v_mfma_f32_16x16x32_bf16 v[56:59], v[166:169], v[174:177], v[56:59]
	s_waitcnt lgkmcnt(2)
	v_mfma_f32_16x16x32_bf16 v[44:47], v[150:153], v[182:185], v[44:47]
	v_mfma_f32_16x16x32_bf16 v[40:43], v[166:169], v[182:185], v[40:43]
	s_waitcnt lgkmcnt(1)
	v_mfma_f32_16x16x32_bf16 v[28:31], v[150:153], v[206:209], v[28:31]
	v_mfma_f32_16x16x32_bf16 v[24:27], v[166:169], v[206:209], v[24:27]
	s_waitcnt lgkmcnt(0)
	v_mfma_f32_16x16x32_bf16 v[12:15], v[150:153], v[218:221], v[12:15]
	v_mfma_f32_16x16x32_bf16 v[8:11], v[166:169], v[218:221], v[8:11]
	s_barrier
	s_add_u32 s2, s42, 0x40080
	s_addc_u32 s3, s43, 0
	s_add_i32 s21, s61, s35
	v_lshl_add_u64 v[136:137], s[2:3], 0, v[130:131]
	s_mov_b32 m0, s21
	s_nop 0
	global_load_lds_dwordx4 v[136:137], off
	v_lshl_add_u64 v[136:137], s[2:3], 0, v[128:129]
	s_add_i32 m0, s21, 0x2000
	s_nop 0
	global_load_lds_dwordx4 v[136:137], off
	s_waitcnt vmcnt(6)
	s_barrier
	v_mfma_f32_16x16x32_bf16 v[52:55], v[222:225], v[170:173], v[52:55]
	v_mfma_f32_16x16x32_bf16 v[48:51], v[230:233], v[170:173], v[48:51]
	v_mfma_f32_16x16x32_bf16 v[36:39], v[222:225], v[178:181], v[36:39]
	v_mfma_f32_16x16x32_bf16 v[32:35], v[230:233], v[178:181], v[32:35]
	v_mfma_f32_16x16x32_bf16 v[20:23], v[222:225], v[186:189], v[20:23]
	v_mfma_f32_16x16x32_bf16 v[16:19], v[230:233], v[186:189], v[16:19]
	v_mfma_f32_16x16x32_bf16 v[4:7], v[222:225], v[214:217], v[4:7]
	v_mfma_f32_16x16x32_bf16 v[0:3], v[230:233], v[214:217], v[0:3]
	v_mfma_f32_16x16x32_bf16 v[52:55], v[226:229], v[174:177], v[52:55]
	v_mfma_f32_16x16x32_bf16 v[48:51], v[234:237], v[174:177], v[48:51]
	v_mfma_f32_16x16x32_bf16 v[36:39], v[226:229], v[182:185], v[36:39]
	v_mfma_f32_16x16x32_bf16 v[32:35], v[234:237], v[182:185], v[32:35]
	v_mfma_f32_16x16x32_bf16 v[20:23], v[226:229], v[206:209], v[20:23]
	v_mfma_f32_16x16x32_bf16 v[16:19], v[234:237], v[206:209], v[16:19]
	v_mfma_f32_16x16x32_bf16 v[4:7], v[226:229], v[218:221], v[4:7]
	v_mfma_f32_16x16x32_bf16 v[0:3], v[234:237], v[218:221], v[0:3]
	s_add_i32 s60, s60, 2
	s_add_u32 s46, s46, 0x100
	s_addc_u32 s47, s47, 0
	s_add_u32 s6, s6, 0x100
	s_addc_u32 s7, s7, 0
	s_cmp_gt_u32 s60, 13
	s_barrier
	s_cbranch_scc1 .Lpost_326
.LBB0_326:
	s_add_u32 s2, s6, 0xfffc0080
	s_addc_u32 s3, s7, -1
	s_add_i32 s21, 0, 0x10000
	v_add_u32_e32 v154, s21, v141
	ds_read_b128 v[136:139], v154
	ds_read_b128 v[162:165], v154 offset:2048
	ds_read_b128 v[150:153], v154 offset:1024
	ds_read_b128 v[166:169], v154 offset:3072
	s_cmp_eq_u32 s60, 12
	s_cselect_b32 s3, s25, s3
	s_cselect_b32 s2, s37, s2
	s_cselect_b32 s43, s44, s47
	s_cselect_b32 s42, s45, s46
	v_lshl_add_u64 v[154:155], s[6:7], 0, v[134:135]
	s_add_i32 m0, s53, 0xc000
	ds_read_b128 v[170:173], v149
	ds_read_b128 v[178:181], v149 offset:2048
	ds_read_b128 v[186:189], v149 offset:4096
	ds_read_b128 v[214:217], v149 offset:6144
	ds_read_b128 v[174:177], v149 offset:1024
	ds_read_b128 v[182:185], v149 offset:3072
	ds_read_b128 v[206:209], v149 offset:5120
	ds_read_b128 v[218:221], v149 offset:7168
	global_load_lds_dwordx4 v[154:155], off
	v_lshl_add_u64 v[154:155], s[6:7], 0, v[132:133]
	s_add_i32 m0, s53, 0xe000
	s_nop 0
	global_load_lds_dwordx4 v[154:155], off
	s_waitcnt lgkmcnt(8)
	s_barrier
	s_waitcnt lgkmcnt(7)
	v_mfma_f32_16x16x32_bf16 v[124:127], v[136:139], v[170:173], v[124:127]
	v_mfma_f32_16x16x32_bf16 v[120:123], v[162:165], v[170:173], v[120:123]
	s_waitcnt lgkmcnt(6)
	v_mfma_f32_16x16x32_bf16 v[108:111], v[136:139], v[178:181], v[108:111]
	v_mfma_f32_16x16x32_bf16 v[104:107], v[162:165], v[178:181], v[104:107]
	s_waitcnt lgkmcnt(5)
	v_mfma_f32_16x16x32_bf16 v[92:95], v[136:139], v[186:189], v[92:95]
	v_mfma_f32_16x16x32_bf16 v[88:91], v[162:165], v[186:189], v[88:91]
	s_waitcnt lgkmcnt(4)
	v_mfma_f32_16x16x32_bf16 v[76:79], v[136:139], v[214:217], v[76:79]
	v_mfma_f32_16x16x32_bf16 v[72:75], v[162:165], v[214:217], v[72:75]
	s_waitcnt lgkmcnt(3)
	v_mfma_f32_16x16x32_bf16 v[124:127], v[150:153], v[174:177], v[124:127]
	v_mfma_f32_16x16x32_bf16 v[120:123], v[166:169], v[174:177], v[120:123]
	s_waitcnt lgkmcnt(2)
	v_mfma_f32_16x16x32_bf16 v[108:111], v[150:153], v[182:185], v[108:111]
	v_mfma_f32_16x16x32_bf16 v[104:107], v[166:169], v[182:185], v[104:107]
	s_waitcnt lgkmcnt(1)
	v_mfma_f32_16x16x32_bf16 v[92:95], v[150:153], v[206:209], v[92:95]
	v_mfma_f32_16x16x32_bf16 v[88:91], v[166:169], v[206:209], v[88:91]
	s_waitcnt lgkmcnt(0)
	v_mfma_f32_16x16x32_bf16 v[76:79], v[150:153], v[218:221], v[76:79]
	v_mfma_f32_16x16x32_bf16 v[72:75], v[166:169], v[218:221], v[72:75]
	s_barrier
	s_add_i32 s61, 0, 0x14000
	v_add_u32_e32 v154, s61, v141
	s_add_i32 s21, s21, s35
	ds_read_b128 v[222:225], v154
	ds_read_b128 v[230:233], v154 offset:2048
	ds_read_b128 v[226:229], v154 offset:1024
	ds_read_b128 v[234:237], v154 offset:3072
	v_lshl_add_u64 v[154:155], s[42:43], 0, v[130:131]
	s_mov_b32 m0, s21
	v_lshl_add_u64 v[238:239], s[42:43], 0, v[128:129]
	global_load_lds_dwordx4 v[154:155], off
	s_add_i32 m0, s21, 0x2000
	s_nop 0
	global_load_lds_dwordx4 v[238:239], off
	s_barrier
	s_waitcnt lgkmcnt(3)
	v_mfma_f32_16x16x32_bf16 v[116:119], v[222:225], v[170:173], v[116:119]
	s_waitcnt lgkmcnt(2)
	v_mfma_f32_16x16x32_bf16 v[112:115], v[230:233], v[170:173], v[112:115]
	v_mfma_f32_16x16x32_bf16 v[100:103], v[222:225], v[178:181], v[100:103]
	v_mfma_f32_16x16x32_bf16 v[96:99], v[230:233], v[178:181], v[96:99]
	v_mfma_f32_16x16x32_bf16 v[84:87], v[222:225], v[186:189], v[84:87]
	v_mfma_f32_16x16x32_bf16 v[80:83], v[230:233], v[186:189], v[80:83]
	v_mfma_f32_16x16x32_bf16 v[68:71], v[222:225], v[214:217], v[68:71]
	v_mfma_f32_16x16x32_bf16 v[64:67], v[230:233], v[214:217], v[64:67]
	s_waitcnt lgkmcnt(1)
	v_mfma_f32_16x16x32_bf16 v[116:119], v[226:229], v[174:177], v[116:119]
	s_waitcnt lgkmcnt(0)
	v_mfma_f32_16x16x32_bf16 v[112:115], v[234:237], v[174:177], v[112:115]
	v_mfma_f32_16x16x32_bf16 v[100:103], v[226:229], v[182:185], v[100:103]
	v_mfma_f32_16x16x32_bf16 v[96:99], v[234:237], v[182:185], v[96:99]
	v_mfma_f32_16x16x32_bf16 v[84:87], v[226:229], v[206:209], v[84:87]
	v_mfma_f32_16x16x32_bf16 v[80:83], v[234:237], v[206:209], v[80:83]
	v_mfma_f32_16x16x32_bf16 v[68:71], v[226:229], v[218:221], v[68:71]
	v_mfma_f32_16x16x32_bf16 v[64:67], v[234:237], v[218:221], v[64:67]
	s_mov_b32 m0, s53
	v_lshl_add_u64 v[240:241], s[2:3], 0, v[130:131]
	s_barrier
	ds_read_b128 v[170:173], v149 offset:16384
	ds_read_b128 v[178:181], v149 offset:18432
	ds_read_b128 v[186:189], v149 offset:20480
	ds_read_b128 v[214:217], v149 offset:22528
	ds_read_b128 v[174:177], v149 offset:17408
	ds_read_b128 v[182:185], v149 offset:19456
	ds_read_b128 v[206:209], v149 offset:21504
	ds_read_b128 v[218:221], v149 offset:23552
	global_load_lds_dwordx4 v[240:241], off
	v_lshl_add_u64 v[242:243], s[2:3], 0, v[128:129]
	s_mov_b32 m0, s54
	s_nop 0
	global_load_lds_dwordx4 v[242:243], off
	s_barrier
	s_waitcnt lgkmcnt(7)
	v_mfma_f32_16x16x32_bf16 v[60:63], v[136:139], v[170:173], v[60:63]
	v_mfma_f32_16x16x32_bf16 v[56:59], v[162:165], v[170:173], v[56:59]
	s_waitcnt lgkmcnt(6)
	v_mfma_f32_16x16x32_bf16 v[44:47], v[136:139], v[178:181], v[44:47]
	v_mfma_f32_16x16x32_bf16 v[40:43], v[162:165], v[178:181], v[40:43]
	s_waitcnt lgkmcnt(5)
	v_mfma_f32_16x16x32_bf16 v[28:31], v[136:139], v[186:189], v[28:31]
	v_mfma_f32_16x16x32_bf16 v[24:27], v[162:165], v[186:189], v[24:27]
	s_waitcnt lgkmcnt(4)
	v_mfma_f32_16x16x32_bf16 v[12:15], v[136:139], v[214:217], v[12:15]
	v_mfma_f32_16x16x32_bf16 v[8:11], v[162:165], v[214:217], v[8:11]
	s_waitcnt lgkmcnt(3)
	v_mfma_f32_16x16x32_bf16 v[60:63], v[150:153], v[174:177], v[60:63]
	v_mfma_f32_16x16x32_bf16 v[56:59], v[166:169], v[174:177], v[56:59]
	s_waitcnt lgkmcnt(2)
	v_mfma_f32_16x16x32_bf16 v[44:47], v[150:153], v[182:185], v[44:47]
	v_mfma_f32_16x16x32_bf16 v[40:43], v[166:169], v[182:185], v[40:43]
	s_waitcnt lgkmcnt(1)
	v_mfma_f32_16x16x32_bf16 v[28:31], v[150:153], v[206:209], v[28:31]
	v_mfma_f32_16x16x32_bf16 v[24:27], v[166:169], v[206:209], v[24:27]
	s_waitcnt lgkmcnt(0)
	v_mfma_f32_16x16x32_bf16 v[12:15], v[150:153], v[218:221], v[12:15]
	v_mfma_f32_16x16x32_bf16 v[8:11], v[166:169], v[218:221], v[8:11]
	s_barrier
	s_add_u32 s80, s42, 0x40000
	s_addc_u32 s81, s43, 0
	s_add_i32 s21, s61, s35
	v_lshl_add_u64 v[136:137], s[80:81], 0, v[130:131]
	s_mov_b32 m0, s21
	s_nop 0
	global_load_lds_dwordx4 v[136:137], off
	v_lshl_add_u64 v[136:137], s[80:81], 0, v[128:129]
	s_add_i32 m0, s21, 0x2000
	s_nop 0
	global_load_lds_dwordx4 v[136:137], off
	s_waitcnt vmcnt(6)
	s_barrier
	v_mfma_f32_16x16x32_bf16 v[52:55], v[222:225], v[170:173], v[52:55]
	v_mfma_f32_16x16x32_bf16 v[48:51], v[230:233], v[170:173], v[48:51]
	v_mfma_f32_16x16x32_bf16 v[36:39], v[222:225], v[178:181], v[36:39]
	v_mfma_f32_16x16x32_bf16 v[32:35], v[230:233], v[178:181], v[32:35]
	v_mfma_f32_16x16x32_bf16 v[20:23], v[222:225], v[186:189], v[20:23]
	v_mfma_f32_16x16x32_bf16 v[16:19], v[230:233], v[186:189], v[16:19]
	v_mfma_f32_16x16x32_bf16 v[4:7], v[222:225], v[214:217], v[4:7]
	v_mfma_f32_16x16x32_bf16 v[0:3], v[230:233], v[214:217], v[0:3]
	v_mfma_f32_16x16x32_bf16 v[52:55], v[226:229], v[174:177], v[52:55]
	v_mfma_f32_16x16x32_bf16 v[48:51], v[234:237], v[174:177], v[48:51]
	v_mfma_f32_16x16x32_bf16 v[36:39], v[226:229], v[182:185], v[36:39]
	v_mfma_f32_16x16x32_bf16 v[32:35], v[234:237], v[182:185], v[32:35]
	v_mfma_f32_16x16x32_bf16 v[20:23], v[226:229], v[206:209], v[20:23]
	v_mfma_f32_16x16x32_bf16 v[16:19], v[234:237], v[206:209], v[16:19]
	v_mfma_f32_16x16x32_bf16 v[4:7], v[226:229], v[218:221], v[4:7]
	v_mfma_f32_16x16x32_bf16 v[0:3], v[234:237], v[218:221], v[0:3]
	s_add_i32 s21, 0, 0x18000
	v_add_u32_e32 v156, s21, v141
	s_barrier
	ds_read_b128 v[136:139], v156
	ds_read_b128 v[162:165], v156 offset:2048
	ds_read_b128 v[150:153], v156 offset:1024
	ds_read_b128 v[166:169], v156 offset:3072
	s_add_u32 s2, s2, 0x40000
	s_addc_u32 s3, s3, 0
	s_mov_b32 m0, s55
	v_lshl_add_u64 v[222:223], s[2:3], 0, v[130:131]
	ds_read_b128 v[170:173], v149 offset:32768
	ds_read_b128 v[178:181], v149 offset:34816
	ds_read_b128 v[186:189], v149 offset:36864
	ds_read_b128 v[214:217], v149 offset:38912
	ds_read_b128 v[174:177], v149 offset:33792
	ds_read_b128 v[182:185], v149 offset:35840
	ds_read_b128 v[206:209], v149 offset:37888
	ds_read_b128 v[218:221], v149 offset:39936
	global_load_lds_dwordx4 v[222:223], off
	v_lshl_add_u64 v[222:223], s[2:3], 0, v[128:129]
	s_mov_b32 m0, s78
	s_nop 0
	global_load_lds_dwordx4 v[222:223], off
	s_waitcnt lgkmcnt(8)
	s_barrier
	s_waitcnt lgkmcnt(7)
	v_mfma_f32_16x16x32_bf16 v[124:127], v[136:139], v[170:173], v[124:127]
	v_mfma_f32_16x16x32_bf16 v[120:123], v[162:165], v[170:173], v[120:123]
	s_waitcnt lgkmcnt(6)
	v_mfma_f32_16x16x32_bf16 v[108:111], v[136:139], v[178:181], v[108:111]
	v_mfma_f32_16x16x32_bf16 v[104:107], v[162:165], v[178:181], v[104:107]
	s_waitcnt lgkmcnt(5)
	v_mfma_f32_16x16x32_bf16 v[92:95], v[136:139], v[186:189], v[92:95]
	v_mfma_f32_16x16x32_bf16 v[88:91], v[162:165], v[186:189], v[88:91]
	s_waitcnt lgkmcnt(4)
	v_mfma_f32_16x16x32_bf16 v[76:79], v[136:139], v[214:217], v[76:79]
	v_mfma_f32_16x16x32_bf16 v[72:75], v[162:165], v[214:217], v[72:75]
	s_waitcnt lgkmcnt(3)
	v_mfma_f32_16x16x32_bf16 v[124:127], v[150:153], v[174:177], v[124:127]
	v_mfma_f32_16x16x32_bf16 v[120:123], v[166:169], v[174:177], v[120:123]
	s_waitcnt lgkmcnt(2)
	v_mfma_f32_16x16x32_bf16 v[108:111], v[150:153], v[182:185], v[108:111]
	v_mfma_f32_16x16x32_bf16 v[104:107], v[166:169], v[182:185], v[104:107]
	s_waitcnt lgkmcnt(1)
	v_mfma_f32_16x16x32_bf16 v[92:95], v[150:153], v[206:209], v[92:95]
	v_mfma_f32_16x16x32_bf16 v[88:91], v[166:169], v[206:209], v[88:91]
	s_waitcnt lgkmcnt(0)
	v_mfma_f32_16x16x32_bf16 v[76:79], v[150:153], v[218:221], v[76:79]
	v_mfma_f32_16x16x32_bf16 v[72:75], v[166:169], v[218:221], v[72:75]
	s_barrier
	s_add_i32 s61, 0, 0x1c000
	s_add_i32 s2, s21, s35
	v_add_u32_e32 v156, s61, v141
	v_lshl_add_u64 v[154:155], v[154:155], 0, s[50:51]
	s_mov_b32 m0, s2
	ds_read_b128 v[222:225], v156
	ds_read_b128 v[230:233], v156 offset:2048
	ds_read_b128 v[226:229], v156 offset:1024
	ds_read_b128 v[234:237], v156 offset:3072
	global_load_lds_dwordx4 v[154:155], off
	v_lshl_add_u64 v[154:155], v[238:239], 0, s[50:51]
	s_add_i32 m0, s2, 0x2000
	s_nop 0
	global_load_lds_dwordx4 v[154:155], off
	s_barrier
	s_waitcnt lgkmcnt(3)
	v_mfma_f32_16x16x32_bf16 v[116:119], v[222:225], v[170:173], v[116:119]
	s_waitcnt lgkmcnt(2)
	v_mfma_f32_16x16x32_bf16 v[112:115], v[230:233], v[170:173], v[112:115]
	v_mfma_f32_16x16x32_bf16 v[100:103], v[222:225], v[178:181], v[100:103]
	v_mfma_f32_16x16x32_bf16 v[96:99], v[230:233], v[178:181], v[96:99]
	v_mfma_f32_16x16x32_bf16 v[84:87], v[222:225], v[186:189], v[84:87]
	v_mfma_f32_16x16x32_bf16 v[80:83], v[230:233], v[186:189], v[80:83]
	v_mfma_f32_16x16x32_bf16 v[68:71], v[222:225], v[214:217], v[68:71]
	v_mfma_f32_16x16x32_bf16 v[64:67], v[230:233], v[214:217], v[64:67]
	s_waitcnt lgkmcnt(1)
	v_mfma_f32_16x16x32_bf16 v[116:119], v[226:229], v[174:177], v[116:119]
	s_waitcnt lgkmcnt(0)
	v_mfma_f32_16x16x32_bf16 v[112:115], v[234:237], v[174:177], v[112:115]
	v_mfma_f32_16x16x32_bf16 v[100:103], v[226:229], v[182:185], v[100:103]
	v_mfma_f32_16x16x32_bf16 v[96:99], v[234:237], v[182:185], v[96:99]
	v_mfma_f32_16x16x32_bf16 v[84:87], v[226:229], v[206:209], v[84:87]
	v_mfma_f32_16x16x32_bf16 v[80:83], v[234:237], v[206:209], v[80:83]
	v_mfma_f32_16x16x32_bf16 v[68:71], v[226:229], v[218:221], v[68:71]
	v_mfma_f32_16x16x32_bf16 v[64:67], v[234:237], v[218:221], v[64:67]
	s_mov_b32 m0, s79
	v_lshl_add_u64 v[154:155], v[240:241], 0, s[50:51]
	s_barrier
	ds_read_b128 v[170:173], v149 offset:49152
	ds_read_b128 v[178:181], v149 offset:51200
	ds_read_b128 v[186:189], v149 offset:53248
	ds_read_b128 v[214:217], v149 offset:55296
	ds_read_b128 v[174:177], v149 offset:50176
	ds_read_b128 v[182:185], v149 offset:52224
	ds_read_b128 v[206:209], v149 offset:54272
	ds_read_b128 v[218:221], v149 offset:56320
	global_load_lds_dwordx4 v[154:155], off
	v_lshl_add_u64 v[154:155], v[242:243], 0, s[50:51]
	s_mov_b32 m0, s82
	s_nop 0
	global_load_lds_dwordx4 v[154:155], off
	s_barrier
	s_waitcnt lgkmcnt(7)
	v_mfma_f32_16x16x32_bf16 v[60:63], v[136:139], v[170:173], v[60:63]
	v_mfma_f32_16x16x32_bf16 v[56:59], v[162:165], v[170:173], v[56:59]
	s_waitcnt lgkmcnt(6)
	v_mfma_f32_16x16x32_bf16 v[44:47], v[136:139], v[178:181], v[44:47]
	v_mfma_f32_16x16x32_bf16 v[40:43], v[162:165], v[178:181], v[40:43]
	s_waitcnt lgkmcnt(5)
	v_mfma_f32_16x16x32_bf16 v[28:31], v[136:139], v[186:189], v[28:31]
	v_mfma_f32_16x16x32_bf16 v[24:27], v[162:165], v[186:189], v[24:27]
	s_waitcnt lgkmcnt(4)
	v_mfma_f32_16x16x32_bf16 v[12:15], v[136:139], v[214:217], v[12:15]
	v_mfma_f32_16x16x32_bf16 v[8:11], v[162:165], v[214:217], v[8:11]
	s_waitcnt lgkmcnt(3)
	v_mfma_f32_16x16x32_bf16 v[60:63], v[150:153], v[174:177], v[60:63]
	v_mfma_f32_16x16x32_bf16 v[56:59], v[166:169], v[174:177], v[56:59]
	s_waitcnt lgkmcnt(2)
	v_mfma_f32_16x16x32_bf16 v[44:47], v[150:153], v[182:185], v[44:47]
	v_mfma_f32_16x16x32_bf16 v[40:43], v[166:169], v[182:185], v[40:43]
	s_waitcnt lgkmcnt(1)
	v_mfma_f32_16x16x32_bf16 v[28:31], v[150:153], v[206:209], v[28:31]
	v_mfma_f32_16x16x32_bf16 v[24:27], v[166:169], v[206:209], v[24:27]
	s_waitcnt lgkmcnt(0)
	v_mfma_f32_16x16x32_bf16 v[12:15], v[150:153], v[218:221], v[12:15]
	v_mfma_f32_16x16x32_bf16 v[8:11], v[166:169], v[218:221], v[8:11]
	s_barrier
	s_add_u32 s2, s42, 0x40080
	s_addc_u32 s3, s43, 0
	s_add_i32 s21, s61, s35
	v_lshl_add_u64 v[136:137], s[2:3], 0, v[130:131]
	s_mov_b32 m0, s21
	s_nop 0
	global_load_lds_dwordx4 v[136:137], off
	v_lshl_add_u64 v[136:137], s[2:3], 0, v[128:129]
	s_add_i32 m0, s21, 0x2000
	s_nop 0
	global_load_lds_dwordx4 v[136:137], off
	s_waitcnt vmcnt(6)
	s_barrier
	v_mfma_f32_16x16x32_bf16 v[52:55], v[222:225], v[170:173], v[52:55]
	v_mfma_f32_16x16x32_bf16 v[48:51], v[230:233], v[170:173], v[48:51]
	v_mfma_f32_16x16x32_bf16 v[36:39], v[222:225], v[178:181], v[36:39]
	v_mfma_f32_16x16x32_bf16 v[32:35], v[230:233], v[178:181], v[32:35]
	v_mfma_f32_16x16x32_bf16 v[20:23], v[222:225], v[186:189], v[20:23]
	v_mfma_f32_16x16x32_bf16 v[16:19], v[230:233], v[186:189], v[16:19]
	v_mfma_f32_16x16x32_bf16 v[4:7], v[222:225], v[214:217], v[4:7]
	v_mfma_f32_16x16x32_bf16 v[0:3], v[230:233], v[214:217], v[0:3]
	v_mfma_f32_16x16x32_bf16 v[52:55], v[226:229], v[174:177], v[52:55]
	v_mfma_f32_16x16x32_bf16 v[48:51], v[234:237], v[174:177], v[48:51]
	v_mfma_f32_16x16x32_bf16 v[36:39], v[226:229], v[182:185], v[36:39]
	v_mfma_f32_16x16x32_bf16 v[32:35], v[234:237], v[182:185], v[32:35]
	v_mfma_f32_16x16x32_bf16 v[20:23], v[226:229], v[206:209], v[20:23]
	v_mfma_f32_16x16x32_bf16 v[16:19], v[234:237], v[206:209], v[16:19]
	v_mfma_f32_16x16x32_bf16 v[4:7], v[226:229], v[218:221], v[4:7]
	v_mfma_f32_16x16x32_bf16 v[0:3], v[234:237], v[218:221], v[0:3]
	s_add_i32 s60, s60, 2
	s_add_u32 s46, s46, 0x100
	s_addc_u32 s47, s47, 0
	s_add_u32 s6, s6, 0x100
	s_addc_u32 s7, s7, 0
	s_cmp_gt_u32 s60, 13
	s_barrier
	s_cbranch_scc0 .LBB0_326

.LBB0_513:
	s_add_i32 s82, s84, -2
	s_add_u32 s83, s6, 0x100
	s_addc_u32 vcc_lo, s7, 0
	s_add_u32 s6, s60, 0x80
	s_addc_u32 s7, s61, 0
	s_mov_b32 s2, 0
	s_add_i32 vcc_hi, s2, 2
	s_add_u32 s21, s6, 0x80
	s_addc_u32 s3, s7, 0
	s_add_i32 s74, 0, 0x10000
	v_add_u32_e32 v140, s74, v161
	ds_read_b128 v[128:131], v140
	ds_read_b128 v[136:139], v140 offset:2048
	ds_read_b128 v[132:135], v140 offset:1024
	ds_read_b128 v[140:143], v140 offset:3072
	s_cmp_eq_u32 s82, s2
	s_cselect_b32 s2, s80, s21
	s_cselect_b32 s3, s81, s3
	s_cselect_b32 s61, s39, vcc_lo
	s_cselect_b32 s60, s38, s83
	v_lshl_add_u64 v[206:207], s[6:7], 0, v[168:169]
	s_add_i32 m0, s88, 0xc000
	ds_read_b128 v[144:147], v214
	ds_read_b128 v[152:155], v214 offset:2048
	ds_read_b128 v[174:177], v214 offset:4096
	ds_read_b128 v[182:185], v214 offset:6144
	ds_read_b128 v[148:151], v214 offset:1024
	ds_read_b128 v[170:173], v214 offset:3072
	ds_read_b128 v[178:181], v214 offset:5120
	ds_read_b128 v[186:189], v214 offset:7168
	global_load_lds_dwordx4 v[206:207], off
	v_lshl_add_u64 v[206:207], s[6:7], 0, v[166:167]
	s_add_i32 m0, s88, 0xe000
	s_nop 0
	global_load_lds_dwordx4 v[206:207], off
	s_waitcnt lgkmcnt(8)
	s_barrier
	s_waitcnt lgkmcnt(7)
	v_mfma_f32_16x16x32_bf16 v[124:127], v[128:131], v[144:147], 0
	v_mfma_f32_16x16x32_bf16 v[120:123], v[136:139], v[144:147], 0
	s_waitcnt lgkmcnt(6)
	v_mfma_f32_16x16x32_bf16 v[116:119], v[128:131], v[152:155], 0
	v_mfma_f32_16x16x32_bf16 v[108:111], v[136:139], v[152:155], 0
	s_waitcnt lgkmcnt(5)
	v_mfma_f32_16x16x32_bf16 v[100:103], v[128:131], v[174:177], 0
	v_mfma_f32_16x16x32_bf16 v[92:95], v[136:139], v[174:177], 0
	s_waitcnt lgkmcnt(4)
	v_mfma_f32_16x16x32_bf16 v[84:87], v[128:131], v[182:185], 0
	v_mfma_f32_16x16x32_bf16 v[76:79], v[136:139], v[182:185], 0
	s_waitcnt lgkmcnt(3)
	v_mfma_f32_16x16x32_bf16 v[124:127], v[132:135], v[148:151], v[124:127]
	v_mfma_f32_16x16x32_bf16 v[120:123], v[140:143], v[148:151], v[120:123]
	s_waitcnt lgkmcnt(2)
	v_mfma_f32_16x16x32_bf16 v[116:119], v[132:135], v[170:173], v[116:119]
	v_mfma_f32_16x16x32_bf16 v[108:111], v[140:143], v[170:173], v[108:111]
	s_waitcnt lgkmcnt(1)
	v_mfma_f32_16x16x32_bf16 v[100:103], v[132:135], v[178:181], v[100:103]
	v_mfma_f32_16x16x32_bf16 v[92:95], v[140:143], v[178:181], v[92:95]
	s_waitcnt lgkmcnt(0)
	v_mfma_f32_16x16x32_bf16 v[84:87], v[132:135], v[186:189], v[84:87]
	v_mfma_f32_16x16x32_bf16 v[76:79], v[140:143], v[186:189], v[76:79]
	s_barrier
	s_add_i32 s21, 0, 0x14000
	s_add_i32 s74, s74, s53
	v_add_u32_e32 v215, s21, v161
	v_lshl_add_u64 v[228:229], s[60:61], 0, v[156:157]
	s_mov_b32 m0, s74
	ds_read_b128 v[206:209], v215
	ds_read_b128 v[220:223], v215 offset:2048
	ds_read_b128 v[216:219], v215 offset:1024
	ds_read_b128 v[224:227], v215 offset:3072
	global_load_lds_dwordx4 v[228:229], off
	v_lshl_add_u64 v[230:231], s[60:61], 0, v[162:163]
	s_add_i32 m0, s74, 0x2000
	s_nop 0
	global_load_lds_dwordx4 v[230:231], off
	s_barrier
	s_waitcnt lgkmcnt(3)
	v_mfma_f32_16x16x32_bf16 v[112:115], v[206:209], v[144:147], 0
	s_waitcnt lgkmcnt(2)
	v_mfma_f32_16x16x32_bf16 v[104:107], v[220:223], v[144:147], 0
	v_mfma_f32_16x16x32_bf16 v[96:99], v[206:209], v[152:155], 0
	v_mfma_f32_16x16x32_bf16 v[88:91], v[220:223], v[152:155], 0
	v_mfma_f32_16x16x32_bf16 v[80:83], v[206:209], v[174:177], 0
	v_mfma_f32_16x16x32_bf16 v[72:75], v[220:223], v[174:177], 0
	v_mfma_f32_16x16x32_bf16 v[68:71], v[206:209], v[182:185], 0
	v_mfma_f32_16x16x32_bf16 v[64:67], v[220:223], v[182:185], 0
	s_waitcnt lgkmcnt(1)
	v_mfma_f32_16x16x32_bf16 v[112:115], v[216:219], v[148:151], v[112:115]
	s_waitcnt lgkmcnt(0)
	v_mfma_f32_16x16x32_bf16 v[104:107], v[224:227], v[148:151], v[104:107]
	v_mfma_f32_16x16x32_bf16 v[96:99], v[216:219], v[170:173], v[96:99]
	v_mfma_f32_16x16x32_bf16 v[88:91], v[224:227], v[170:173], v[88:91]
	v_mfma_f32_16x16x32_bf16 v[80:83], v[216:219], v[178:181], v[80:83]
	v_mfma_f32_16x16x32_bf16 v[72:75], v[224:227], v[178:181], v[72:75]
	v_mfma_f32_16x16x32_bf16 v[68:71], v[216:219], v[186:189], v[68:71]
	v_mfma_f32_16x16x32_bf16 v[64:67], v[224:227], v[186:189], v[64:67]
	s_mov_b32 m0, s88
	v_lshl_add_u64 v[232:233], s[2:3], 0, v[156:157]
	s_barrier
	ds_read_b128 v[144:147], v214 offset:16384
	ds_read_b128 v[152:155], v214 offset:18432
	ds_read_b128 v[174:177], v214 offset:20480
	ds_read_b128 v[182:185], v214 offset:22528
	ds_read_b128 v[148:151], v214 offset:17408
	ds_read_b128 v[170:173], v214 offset:19456
	ds_read_b128 v[178:181], v214 offset:21504
	ds_read_b128 v[186:189], v214 offset:23552
	global_load_lds_dwordx4 v[232:233], off
	v_lshl_add_u64 v[234:235], s[2:3], 0, v[162:163]
	s_mov_b32 m0, s89
	s_nop 0
	global_load_lds_dwordx4 v[234:235], off
	s_barrier
	s_waitcnt lgkmcnt(7)
	v_mfma_f32_16x16x32_bf16 v[60:63], v[128:131], v[144:147], 0
	v_mfma_f32_16x16x32_bf16 v[56:59], v[136:139], v[144:147], 0
	s_waitcnt lgkmcnt(6)
	v_mfma_f32_16x16x32_bf16 v[52:55], v[128:131], v[152:155], 0
	v_mfma_f32_16x16x32_bf16 v[44:47], v[136:139], v[152:155], 0
	s_waitcnt lgkmcnt(5)
	v_mfma_f32_16x16x32_bf16 v[36:39], v[128:131], v[174:177], 0
	v_mfma_f32_16x16x32_bf16 v[28:31], v[136:139], v[174:177], 0
	s_waitcnt lgkmcnt(4)
	v_mfma_f32_16x16x32_bf16 v[20:23], v[128:131], v[182:185], 0
	v_mfma_f32_16x16x32_bf16 v[12:15], v[136:139], v[182:185], 0
	s_waitcnt lgkmcnt(3)
	v_mfma_f32_16x16x32_bf16 v[60:63], v[132:135], v[148:151], v[60:63]
	v_mfma_f32_16x16x32_bf16 v[56:59], v[140:143], v[148:151], v[56:59]
	s_waitcnt lgkmcnt(2)
	v_mfma_f32_16x16x32_bf16 v[52:55], v[132:135], v[170:173], v[52:55]
	v_mfma_f32_16x16x32_bf16 v[44:47], v[140:143], v[170:173], v[44:47]
	s_waitcnt lgkmcnt(1)
	v_mfma_f32_16x16x32_bf16 v[36:39], v[132:135], v[178:181], v[36:39]
	v_mfma_f32_16x16x32_bf16 v[28:31], v[140:143], v[178:181], v[28:31]
	s_waitcnt lgkmcnt(0)
	v_mfma_f32_16x16x32_bf16 v[20:23], v[132:135], v[186:189], v[20:23]
	v_mfma_f32_16x16x32_bf16 v[12:15], v[140:143], v[186:189], v[12:15]
	s_barrier
	s_add_u32 s60, s60, s54
	s_addc_u32 s61, s61, 0
	s_add_i32 s21, s21, s53
	v_lshl_add_u64 v[236:237], s[60:61], 0, v[156:157]
	s_mov_b32 m0, s21
	v_lshl_add_u64 v[238:239], s[60:61], 0, v[162:163]
	global_load_lds_dwordx4 v[236:237], off
	s_add_i32 m0, s21, 0x2000
	s_nop 0
	global_load_lds_dwordx4 v[238:239], off
	s_waitcnt vmcnt(6)
	s_barrier
	v_mfma_f32_16x16x32_bf16 v[48:51], v[206:209], v[144:147], 0
	v_mfma_f32_16x16x32_bf16 v[40:43], v[220:223], v[144:147], 0
	v_mfma_f32_16x16x32_bf16 v[32:35], v[206:209], v[152:155], 0
	v_mfma_f32_16x16x32_bf16 v[24:27], v[220:223], v[152:155], 0
	v_mfma_f32_16x16x32_bf16 v[16:19], v[206:209], v[174:177], 0
	v_mfma_f32_16x16x32_bf16 v[8:11], v[220:223], v[174:177], 0
	v_mfma_f32_16x16x32_bf16 v[4:7], v[206:209], v[182:185], 0
	v_mfma_f32_16x16x32_bf16 v[0:3], v[220:223], v[182:185], 0
	v_mfma_f32_16x16x32_bf16 v[48:51], v[216:219], v[148:151], v[48:51]
	v_mfma_f32_16x16x32_bf16 v[40:43], v[224:227], v[148:151], v[40:43]
	v_mfma_f32_16x16x32_bf16 v[32:35], v[216:219], v[170:173], v[32:35]
	v_mfma_f32_16x16x32_bf16 v[24:27], v[224:227], v[170:173], v[24:27]
	v_mfma_f32_16x16x32_bf16 v[16:19], v[216:219], v[178:181], v[16:19]
	v_mfma_f32_16x16x32_bf16 v[8:11], v[224:227], v[178:181], v[8:11]
	v_mfma_f32_16x16x32_bf16 v[4:7], v[216:219], v[186:189], v[4:7]
	v_mfma_f32_16x16x32_bf16 v[0:3], v[224:227], v[186:189], v[0:3]
	s_add_i32 s21, 0, 0x18000
	v_add_u32_e32 v140, s21, v161
	s_barrier
	ds_read_b128 v[128:131], v140
	ds_read_b128 v[136:139], v140 offset:2048
	ds_read_b128 v[132:135], v140 offset:1024
	ds_read_b128 v[140:143], v140 offset:3072
	s_add_u32 s2, s2, s54
	s_addc_u32 s3, s3, 0
	s_mov_b32 m0, s94
	v_lshl_add_u64 v[206:207], s[2:3], 0, v[156:157]
	ds_read_b128 v[144:147], v214 offset:32768
	ds_read_b128 v[152:155], v214 offset:34816
	ds_read_b128 v[174:177], v214 offset:36864
	ds_read_b128 v[182:185], v214 offset:38912
	ds_read_b128 v[148:151], v214 offset:33792
	ds_read_b128 v[170:173], v214 offset:35840
	ds_read_b128 v[178:181], v214 offset:37888
	ds_read_b128 v[186:189], v214 offset:39936
	global_load_lds_dwordx4 v[206:207], off
	v_lshl_add_u64 v[206:207], s[2:3], 0, v[162:163]
	s_mov_b32 m0, s95
	s_nop 0
	global_load_lds_dwordx4 v[206:207], off
	s_waitcnt lgkmcnt(8)
	s_barrier
	s_waitcnt lgkmcnt(7)
	v_mfma_f32_16x16x32_bf16 v[124:127], v[128:131], v[144:147], v[124:127]
	v_mfma_f32_16x16x32_bf16 v[120:123], v[136:139], v[144:147], v[120:123]
	s_waitcnt lgkmcnt(6)
	v_mfma_f32_16x16x32_bf16 v[116:119], v[128:131], v[152:155], v[116:119]
	v_mfma_f32_16x16x32_bf16 v[108:111], v[136:139], v[152:155], v[108:111]
	s_waitcnt lgkmcnt(5)
	v_mfma_f32_16x16x32_bf16 v[100:103], v[128:131], v[174:177], v[100:103]
	v_mfma_f32_16x16x32_bf16 v[92:95], v[136:139], v[174:177], v[92:95]
	s_waitcnt lgkmcnt(4)
	v_mfma_f32_16x16x32_bf16 v[84:87], v[128:131], v[182:185], v[84:87]
	v_mfma_f32_16x16x32_bf16 v[76:79], v[136:139], v[182:185], v[76:79]
	s_waitcnt lgkmcnt(3)
	v_mfma_f32_16x16x32_bf16 v[124:127], v[132:135], v[148:151], v[124:127]
	v_mfma_f32_16x16x32_bf16 v[120:123], v[140:143], v[148:151], v[120:123]
	s_waitcnt lgkmcnt(2)
	v_mfma_f32_16x16x32_bf16 v[116:119], v[132:135], v[170:173], v[116:119]
	v_mfma_f32_16x16x32_bf16 v[108:111], v[140:143], v[170:173], v[108:111]
	s_waitcnt lgkmcnt(1)
	v_mfma_f32_16x16x32_bf16 v[100:103], v[132:135], v[178:181], v[100:103]
	v_mfma_f32_16x16x32_bf16 v[92:95], v[140:143], v[178:181], v[92:95]
	s_waitcnt lgkmcnt(0)
	v_mfma_f32_16x16x32_bf16 v[84:87], v[132:135], v[186:189], v[84:87]
	v_mfma_f32_16x16x32_bf16 v[76:79], v[140:143], v[186:189], v[76:79]
	s_barrier
	s_add_i32 s2, 0, 0x1c000
	s_add_i32 s3, s21, s53
	v_add_u32_e32 v215, s2, v161
	v_lshl_add_u64 v[228:229], v[228:229], 0, s[50:51]
	s_mov_b32 m0, s3
	ds_read_b128 v[206:209], v215
	ds_read_b128 v[220:223], v215 offset:2048
	ds_read_b128 v[216:219], v215 offset:1024
	ds_read_b128 v[224:227], v215 offset:3072
	global_load_lds_dwordx4 v[228:229], off
	v_lshl_add_u64 v[228:229], v[230:231], 0, s[50:51]
	s_add_i32 m0, s3, 0x2000
	s_nop 0
	global_load_lds_dwordx4 v[228:229], off
	s_barrier
	s_waitcnt lgkmcnt(3)
	v_mfma_f32_16x16x32_bf16 v[112:115], v[206:209], v[144:147], v[112:115]
	s_waitcnt lgkmcnt(2)
	v_mfma_f32_16x16x32_bf16 v[104:107], v[220:223], v[144:147], v[104:107]
	v_mfma_f32_16x16x32_bf16 v[96:99], v[206:209], v[152:155], v[96:99]
	v_mfma_f32_16x16x32_bf16 v[88:91], v[220:223], v[152:155], v[88:91]
	v_mfma_f32_16x16x32_bf16 v[80:83], v[206:209], v[174:177], v[80:83]
	v_mfma_f32_16x16x32_bf16 v[72:75], v[220:223], v[174:177], v[72:75]
	v_mfma_f32_16x16x32_bf16 v[68:71], v[206:209], v[182:185], v[68:71]
	v_mfma_f32_16x16x32_bf16 v[64:67], v[220:223], v[182:185], v[64:67]
	s_waitcnt lgkmcnt(1)
	v_mfma_f32_16x16x32_bf16 v[112:115], v[216:219], v[148:151], v[112:115]
	s_waitcnt lgkmcnt(0)
	v_mfma_f32_16x16x32_bf16 v[104:107], v[224:227], v[148:151], v[104:107]
	v_mfma_f32_16x16x32_bf16 v[96:99], v[216:219], v[170:173], v[96:99]
	v_mfma_f32_16x16x32_bf16 v[88:91], v[224:227], v[170:173], v[88:91]
	v_mfma_f32_16x16x32_bf16 v[80:83], v[216:219], v[178:181], v[80:83]
	v_mfma_f32_16x16x32_bf16 v[72:75], v[224:227], v[178:181], v[72:75]
	v_mfma_f32_16x16x32_bf16 v[68:71], v[216:219], v[186:189], v[68:71]
	v_mfma_f32_16x16x32_bf16 v[64:67], v[224:227], v[186:189], v[64:67]
	s_mov_b32 m0, s96
	v_lshl_add_u64 v[228:229], v[232:233], 0, s[50:51]
	s_barrier
	ds_read_b128 v[144:147], v214 offset:49152
	ds_read_b128 v[152:155], v214 offset:51200
	ds_read_b128 v[174:177], v214 offset:53248
	ds_read_b128 v[182:185], v214 offset:55296
	ds_read_b128 v[148:151], v214 offset:50176
	ds_read_b128 v[170:173], v214 offset:52224
	ds_read_b128 v[178:181], v214 offset:54272
	ds_read_b128 v[186:189], v214 offset:56320
	global_load_lds_dwordx4 v[228:229], off
	v_lshl_add_u64 v[228:229], v[234:235], 0, s[50:51]
	s_mov_b32 m0, s97
	s_nop 0
	global_load_lds_dwordx4 v[228:229], off
	s_barrier
	s_waitcnt lgkmcnt(7)
	v_mfma_f32_16x16x32_bf16 v[60:63], v[128:131], v[144:147], v[60:63]
	v_mfma_f32_16x16x32_bf16 v[56:59], v[136:139], v[144:147], v[56:59]
	s_waitcnt lgkmcnt(6)
	v_mfma_f32_16x16x32_bf16 v[52:55], v[128:131], v[152:155], v[52:55]
	v_mfma_f32_16x16x32_bf16 v[44:47], v[136:139], v[152:155], v[44:47]
	s_waitcnt lgkmcnt(5)
	v_mfma_f32_16x16x32_bf16 v[36:39], v[128:131], v[174:177], v[36:39]
	v_mfma_f32_16x16x32_bf16 v[28:31], v[136:139], v[174:177], v[28:31]
	s_waitcnt lgkmcnt(4)
	v_mfma_f32_16x16x32_bf16 v[20:23], v[128:131], v[182:185], v[20:23]
	v_mfma_f32_16x16x32_bf16 v[12:15], v[136:139], v[182:185], v[12:15]
	s_waitcnt lgkmcnt(3)
	v_mfma_f32_16x16x32_bf16 v[60:63], v[132:135], v[148:151], v[60:63]
	v_mfma_f32_16x16x32_bf16 v[56:59], v[140:143], v[148:151], v[56:59]
	s_waitcnt lgkmcnt(2)
	v_mfma_f32_16x16x32_bf16 v[52:55], v[132:135], v[170:173], v[52:55]
	v_mfma_f32_16x16x32_bf16 v[44:47], v[140:143], v[170:173], v[44:47]
	s_waitcnt lgkmcnt(1)
	v_mfma_f32_16x16x32_bf16 v[36:39], v[132:135], v[178:181], v[36:39]
	v_mfma_f32_16x16x32_bf16 v[28:31], v[140:143], v[178:181], v[28:31]
	s_waitcnt lgkmcnt(0)
	v_mfma_f32_16x16x32_bf16 v[20:23], v[132:135], v[186:189], v[20:23]
	v_mfma_f32_16x16x32_bf16 v[12:15], v[140:143], v[186:189], v[12:15]
	s_barrier
	s_add_i32 s2, s2, s53
	v_lshl_add_u64 v[128:129], v[236:237], 0, s[50:51]
	s_mov_b32 m0, s2
	s_nop 0
	global_load_lds_dwordx4 v[128:129], off
	v_lshl_add_u64 v[128:129], v[238:239], 0, s[50:51]
	s_add_i32 m0, s2, 0x2000
	s_nop 0
	global_load_lds_dwordx4 v[128:129], off
	s_waitcnt vmcnt(6)
	s_barrier
	v_mfma_f32_16x16x32_bf16 v[48:51], v[206:209], v[144:147], v[48:51]
	v_mfma_f32_16x16x32_bf16 v[40:43], v[220:223], v[144:147], v[40:43]
	v_mfma_f32_16x16x32_bf16 v[32:35], v[206:209], v[152:155], v[32:35]
	v_mfma_f32_16x16x32_bf16 v[24:27], v[220:223], v[152:155], v[24:27]
	v_mfma_f32_16x16x32_bf16 v[16:19], v[206:209], v[174:177], v[16:19]
	v_mfma_f32_16x16x32_bf16 v[8:11], v[220:223], v[174:177], v[8:11]
	v_mfma_f32_16x16x32_bf16 v[4:7], v[206:209], v[182:185], v[4:7]
	v_mfma_f32_16x16x32_bf16 v[0:3], v[220:223], v[182:185], v[0:3]
	v_mfma_f32_16x16x32_bf16 v[48:51], v[216:219], v[148:151], v[48:51]
	v_mfma_f32_16x16x32_bf16 v[40:43], v[224:227], v[148:151], v[40:43]
	v_mfma_f32_16x16x32_bf16 v[32:35], v[216:219], v[170:173], v[32:35]
	v_mfma_f32_16x16x32_bf16 v[24:27], v[224:227], v[170:173], v[24:27]
	v_mfma_f32_16x16x32_bf16 v[16:19], v[216:219], v[178:181], v[16:19]
	v_mfma_f32_16x16x32_bf16 v[8:11], v[224:227], v[178:181], v[8:11]
	v_mfma_f32_16x16x32_bf16 v[4:7], v[216:219], v[186:189], v[4:7]
	v_mfma_f32_16x16x32_bf16 v[0:3], v[224:227], v[186:189], v[0:3]
	s_add_u32 s83, s83, 0x100
	s_addc_u32 vcc_lo, vcc_lo, 0
	s_add_u32 s6, s6, 0x100
	s_addc_u32 s7, s7, 0
	s_cmp_ge_u32 vcc_hi, s84
	s_mov_b32 s2, vcc_hi
	s_barrier
	s_cbranch_scc1 .Lpost_514
.LBB0_514:
	s_add_i32 vcc_hi, s2, 2
	s_add_u32 s21, s6, 0x80
	s_addc_u32 s3, s7, 0
	s_add_i32 s74, 0, 0x10000
	v_add_u32_e32 v140, s74, v161
	ds_read_b128 v[128:131], v140
	ds_read_b128 v[136:139], v140 offset:2048
	ds_read_b128 v[132:135], v140 offset:1024
	ds_read_b128 v[140:143], v140 offset:3072
	s_cmp_eq_u32 s82, s2
	s_cselect_b32 s2, s80, s21
	s_cselect_b32 s3, s81, s3
	s_cselect_b32 s61, s39, vcc_lo
	s_cselect_b32 s60, s38, s83
	v_lshl_add_u64 v[206:207], s[6:7], 0, v[168:169]
	s_add_i32 m0, s88, 0xc000
	ds_read_b128 v[144:147], v214
	ds_read_b128 v[152:155], v214 offset:2048
	ds_read_b128 v[174:177], v214 offset:4096
	ds_read_b128 v[182:185], v214 offset:6144
	ds_read_b128 v[148:151], v214 offset:1024
	ds_read_b128 v[170:173], v214 offset:3072
	ds_read_b128 v[178:181], v214 offset:5120
	ds_read_b128 v[186:189], v214 offset:7168
	global_load_lds_dwordx4 v[206:207], off
	v_lshl_add_u64 v[206:207], s[6:7], 0, v[166:167]
	s_add_i32 m0, s88, 0xe000
	s_nop 0
	global_load_lds_dwordx4 v[206:207], off
	s_waitcnt lgkmcnt(8)
	s_barrier
	s_waitcnt lgkmcnt(7)
	v_mfma_f32_16x16x32_bf16 v[124:127], v[128:131], v[144:147], v[124:127]
	v_mfma_f32_16x16x32_bf16 v[120:123], v[136:139], v[144:147], v[120:123]
	s_waitcnt lgkmcnt(6)
	v_mfma_f32_16x16x32_bf16 v[116:119], v[128:131], v[152:155], v[116:119]
	v_mfma_f32_16x16x32_bf16 v[108:111], v[136:139], v[152:155], v[108:111]
	s_waitcnt lgkmcnt(5)
	v_mfma_f32_16x16x32_bf16 v[100:103], v[128:131], v[174:177], v[100:103]
	v_mfma_f32_16x16x32_bf16 v[92:95], v[136:139], v[174:177], v[92:95]
	s_waitcnt lgkmcnt(4)
	v_mfma_f32_16x16x32_bf16 v[84:87], v[128:131], v[182:185], v[84:87]
	v_mfma_f32_16x16x32_bf16 v[76:79], v[136:139], v[182:185], v[76:79]
	s_waitcnt lgkmcnt(3)
	v_mfma_f32_16x16x32_bf16 v[124:127], v[132:135], v[148:151], v[124:127]
	v_mfma_f32_16x16x32_bf16 v[120:123], v[140:143], v[148:151], v[120:123]
	s_waitcnt lgkmcnt(2)
	v_mfma_f32_16x16x32_bf16 v[116:119], v[132:135], v[170:173], v[116:119]
	v_mfma_f32_16x16x32_bf16 v[108:111], v[140:143], v[170:173], v[108:111]
	s_waitcnt lgkmcnt(1)
	v_mfma_f32_16x16x32_bf16 v[100:103], v[132:135], v[178:181], v[100:103]
	v_mfma_f32_16x16x32_bf16 v[92:95], v[140:143], v[178:181], v[92:95]
	s_waitcnt lgkmcnt(0)
	v_mfma_f32_16x16x32_bf16 v[84:87], v[132:135], v[186:189], v[84:87]
	v_mfma_f32_16x16x32_bf16 v[76:79], v[140:143], v[186:189], v[76:79]
	s_barrier
	s_add_i32 s21, 0, 0x14000
	s_add_i32 s74, s74, s53
	v_add_u32_e32 v215, s21, v161
	v_lshl_add_u64 v[228:229], s[60:61], 0, v[156:157]
	s_mov_b32 m0, s74
	ds_read_b128 v[206:209], v215
	ds_read_b128 v[220:223], v215 offset:2048
	ds_read_b128 v[216:219], v215 offset:1024
	ds_read_b128 v[224:227], v215 offset:3072
	global_load_lds_dwordx4 v[228:229], off
	v_lshl_add_u64 v[230:231], s[60:61], 0, v[162:163]
	s_add_i32 m0, s74, 0x2000
	s_nop 0
	global_load_lds_dwordx4 v[230:231], off
	s_barrier
	s_waitcnt lgkmcnt(3)
	v_mfma_f32_16x16x32_bf16 v[112:115], v[206:209], v[144:147], v[112:115]
	s_waitcnt lgkmcnt(2)
	v_mfma_f32_16x16x32_bf16 v[104:107], v[220:223], v[144:147], v[104:107]
	v_mfma_f32_16x16x32_bf16 v[96:99], v[206:209], v[152:155], v[96:99]
	v_mfma_f32_16x16x32_bf16 v[88:91], v[220:223], v[152:155], v[88:91]
	v_mfma_f32_16x16x32_bf16 v[80:83], v[206:209], v[174:177], v[80:83]
	v_mfma_f32_16x16x32_bf16 v[72:75], v[220:223], v[174:177], v[72:75]
	v_mfma_f32_16x16x32_bf16 v[68:71], v[206:209], v[182:185], v[68:71]
	v_mfma_f32_16x16x32_bf16 v[64:67], v[220:223], v[182:185], v[64:67]
	s_waitcnt lgkmcnt(1)
	v_mfma_f32_16x16x32_bf16 v[112:115], v[216:219], v[148:151], v[112:115]
	s_waitcnt lgkmcnt(0)
	v_mfma_f32_16x16x32_bf16 v[104:107], v[224:227], v[148:151], v[104:107]
	v_mfma_f32_16x16x32_bf16 v[96:99], v[216:219], v[170:173], v[96:99]
	v_mfma_f32_16x16x32_bf16 v[88:91], v[224:227], v[170:173], v[88:91]
	v_mfma_f32_16x16x32_bf16 v[80:83], v[216:219], v[178:181], v[80:83]
	v_mfma_f32_16x16x32_bf16 v[72:75], v[224:227], v[178:181], v[72:75]
	v_mfma_f32_16x16x32_bf16 v[68:71], v[216:219], v[186:189], v[68:71]
	v_mfma_f32_16x16x32_bf16 v[64:67], v[224:227], v[186:189], v[64:67]
	s_mov_b32 m0, s88
	v_lshl_add_u64 v[232:233], s[2:3], 0, v[156:157]
	s_barrier
	ds_read_b128 v[144:147], v214 offset:16384
	ds_read_b128 v[152:155], v214 offset:18432
	ds_read_b128 v[174:177], v214 offset:20480
	ds_read_b128 v[182:185], v214 offset:22528
	ds_read_b128 v[148:151], v214 offset:17408
	ds_read_b128 v[170:173], v214 offset:19456
	ds_read_b128 v[178:181], v214 offset:21504
	ds_read_b128 v[186:189], v214 offset:23552
	global_load_lds_dwordx4 v[232:233], off
	v_lshl_add_u64 v[234:235], s[2:3], 0, v[162:163]
	s_mov_b32 m0, s89
	s_nop 0
	global_load_lds_dwordx4 v[234:235], off
	s_barrier
	s_waitcnt lgkmcnt(7)
	v_mfma_f32_16x16x32_bf16 v[60:63], v[128:131], v[144:147], v[60:63]
	v_mfma_f32_16x16x32_bf16 v[56:59], v[136:139], v[144:147], v[56:59]
	s_waitcnt lgkmcnt(6)
	v_mfma_f32_16x16x32_bf16 v[52:55], v[128:131], v[152:155], v[52:55]
	v_mfma_f32_16x16x32_bf16 v[44:47], v[136:139], v[152:155], v[44:47]
	s_waitcnt lgkmcnt(5)
	v_mfma_f32_16x16x32_bf16 v[36:39], v[128:131], v[174:177], v[36:39]
	v_mfma_f32_16x16x32_bf16 v[28:31], v[136:139], v[174:177], v[28:31]
	s_waitcnt lgkmcnt(4)
	v_mfma_f32_16x16x32_bf16 v[20:23], v[128:131], v[182:185], v[20:23]
	v_mfma_f32_16x16x32_bf16 v[12:15], v[136:139], v[182:185], v[12:15]
	s_waitcnt lgkmcnt(3)
	v_mfma_f32_16x16x32_bf16 v[60:63], v[132:135], v[148:151], v[60:63]
	v_mfma_f32_16x16x32_bf16 v[56:59], v[140:143], v[148:151], v[56:59]
	s_waitcnt lgkmcnt(2)
	v_mfma_f32_16x16x32_bf16 v[52:55], v[132:135], v[170:173], v[52:55]
	v_mfma_f32_16x16x32_bf16 v[44:47], v[140:143], v[170:173], v[44:47]
	s_waitcnt lgkmcnt(1)
	v_mfma_f32_16x16x32_bf16 v[36:39], v[132:135], v[178:181], v[36:39]
	v_mfma_f32_16x16x32_bf16 v[28:31], v[140:143], v[178:181], v[28:31]
	s_waitcnt lgkmcnt(0)
	v_mfma_f32_16x16x32_bf16 v[20:23], v[132:135], v[186:189], v[20:23]
	v_mfma_f32_16x16x32_bf16 v[12:15], v[140:143], v[186:189], v[12:15]
	s_barrier
	s_add_u32 s60, s60, s54
	s_addc_u32 s61, s61, 0
	s_add_i32 s21, s21, s53
	v_lshl_add_u64 v[236:237], s[60:61], 0, v[156:157]
	s_mov_b32 m0, s21
	v_lshl_add_u64 v[238:239], s[60:61], 0, v[162:163]
	global_load_lds_dwordx4 v[236:237], off
	s_add_i32 m0, s21, 0x2000
	s_nop 0
	global_load_lds_dwordx4 v[238:239], off
	s_waitcnt vmcnt(6)
	s_barrier
	v_mfma_f32_16x16x32_bf16 v[48:51], v[206:209], v[144:147], v[48:51]
	v_mfma_f32_16x16x32_bf16 v[40:43], v[220:223], v[144:147], v[40:43]
	v_mfma_f32_16x16x32_bf16 v[32:35], v[206:209], v[152:155], v[32:35]
	v_mfma_f32_16x16x32_bf16 v[24:27], v[220:223], v[152:155], v[24:27]
	v_mfma_f32_16x16x32_bf16 v[16:19], v[206:209], v[174:177], v[16:19]
	v_mfma_f32_16x16x32_bf16 v[8:11], v[220:223], v[174:177], v[8:11]
	v_mfma_f32_16x16x32_bf16 v[4:7], v[206:209], v[182:185], v[4:7]
	v_mfma_f32_16x16x32_bf16 v[0:3], v[220:223], v[182:185], v[0:3]
	v_mfma_f32_16x16x32_bf16 v[48:51], v[216:219], v[148:151], v[48:51]
	v_mfma_f32_16x16x32_bf16 v[40:43], v[224:227], v[148:151], v[40:43]
	v_mfma_f32_16x16x32_bf16 v[32:35], v[216:219], v[170:173], v[32:35]
	v_mfma_f32_16x16x32_bf16 v[24:27], v[224:227], v[170:173], v[24:27]
	v_mfma_f32_16x16x32_bf16 v[16:19], v[216:219], v[178:181], v[16:19]
	v_mfma_f32_16x16x32_bf16 v[8:11], v[224:227], v[178:181], v[8:11]
	v_mfma_f32_16x16x32_bf16 v[4:7], v[216:219], v[186:189], v[4:7]
	v_mfma_f32_16x16x32_bf16 v[0:3], v[224:227], v[186:189], v[0:3]
	s_add_i32 s21, 0, 0x18000
	v_add_u32_e32 v140, s21, v161
	s_barrier
	ds_read_b128 v[128:131], v140
	ds_read_b128 v[136:139], v140 offset:2048
	ds_read_b128 v[132:135], v140 offset:1024
	ds_read_b128 v[140:143], v140 offset:3072
	s_add_u32 s2, s2, s54
	s_addc_u32 s3, s3, 0
	s_mov_b32 m0, s94
	v_lshl_add_u64 v[206:207], s[2:3], 0, v[156:157]
	ds_read_b128 v[144:147], v214 offset:32768
	ds_read_b128 v[152:155], v214 offset:34816
	ds_read_b128 v[174:177], v214 offset:36864
	ds_read_b128 v[182:185], v214 offset:38912
	ds_read_b128 v[148:151], v214 offset:33792
	ds_read_b128 v[170:173], v214 offset:35840
	ds_read_b128 v[178:181], v214 offset:37888
	ds_read_b128 v[186:189], v214 offset:39936
	global_load_lds_dwordx4 v[206:207], off
	v_lshl_add_u64 v[206:207], s[2:3], 0, v[162:163]
	s_mov_b32 m0, s95
	s_nop 0
	global_load_lds_dwordx4 v[206:207], off
	s_waitcnt lgkmcnt(8)
	s_barrier
	s_waitcnt lgkmcnt(7)
	v_mfma_f32_16x16x32_bf16 v[124:127], v[128:131], v[144:147], v[124:127]
	v_mfma_f32_16x16x32_bf16 v[120:123], v[136:139], v[144:147], v[120:123]
	s_waitcnt lgkmcnt(6)
	v_mfma_f32_16x16x32_bf16 v[116:119], v[128:131], v[152:155], v[116:119]
	v_mfma_f32_16x16x32_bf16 v[108:111], v[136:139], v[152:155], v[108:111]
	s_waitcnt lgkmcnt(5)
	v_mfma_f32_16x16x32_bf16 v[100:103], v[128:131], v[174:177], v[100:103]
	v_mfma_f32_16x16x32_bf16 v[92:95], v[136:139], v[174:177], v[92:95]
	s_waitcnt lgkmcnt(4)
	v_mfma_f32_16x16x32_bf16 v[84:87], v[128:131], v[182:185], v[84:87]
	v_mfma_f32_16x16x32_bf16 v[76:79], v[136:139], v[182:185], v[76:79]
	s_waitcnt lgkmcnt(3)
	v_mfma_f32_16x16x32_bf16 v[124:127], v[132:135], v[148:151], v[124:127]
	v_mfma_f32_16x16x32_bf16 v[120:123], v[140:143], v[148:151], v[120:123]
	s_waitcnt lgkmcnt(2)
	v_mfma_f32_16x16x32_bf16 v[116:119], v[132:135], v[170:173], v[116:119]
	v_mfma_f32_16x16x32_bf16 v[108:111], v[140:143], v[170:173], v[108:111]
	s_waitcnt lgkmcnt(1)
	v_mfma_f32_16x16x32_bf16 v[100:103], v[132:135], v[178:181], v[100:103]
	v_mfma_f32_16x16x32_bf16 v[92:95], v[140:143], v[178:181], v[92:95]
	s_waitcnt lgkmcnt(0)
	v_mfma_f32_16x16x32_bf16 v[84:87], v[132:135], v[186:189], v[84:87]
	v_mfma_f32_16x16x32_bf16 v[76:79], v[140:143], v[186:189], v[76:79]
	s_barrier
	s_add_i32 s2, 0, 0x1c000
	s_add_i32 s3, s21, s53
	v_add_u32_e32 v215, s2, v161
	v_lshl_add_u64 v[228:229], v[228:229], 0, s[50:51]
	s_mov_b32 m0, s3
	ds_read_b128 v[206:209], v215
	ds_read_b128 v[220:223], v215 offset:2048
	ds_read_b128 v[216:219], v215 offset:1024
	ds_read_b128 v[224:227], v215 offset:3072
	global_load_lds_dwordx4 v[228:229], off
	v_lshl_add_u64 v[228:229], v[230:231], 0, s[50:51]
	s_add_i32 m0, s3, 0x2000
	s_nop 0
	global_load_lds_dwordx4 v[228:229], off
	s_barrier
	s_waitcnt lgkmcnt(3)
	v_mfma_f32_16x16x32_bf16 v[112:115], v[206:209], v[144:147], v[112:115]
	s_waitcnt lgkmcnt(2)
	v_mfma_f32_16x16x32_bf16 v[104:107], v[220:223], v[144:147], v[104:107]
	v_mfma_f32_16x16x32_bf16 v[96:99], v[206:209], v[152:155], v[96:99]
	v_mfma_f32_16x16x32_bf16 v[88:91], v[220:223], v[152:155], v[88:91]
	v_mfma_f32_16x16x32_bf16 v[80:83], v[206:209], v[174:177], v[80:83]
	v_mfma_f32_16x16x32_bf16 v[72:75], v[220:223], v[174:177], v[72:75]
	v_mfma_f32_16x16x32_bf16 v[68:71], v[206:209], v[182:185], v[68:71]
	v_mfma_f32_16x16x32_bf16 v[64:67], v[220:223], v[182:185], v[64:67]
	s_waitcnt lgkmcnt(1)
	v_mfma_f32_16x16x32_bf16 v[112:115], v[216:219], v[148:151], v[112:115]
	s_waitcnt lgkmcnt(0)
	v_mfma_f32_16x16x32_bf16 v[104:107], v[224:227], v[148:151], v[104:107]
	v_mfma_f32_16x16x32_bf16 v[96:99], v[216:219], v[170:173], v[96:99]
	v_mfma_f32_16x16x32_bf16 v[88:91], v[224:227], v[170:173], v[88:91]
	v_mfma_f32_16x16x32_bf16 v[80:83], v[216:219], v[178:181], v[80:83]
	v_mfma_f32_16x16x32_bf16 v[72:75], v[224:227], v[178:181], v[72:75]
	v_mfma_f32_16x16x32_bf16 v[68:71], v[216:219], v[186:189], v[68:71]
	v_mfma_f32_16x16x32_bf16 v[64:67], v[224:227], v[186:189], v[64:67]
	s_mov_b32 m0, s96
	v_lshl_add_u64 v[228:229], v[232:233], 0, s[50:51]
	s_barrier
	ds_read_b128 v[144:147], v214 offset:49152
	ds_read_b128 v[152:155], v214 offset:51200
	ds_read_b128 v[174:177], v214 offset:53248
	ds_read_b128 v[182:185], v214 offset:55296
	ds_read_b128 v[148:151], v214 offset:50176
	ds_read_b128 v[170:173], v214 offset:52224
	ds_read_b128 v[178:181], v214 offset:54272
	ds_read_b128 v[186:189], v214 offset:56320
	global_load_lds_dwordx4 v[228:229], off
	v_lshl_add_u64 v[228:229], v[234:235], 0, s[50:51]
	s_mov_b32 m0, s97
	s_nop 0
	global_load_lds_dwordx4 v[228:229], off
	s_barrier
	s_waitcnt lgkmcnt(7)
	v_mfma_f32_16x16x32_bf16 v[60:63], v[128:131], v[144:147], v[60:63]
	v_mfma_f32_16x16x32_bf16 v[56:59], v[136:139], v[144:147], v[56:59]
	s_waitcnt lgkmcnt(6)
	v_mfma_f32_16x16x32_bf16 v[52:55], v[128:131], v[152:155], v[52:55]
	v_mfma_f32_16x16x32_bf16 v[44:47], v[136:139], v[152:155], v[44:47]
	s_waitcnt lgkmcnt(5)
	v_mfma_f32_16x16x32_bf16 v[36:39], v[128:131], v[174:177], v[36:39]
	v_mfma_f32_16x16x32_bf16 v[28:31], v[136:139], v[174:177], v[28:31]
	s_waitcnt lgkmcnt(4)
	v_mfma_f32_16x16x32_bf16 v[20:23], v[128:131], v[182:185], v[20:23]
	v_mfma_f32_16x16x32_bf16 v[12:15], v[136:139], v[182:185], v[12:15]
	s_waitcnt lgkmcnt(3)
	v_mfma_f32_16x16x32_bf16 v[60:63], v[132:135], v[148:151], v[60:63]
	v_mfma_f32_16x16x32_bf16 v[56:59], v[140:143], v[148:151], v[56:59]
	s_waitcnt lgkmcnt(2)
	v_mfma_f32_16x16x32_bf16 v[52:55], v[132:135], v[170:173], v[52:55]
	v_mfma_f32_16x16x32_bf16 v[44:47], v[140:143], v[170:173], v[44:47]
	s_waitcnt lgkmcnt(1)
	v_mfma_f32_16x16x32_bf16 v[36:39], v[132:135], v[178:181], v[36:39]
	v_mfma_f32_16x16x32_bf16 v[28:31], v[140:143], v[178:181], v[28:31]
	s_waitcnt lgkmcnt(0)
	v_mfma_f32_16x16x32_bf16 v[20:23], v[132:135], v[186:189], v[20:23]
	v_mfma_f32_16x16x32_bf16 v[12:15], v[140:143], v[186:189], v[12:15]
	s_barrier
	s_add_i32 s2, s2, s53
	v_lshl_add_u64 v[128:129], v[236:237], 0, s[50:51]
	s_mov_b32 m0, s2
	s_nop 0
	global_load_lds_dwordx4 v[128:129], off
	v_lshl_add_u64 v[128:129], v[238:239], 0, s[50:51]
	s_add_i32 m0, s2, 0x2000
	s_nop 0
	global_load_lds_dwordx4 v[128:129], off
	s_waitcnt vmcnt(6)
	s_barrier
	v_mfma_f32_16x16x32_bf16 v[48:51], v[206:209], v[144:147], v[48:51]
	v_mfma_f32_16x16x32_bf16 v[40:43], v[220:223], v[144:147], v[40:43]
	v_mfma_f32_16x16x32_bf16 v[32:35], v[206:209], v[152:155], v[32:35]
	v_mfma_f32_16x16x32_bf16 v[24:27], v[220:223], v[152:155], v[24:27]
	v_mfma_f32_16x16x32_bf16 v[16:19], v[206:209], v[174:177], v[16:19]
	v_mfma_f32_16x16x32_bf16 v[8:11], v[220:223], v[174:177], v[8:11]
	v_mfma_f32_16x16x32_bf16 v[4:7], v[206:209], v[182:185], v[4:7]
	v_mfma_f32_16x16x32_bf16 v[0:3], v[220:223], v[182:185], v[0:3]
	v_mfma_f32_16x16x32_bf16 v[48:51], v[216:219], v[148:151], v[48:51]
	v_mfma_f32_16x16x32_bf16 v[40:43], v[224:227], v[148:151], v[40:43]
	v_mfma_f32_16x16x32_bf16 v[32:35], v[216:219], v[170:173], v[32:35]
	v_mfma_f32_16x16x32_bf16 v[24:27], v[224:227], v[170:173], v[24:27]
	v_mfma_f32_16x16x32_bf16 v[16:19], v[216:219], v[178:181], v[16:19]
	v_mfma_f32_16x16x32_bf16 v[8:11], v[224:227], v[178:181], v[8:11]
	v_mfma_f32_16x16x32_bf16 v[4:7], v[216:219], v[186:189], v[4:7]
	v_mfma_f32_16x16x32_bf16 v[0:3], v[224:227], v[186:189], v[0:3]
	s_add_u32 s83, s83, 0x100
	s_addc_u32 vcc_lo, vcc_lo, 0
	s_add_u32 s6, s6, 0x100
	s_addc_u32 s7, s7, 0
	s_cmp_ge_u32 vcc_hi, s84
	s_mov_b32 s2, vcc_hi
	s_barrier
	s_cbranch_scc0 .LBB0_514

.LBB0_554:
	s_add_i32 s68, s68, 1
	s_mul_i32 s2, s68, s18
	s_add_i32 s10, s2, s20
	s_cmp_lt_i32 s10, s19
	s_cselect_b64 s[2:3], -1, 0
	s_cmp_ge_i32 s10, s19
	s_cselect_b64 s[38:39], -1, 0
	s_and_b64 s[6:7], s[2:3], exec
	s_cselect_b32 s6, s10, 0
	s_ashr_i32 s7, s6, 31
	s_lshr_b32 s7, s7, 29
	s_add_i32 s7, s6, s7
	s_ashr_i32 s10, s7, 3
	s_and_b32 s7, s7, -8
	s_sub_i32 s6, s6, s7
	s_cmp_lt_i32 s6, 0
	s_cselect_b32 s7, s61, s60
	s_mul_i32 s6, s7, s6
	s_add_i32 s10, s6, s10
	s_mul_hi_i32 s6, s10, 0x2e8ba2e9
	s_lshr_b32 s7, s6, 31
	s_ashr_i32 s6, s6, 4
	s_add_i32 s24, s6, s7
	s_lshl_b32 s25, s24, 2
	s_sub_i32 s6, s9, s25
	s_min_i32 s41, s6, 4
	s_abs_i32 s40, s41
	v_cvt_f32_u32_e32 v0, s40
	s_mov_b64 s[6:7], s[34:35]
	s_mov_b64 s[54:55], s[36:37]
	s_sub_i32 s35, 0, s40
	v_rcp_iflag_f32_e32 v0, v0
	s_mulk_i32 s24, 0x58
	s_sub_i32 s10, s10, s24
	s_abs_i32 s34, s10
	v_mul_f32_e32 v0, 0x4f7ffffe, v0
	v_cvt_u32_f32_e32 v0, v0
	s_xor_b32 s24, s10, s41
	s_ashr_i32 s24, s24, 31
	s_mov_b32 s73, -2
	v_readfirstlane_b32 s36, v0
	s_mul_i32 s35, s35, s36
	s_mul_hi_u32 s35, s36, s35
	s_add_i32 s36, s36, s35
	s_mul_hi_u32 s35, s34, s36
	s_mul_i32 s36, s35, s40
	s_sub_i32 s34, s34, s36
	s_add_i32 s36, s35, 1
	s_sub_i32 s37, s34, s40
	s_cmp_ge_u32 s34, s40
	s_cselect_b32 s35, s36, s35
	s_cselect_b32 s34, s37, s34
	s_add_i32 s36, s35, 1
	s_cmp_ge_u32 s34, s40
	s_cselect_b32 s34, s36, s35
	s_xor_b32 s34, s34, s24
	s_sub_i32 s40, s34, s24
	s_mul_i32 s24, s40, s41
	s_sub_i32 s10, s10, s24
	s_add_i32 s42, s25, s10
	s_ashr_i32 s43, s42, 31
	s_lshl_b64 s[24:25], s[42:43], 19
	s_add_u32 s34, s58, s24
	s_addc_u32 s35, s59, s25
	s_and_b64 s[24:25], s[2:3], exec
	s_cselect_b32 s10, s35, s7
	s_cselect_b32 s24, s34, s6
	s_ashr_i32 s41, s40, 31
	s_lshl_b64 s[36:37], s[40:41], 19
	s_add_u32 s36, s44, s36
	s_addc_u32 s37, s45, s37
	s_and_b64 s[2:3], s[2:3], exec
	s_cselect_b32 s25, s37, s55
	s_cselect_b32 s41, s36, s54
	s_add_u32 s43, s54, 0x100
	s_addc_u32 s69, s55, 0
	s_add_u32 s6, s6, 0x40080
	s_addc_u32 s7, s7, 0
	s_add_u32 s2, s6, 0xfffc0080
	s_addc_u32 s3, s7, -1
	s_add_i32 s77, 0, 0x10000
	v_add_u32_e32 v150, s77, v139
	ds_read_b128 v[134:137], v150
	ds_read_b128 v[146:149], v150 offset:2048
	ds_read_b128 v[142:145], v150 offset:1024
	ds_read_b128 v[150:153], v150 offset:3072
	s_cmp_eq_u32 s73, 12
	s_cselect_b32 s3, s10, s3
	s_cselect_b32 s2, s24, s2
	s_cselect_b32 s55, s25, s69
	s_cselect_b32 s54, s41, s43
	v_lshl_add_u64 v[154:155], s[6:7], 0, v[132:133]
	s_add_i32 m0, s47, 0xc000
	ds_read_b128 v[162:165], v141
	ds_read_b128 v[170:173], v141 offset:2048
	ds_read_b128 v[178:181], v141 offset:4096
	ds_read_b128 v[186:189], v141 offset:6144
	ds_read_b128 v[166:169], v141 offset:1024
	ds_read_b128 v[174:177], v141 offset:3072
	ds_read_b128 v[182:185], v141 offset:5120
	ds_read_b128 v[214:217], v141 offset:7168
	global_load_lds_dwordx4 v[154:155], off
	v_lshl_add_u64 v[154:155], s[6:7], 0, v[130:131]
	s_add_i32 m0, s47, 0xe000
	s_nop 0
	global_load_lds_dwordx4 v[154:155], off
	s_waitcnt lgkmcnt(8)
	s_barrier
	s_waitcnt lgkmcnt(7)
	v_mfma_f32_16x16x32_bf16 v[124:127], v[134:137], v[162:165], 0
	v_mfma_f32_16x16x32_bf16 v[116:119], v[146:149], v[162:165], 0
	s_waitcnt lgkmcnt(6)
	v_mfma_f32_16x16x32_bf16 v[108:111], v[134:137], v[170:173], 0
	v_mfma_f32_16x16x32_bf16 v[100:103], v[146:149], v[170:173], 0
	s_waitcnt lgkmcnt(5)
	v_mfma_f32_16x16x32_bf16 v[92:95], v[134:137], v[178:181], 0
	v_mfma_f32_16x16x32_bf16 v[84:87], v[146:149], v[178:181], 0
	s_waitcnt lgkmcnt(4)
	v_mfma_f32_16x16x32_bf16 v[76:79], v[134:137], v[186:189], 0
	v_mfma_f32_16x16x32_bf16 v[68:71], v[146:149], v[186:189], 0
	s_waitcnt lgkmcnt(3)
	v_mfma_f32_16x16x32_bf16 v[124:127], v[142:145], v[166:169], v[124:127]
	v_mfma_f32_16x16x32_bf16 v[116:119], v[150:153], v[166:169], v[116:119]
	s_waitcnt lgkmcnt(2)
	v_mfma_f32_16x16x32_bf16 v[108:111], v[142:145], v[174:177], v[108:111]
	v_mfma_f32_16x16x32_bf16 v[100:103], v[150:153], v[174:177], v[100:103]
	s_waitcnt lgkmcnt(1)
	v_mfma_f32_16x16x32_bf16 v[92:95], v[142:145], v[182:185], v[92:95]
	v_mfma_f32_16x16x32_bf16 v[84:87], v[150:153], v[182:185], v[84:87]
	s_waitcnt lgkmcnt(0)
	v_mfma_f32_16x16x32_bf16 v[76:79], v[142:145], v[214:217], v[76:79]
	v_mfma_f32_16x16x32_bf16 v[68:71], v[150:153], v[214:217], v[68:71]
	s_barrier
	s_add_i32 s80, 0, 0x14000
	v_add_u32_e32 v154, s80, v139
	s_add_i32 s77, s77, s53
	ds_read_b128 v[218:221], v154
	ds_read_b128 v[226:229], v154 offset:2048
	ds_read_b128 v[222:225], v154 offset:1024
	ds_read_b128 v[230:233], v154 offset:3072
	v_lshl_add_u64 v[154:155], s[54:55], 0, v[156:157]
	s_mov_b32 m0, s77
	v_lshl_add_u64 v[206:207], s[54:55], 0, v[128:129]
	global_load_lds_dwordx4 v[154:155], off
	s_add_i32 m0, s77, 0x2000
	s_nop 0
	global_load_lds_dwordx4 v[206:207], off
	s_barrier
	s_waitcnt lgkmcnt(3)
	v_mfma_f32_16x16x32_bf16 v[120:123], v[218:221], v[162:165], 0
	s_waitcnt lgkmcnt(2)
	v_mfma_f32_16x16x32_bf16 v[112:115], v[226:229], v[162:165], 0
	v_mfma_f32_16x16x32_bf16 v[104:107], v[218:221], v[170:173], 0
	v_mfma_f32_16x16x32_bf16 v[96:99], v[226:229], v[170:173], 0
	v_mfma_f32_16x16x32_bf16 v[88:91], v[218:221], v[178:181], 0
	v_mfma_f32_16x16x32_bf16 v[80:83], v[226:229], v[178:181], 0
	v_mfma_f32_16x16x32_bf16 v[72:75], v[218:221], v[186:189], 0
	v_mfma_f32_16x16x32_bf16 v[64:67], v[226:229], v[186:189], 0
	s_waitcnt lgkmcnt(1)
	v_mfma_f32_16x16x32_bf16 v[120:123], v[222:225], v[166:169], v[120:123]
	s_waitcnt lgkmcnt(0)
	v_mfma_f32_16x16x32_bf16 v[112:115], v[230:233], v[166:169], v[112:115]
	v_mfma_f32_16x16x32_bf16 v[104:107], v[222:225], v[174:177], v[104:107]
	v_mfma_f32_16x16x32_bf16 v[96:99], v[230:233], v[174:177], v[96:99]
	v_mfma_f32_16x16x32_bf16 v[88:91], v[222:225], v[182:185], v[88:91]
	v_mfma_f32_16x16x32_bf16 v[80:83], v[230:233], v[182:185], v[80:83]
	v_mfma_f32_16x16x32_bf16 v[72:75], v[222:225], v[214:217], v[72:75]
	v_mfma_f32_16x16x32_bf16 v[64:67], v[230:233], v[214:217], v[64:67]
	s_mov_b32 m0, s47
	v_lshl_add_u64 v[208:209], s[2:3], 0, v[156:157]
	s_barrier
	ds_read_b128 v[162:165], v141 offset:16384
	ds_read_b128 v[170:173], v141 offset:18432
	ds_read_b128 v[178:181], v141 offset:20480
	ds_read_b128 v[186:189], v141 offset:22528
	ds_read_b128 v[166:169], v141 offset:17408
	ds_read_b128 v[174:177], v141 offset:19456
	ds_read_b128 v[182:185], v141 offset:21504
	ds_read_b128 v[214:217], v141 offset:23552
	global_load_lds_dwordx4 v[208:209], off
	v_lshl_add_u64 v[234:235], s[2:3], 0, v[128:129]
	s_mov_b32 m0, s49
	s_nop 0
	global_load_lds_dwordx4 v[234:235], off
	s_barrier
	s_waitcnt lgkmcnt(7)
	v_mfma_f32_16x16x32_bf16 v[60:63], v[134:137], v[162:165], 0
	v_mfma_f32_16x16x32_bf16 v[52:55], v[146:149], v[162:165], 0
	s_waitcnt lgkmcnt(6)
	v_mfma_f32_16x16x32_bf16 v[44:47], v[134:137], v[170:173], 0
	v_mfma_f32_16x16x32_bf16 v[36:39], v[146:149], v[170:173], 0
	s_waitcnt lgkmcnt(5)
	v_mfma_f32_16x16x32_bf16 v[28:31], v[134:137], v[178:181], 0
	v_mfma_f32_16x16x32_bf16 v[20:23], v[146:149], v[178:181], 0
	s_waitcnt lgkmcnt(4)
	v_mfma_f32_16x16x32_bf16 v[12:15], v[134:137], v[186:189], 0
	v_mfma_f32_16x16x32_bf16 v[4:7], v[146:149], v[186:189], 0
	s_waitcnt lgkmcnt(3)
	v_mfma_f32_16x16x32_bf16 v[60:63], v[142:145], v[166:169], v[60:63]
	v_mfma_f32_16x16x32_bf16 v[52:55], v[150:153], v[166:169], v[52:55]
	s_waitcnt lgkmcnt(2)
	v_mfma_f32_16x16x32_bf16 v[44:47], v[142:145], v[174:177], v[44:47]
	v_mfma_f32_16x16x32_bf16 v[36:39], v[150:153], v[174:177], v[36:39]
	s_waitcnt lgkmcnt(1)
	v_mfma_f32_16x16x32_bf16 v[28:31], v[142:145], v[182:185], v[28:31]
	v_mfma_f32_16x16x32_bf16 v[20:23], v[150:153], v[182:185], v[20:23]
	s_waitcnt lgkmcnt(0)
	v_mfma_f32_16x16x32_bf16 v[12:15], v[142:145], v[214:217], v[12:15]
	v_mfma_f32_16x16x32_bf16 v[4:7], v[150:153], v[214:217], v[4:7]
	s_barrier
	s_add_u32 s78, s54, 0x40000
	s_addc_u32 s79, s55, 0
	s_add_i32 s77, s80, s53
	v_lshl_add_u64 v[134:135], s[78:79], 0, v[156:157]
	s_mov_b32 m0, s77
	s_nop 0
	global_load_lds_dwordx4 v[134:135], off
	v_lshl_add_u64 v[134:135], s[78:79], 0, v[128:129]
	s_add_i32 m0, s77, 0x2000
	s_nop 0
	global_load_lds_dwordx4 v[134:135], off
	s_waitcnt vmcnt(6)
	s_barrier
	v_mfma_f32_16x16x32_bf16 v[56:59], v[218:221], v[162:165], 0
	v_mfma_f32_16x16x32_bf16 v[48:51], v[226:229], v[162:165], 0
	v_mfma_f32_16x16x32_bf16 v[40:43], v[218:221], v[170:173], 0
	v_mfma_f32_16x16x32_bf16 v[32:35], v[226:229], v[170:173], 0
	v_mfma_f32_16x16x32_bf16 v[24:27], v[218:221], v[178:181], 0
	v_mfma_f32_16x16x32_bf16 v[16:19], v[226:229], v[178:181], 0
	v_mfma_f32_16x16x32_bf16 v[8:11], v[218:221], v[186:189], 0
	v_mfma_f32_16x16x32_bf16 v[0:3], v[226:229], v[186:189], 0
	v_mfma_f32_16x16x32_bf16 v[56:59], v[222:225], v[166:169], v[56:59]
	v_mfma_f32_16x16x32_bf16 v[48:51], v[230:233], v[166:169], v[48:51]
	v_mfma_f32_16x16x32_bf16 v[40:43], v[222:225], v[174:177], v[40:43]
	v_mfma_f32_16x16x32_bf16 v[32:35], v[230:233], v[174:177], v[32:35]
	v_mfma_f32_16x16x32_bf16 v[24:27], v[222:225], v[182:185], v[24:27]
	v_mfma_f32_16x16x32_bf16 v[16:19], v[230:233], v[182:185], v[16:19]
	v_mfma_f32_16x16x32_bf16 v[8:11], v[222:225], v[214:217], v[8:11]
	v_mfma_f32_16x16x32_bf16 v[0:3], v[230:233], v[214:217], v[0:3]
	s_add_i32 s77, 0, 0x18000
	v_add_u32_e32 v150, s77, v139
	s_barrier
	ds_read_b128 v[134:137], v150
	ds_read_b128 v[146:149], v150 offset:2048
	ds_read_b128 v[142:145], v150 offset:1024
	ds_read_b128 v[150:153], v150 offset:3072
	s_add_u32 s2, s2, 0x40000
	s_addc_u32 s3, s3, 0
	s_mov_b32 m0, s62
	v_lshl_add_u64 v[218:219], s[2:3], 0, v[156:157]
	ds_read_b128 v[162:165], v141 offset:32768
	ds_read_b128 v[170:173], v141 offset:34816
	ds_read_b128 v[178:181], v141 offset:36864
	ds_read_b128 v[186:189], v141 offset:38912
	ds_read_b128 v[166:169], v141 offset:33792
	ds_read_b128 v[174:177], v141 offset:35840
	ds_read_b128 v[182:185], v141 offset:37888
	ds_read_b128 v[214:217], v141 offset:39936
	global_load_lds_dwordx4 v[218:219], off
	v_lshl_add_u64 v[218:219], s[2:3], 0, v[128:129]
	s_mov_b32 m0, s63
	s_nop 0
	global_load_lds_dwordx4 v[218:219], off
	s_waitcnt lgkmcnt(8)
	s_barrier
	s_waitcnt lgkmcnt(7)
	v_mfma_f32_16x16x32_bf16 v[124:127], v[134:137], v[162:165], v[124:127]
	v_mfma_f32_16x16x32_bf16 v[116:119], v[146:149], v[162:165], v[116:119]
	s_waitcnt lgkmcnt(6)
	v_mfma_f32_16x16x32_bf16 v[108:111], v[134:137], v[170:173], v[108:111]
	v_mfma_f32_16x16x32_bf16 v[100:103], v[146:149], v[170:173], v[100:103]
	s_waitcnt lgkmcnt(5)
	v_mfma_f32_16x16x32_bf16 v[92:95], v[134:137], v[178:181], v[92:95]
	v_mfma_f32_16x16x32_bf16 v[84:87], v[146:149], v[178:181], v[84:87]
	s_waitcnt lgkmcnt(4)
	v_mfma_f32_16x16x32_bf16 v[76:79], v[134:137], v[186:189], v[76:79]
	v_mfma_f32_16x16x32_bf16 v[68:71], v[146:149], v[186:189], v[68:71]
	s_waitcnt lgkmcnt(3)
	v_mfma_f32_16x16x32_bf16 v[124:127], v[142:145], v[166:169], v[124:127]
	v_mfma_f32_16x16x32_bf16 v[116:119], v[150:153], v[166:169], v[116:119]
	s_waitcnt lgkmcnt(2)
	v_mfma_f32_16x16x32_bf16 v[108:111], v[142:145], v[174:177], v[108:111]
	v_mfma_f32_16x16x32_bf16 v[100:103], v[150:153], v[174:177], v[100:103]
	s_waitcnt lgkmcnt(1)
	v_mfma_f32_16x16x32_bf16 v[92:95], v[142:145], v[182:185], v[92:95]
	v_mfma_f32_16x16x32_bf16 v[84:87], v[150:153], v[182:185], v[84:87]
	s_waitcnt lgkmcnt(0)
	v_mfma_f32_16x16x32_bf16 v[76:79], v[142:145], v[214:217], v[76:79]
	v_mfma_f32_16x16x32_bf16 v[68:71], v[150:153], v[214:217], v[68:71]
	s_barrier
	s_add_i32 s78, 0, 0x1c000
	s_add_i32 s2, s77, s53
	v_add_u32_e32 v161, s78, v139
	v_lshl_add_u64 v[154:155], v[154:155], 0, s[50:51]
	s_mov_b32 m0, s2
	ds_read_b128 v[218:221], v161
	ds_read_b128 v[226:229], v161 offset:2048
	ds_read_b128 v[222:225], v161 offset:1024
	ds_read_b128 v[230:233], v161 offset:3072
	global_load_lds_dwordx4 v[154:155], off
	v_lshl_add_u64 v[154:155], v[206:207], 0, s[50:51]
	s_add_i32 m0, s2, 0x2000
	s_nop 0
	global_load_lds_dwordx4 v[154:155], off
	s_barrier
	s_waitcnt lgkmcnt(3)
	v_mfma_f32_16x16x32_bf16 v[120:123], v[218:221], v[162:165], v[120:123]
	s_waitcnt lgkmcnt(2)
	v_mfma_f32_16x16x32_bf16 v[112:115], v[226:229], v[162:165], v[112:115]
	v_mfma_f32_16x16x32_bf16 v[104:107], v[218:221], v[170:173], v[104:107]
	v_mfma_f32_16x16x32_bf16 v[96:99], v[226:229], v[170:173], v[96:99]
	v_mfma_f32_16x16x32_bf16 v[88:91], v[218:221], v[178:181], v[88:91]
	v_mfma_f32_16x16x32_bf16 v[80:83], v[226:229], v[178:181], v[80:83]
	v_mfma_f32_16x16x32_bf16 v[72:75], v[218:221], v[186:189], v[72:75]
	v_mfma_f32_16x16x32_bf16 v[64:67], v[226:229], v[186:189], v[64:67]
	s_waitcnt lgkmcnt(1)
	v_mfma_f32_16x16x32_bf16 v[120:123], v[222:225], v[166:169], v[120:123]
	s_waitcnt lgkmcnt(0)
	v_mfma_f32_16x16x32_bf16 v[112:115], v[230:233], v[166:169], v[112:115]
	v_mfma_f32_16x16x32_bf16 v[104:107], v[222:225], v[174:177], v[104:107]
	v_mfma_f32_16x16x32_bf16 v[96:99], v[230:233], v[174:177], v[96:99]
	v_mfma_f32_16x16x32_bf16 v[88:91], v[222:225], v[182:185], v[88:91]
	v_mfma_f32_16x16x32_bf16 v[80:83], v[230:233], v[182:185], v[80:83]
	v_mfma_f32_16x16x32_bf16 v[72:75], v[222:225], v[214:217], v[72:75]
	v_mfma_f32_16x16x32_bf16 v[64:67], v[230:233], v[214:217], v[64:67]
	s_mov_b32 m0, s66
	v_lshl_add_u64 v[154:155], v[208:209], 0, s[50:51]
	s_barrier
	ds_read_b128 v[162:165], v141 offset:49152
	ds_read_b128 v[170:173], v141 offset:51200
	ds_read_b128 v[178:181], v141 offset:53248
	ds_read_b128 v[186:189], v141 offset:55296
	ds_read_b128 v[166:169], v141 offset:50176
	ds_read_b128 v[174:177], v141 offset:52224
	ds_read_b128 v[182:185], v141 offset:54272
	ds_read_b128 v[214:217], v141 offset:56320
	global_load_lds_dwordx4 v[154:155], off
	v_lshl_add_u64 v[154:155], v[234:235], 0, s[50:51]
	s_mov_b32 m0, s67
	s_nop 0
	global_load_lds_dwordx4 v[154:155], off
	s_barrier
	s_waitcnt lgkmcnt(7)
	v_mfma_f32_16x16x32_bf16 v[60:63], v[134:137], v[162:165], v[60:63]
	v_mfma_f32_16x16x32_bf16 v[52:55], v[146:149], v[162:165], v[52:55]
	s_waitcnt lgkmcnt(6)
	v_mfma_f32_16x16x32_bf16 v[44:47], v[134:137], v[170:173], v[44:47]
	v_mfma_f32_16x16x32_bf16 v[36:39], v[146:149], v[170:173], v[36:39]
	s_waitcnt lgkmcnt(5)
	v_mfma_f32_16x16x32_bf16 v[28:31], v[134:137], v[178:181], v[28:31]
	v_mfma_f32_16x16x32_bf16 v[20:23], v[146:149], v[178:181], v[20:23]
	s_waitcnt lgkmcnt(4)
	v_mfma_f32_16x16x32_bf16 v[12:15], v[134:137], v[186:189], v[12:15]
	v_mfma_f32_16x16x32_bf16 v[4:7], v[146:149], v[186:189], v[4:7]
	s_waitcnt lgkmcnt(3)
	v_mfma_f32_16x16x32_bf16 v[60:63], v[142:145], v[166:169], v[60:63]
	v_mfma_f32_16x16x32_bf16 v[52:55], v[150:153], v[166:169], v[52:55]
	s_waitcnt lgkmcnt(2)
	v_mfma_f32_16x16x32_bf16 v[44:47], v[142:145], v[174:177], v[44:47]
	v_mfma_f32_16x16x32_bf16 v[36:39], v[150:153], v[174:177], v[36:39]
	s_waitcnt lgkmcnt(1)
	v_mfma_f32_16x16x32_bf16 v[28:31], v[142:145], v[182:185], v[28:31]
	v_mfma_f32_16x16x32_bf16 v[20:23], v[150:153], v[182:185], v[20:23]
	s_waitcnt lgkmcnt(0)
	v_mfma_f32_16x16x32_bf16 v[12:15], v[142:145], v[214:217], v[12:15]
	v_mfma_f32_16x16x32_bf16 v[4:7], v[150:153], v[214:217], v[4:7]
	s_barrier
	s_add_u32 s2, s54, 0x40080
	s_addc_u32 s3, s55, 0
	s_add_i32 s54, s78, s53
	v_lshl_add_u64 v[134:135], s[2:3], 0, v[156:157]
	s_mov_b32 m0, s54
	s_nop 0
	global_load_lds_dwordx4 v[134:135], off
	v_lshl_add_u64 v[134:135], s[2:3], 0, v[128:129]
	s_add_i32 m0, s54, 0x2000
	s_nop 0
	global_load_lds_dwordx4 v[134:135], off
	s_waitcnt vmcnt(6)
	s_barrier
	v_mfma_f32_16x16x32_bf16 v[56:59], v[218:221], v[162:165], v[56:59]
	v_mfma_f32_16x16x32_bf16 v[48:51], v[226:229], v[162:165], v[48:51]
	v_mfma_f32_16x16x32_bf16 v[40:43], v[218:221], v[170:173], v[40:43]
	v_mfma_f32_16x16x32_bf16 v[32:35], v[226:229], v[170:173], v[32:35]
	v_mfma_f32_16x16x32_bf16 v[24:27], v[218:221], v[178:181], v[24:27]
	v_mfma_f32_16x16x32_bf16 v[16:19], v[226:229], v[178:181], v[16:19]
	v_mfma_f32_16x16x32_bf16 v[8:11], v[218:221], v[186:189], v[8:11]
	v_mfma_f32_16x16x32_bf16 v[0:3], v[226:229], v[186:189], v[0:3]
	v_mfma_f32_16x16x32_bf16 v[56:59], v[222:225], v[166:169], v[56:59]
	v_mfma_f32_16x16x32_bf16 v[48:51], v[230:233], v[166:169], v[48:51]
	v_mfma_f32_16x16x32_bf16 v[40:43], v[222:225], v[174:177], v[40:43]
	v_mfma_f32_16x16x32_bf16 v[32:35], v[230:233], v[174:177], v[32:35]
	v_mfma_f32_16x16x32_bf16 v[24:27], v[222:225], v[182:185], v[24:27]
	v_mfma_f32_16x16x32_bf16 v[16:19], v[230:233], v[182:185], v[16:19]
	v_mfma_f32_16x16x32_bf16 v[8:11], v[222:225], v[214:217], v[8:11]
	v_mfma_f32_16x16x32_bf16 v[0:3], v[230:233], v[214:217], v[0:3]
	s_add_i32 s73, s73, 2
	s_add_u32 s43, s43, 0x100
	s_addc_u32 s69, s69, 0
	s_add_u32 s6, s6, 0x100
	s_addc_u32 s7, s7, 0
	s_cmp_gt_u32 s73, 13
	s_barrier
	s_cbranch_scc1 .Lpost_555
.LBB0_555:
	s_add_u32 s2, s6, 0xfffc0080
	s_addc_u32 s3, s7, -1
	s_add_i32 s77, 0, 0x10000
	v_add_u32_e32 v150, s77, v139
	ds_read_b128 v[134:137], v150
	ds_read_b128 v[146:149], v150 offset:2048
	ds_read_b128 v[142:145], v150 offset:1024
	ds_read_b128 v[150:153], v150 offset:3072
	s_cmp_eq_u32 s73, 12
	s_cselect_b32 s3, s10, s3
	s_cselect_b32 s2, s24, s2
	s_cselect_b32 s55, s25, s69
	s_cselect_b32 s54, s41, s43
	v_lshl_add_u64 v[154:155], s[6:7], 0, v[132:133]
	s_add_i32 m0, s47, 0xc000
	ds_read_b128 v[162:165], v141
	ds_read_b128 v[170:173], v141 offset:2048
	ds_read_b128 v[178:181], v141 offset:4096
	ds_read_b128 v[186:189], v141 offset:6144
	ds_read_b128 v[166:169], v141 offset:1024
	ds_read_b128 v[174:177], v141 offset:3072
	ds_read_b128 v[182:185], v141 offset:5120
	ds_read_b128 v[214:217], v141 offset:7168
	global_load_lds_dwordx4 v[154:155], off
	v_lshl_add_u64 v[154:155], s[6:7], 0, v[130:131]
	s_add_i32 m0, s47, 0xe000
	s_nop 0
	global_load_lds_dwordx4 v[154:155], off
	s_waitcnt lgkmcnt(8)
	s_barrier
	s_waitcnt lgkmcnt(7)
	v_mfma_f32_16x16x32_bf16 v[124:127], v[134:137], v[162:165], v[124:127]
	v_mfma_f32_16x16x32_bf16 v[116:119], v[146:149], v[162:165], v[116:119]
	s_waitcnt lgkmcnt(6)
	v_mfma_f32_16x16x32_bf16 v[108:111], v[134:137], v[170:173], v[108:111]
	v_mfma_f32_16x16x32_bf16 v[100:103], v[146:149], v[170:173], v[100:103]
	s_waitcnt lgkmcnt(5)
	v_mfma_f32_16x16x32_bf16 v[92:95], v[134:137], v[178:181], v[92:95]
	v_mfma_f32_16x16x32_bf16 v[84:87], v[146:149], v[178:181], v[84:87]
	s_waitcnt lgkmcnt(4)
	v_mfma_f32_16x16x32_bf16 v[76:79], v[134:137], v[186:189], v[76:79]
	v_mfma_f32_16x16x32_bf16 v[68:71], v[146:149], v[186:189], v[68:71]
	s_waitcnt lgkmcnt(3)
	v_mfma_f32_16x16x32_bf16 v[124:127], v[142:145], v[166:169], v[124:127]
	v_mfma_f32_16x16x32_bf16 v[116:119], v[150:153], v[166:169], v[116:119]
	s_waitcnt lgkmcnt(2)
	v_mfma_f32_16x16x32_bf16 v[108:111], v[142:145], v[174:177], v[108:111]
	v_mfma_f32_16x16x32_bf16 v[100:103], v[150:153], v[174:177], v[100:103]
	s_waitcnt lgkmcnt(1)
	v_mfma_f32_16x16x32_bf16 v[92:95], v[142:145], v[182:185], v[92:95]
	v_mfma_f32_16x16x32_bf16 v[84:87], v[150:153], v[182:185], v[84:87]
	s_waitcnt lgkmcnt(0)
	v_mfma_f32_16x16x32_bf16 v[76:79], v[142:145], v[214:217], v[76:79]
	v_mfma_f32_16x16x32_bf16 v[68:71], v[150:153], v[214:217], v[68:71]
	s_barrier
	s_add_i32 s80, 0, 0x14000
	v_add_u32_e32 v154, s80, v139
	s_add_i32 s77, s77, s53
	ds_read_b128 v[218:221], v154
	ds_read_b128 v[226:229], v154 offset:2048
	ds_read_b128 v[222:225], v154 offset:1024
	ds_read_b128 v[230:233], v154 offset:3072
	v_lshl_add_u64 v[154:155], s[54:55], 0, v[156:157]
	s_mov_b32 m0, s77
	v_lshl_add_u64 v[206:207], s[54:55], 0, v[128:129]
	global_load_lds_dwordx4 v[154:155], off
	s_add_i32 m0, s77, 0x2000
	s_nop 0
	global_load_lds_dwordx4 v[206:207], off
	s_barrier
	s_waitcnt lgkmcnt(3)
	v_mfma_f32_16x16x32_bf16 v[120:123], v[218:221], v[162:165], v[120:123]
	s_waitcnt lgkmcnt(2)
	v_mfma_f32_16x16x32_bf16 v[112:115], v[226:229], v[162:165], v[112:115]
	v_mfma_f32_16x16x32_bf16 v[104:107], v[218:221], v[170:173], v[104:107]
	v_mfma_f32_16x16x32_bf16 v[96:99], v[226:229], v[170:173], v[96:99]
	v_mfma_f32_16x16x32_bf16 v[88:91], v[218:221], v[178:181], v[88:91]
	v_mfma_f32_16x16x32_bf16 v[80:83], v[226:229], v[178:181], v[80:83]
	v_mfma_f32_16x16x32_bf16 v[72:75], v[218:221], v[186:189], v[72:75]
	v_mfma_f32_16x16x32_bf16 v[64:67], v[226:229], v[186:189], v[64:67]
	s_waitcnt lgkmcnt(1)
	v_mfma_f32_16x16x32_bf16 v[120:123], v[222:225], v[166:169], v[120:123]
	s_waitcnt lgkmcnt(0)
	v_mfma_f32_16x16x32_bf16 v[112:115], v[230:233], v[166:169], v[112:115]
	v_mfma_f32_16x16x32_bf16 v[104:107], v[222:225], v[174:177], v[104:107]
	v_mfma_f32_16x16x32_bf16 v[96:99], v[230:233], v[174:177], v[96:99]
	v_mfma_f32_16x16x32_bf16 v[88:91], v[222:225], v[182:185], v[88:91]
	v_mfma_f32_16x16x32_bf16 v[80:83], v[230:233], v[182:185], v[80:83]
	v_mfma_f32_16x16x32_bf16 v[72:75], v[222:225], v[214:217], v[72:75]
	v_mfma_f32_16x16x32_bf16 v[64:67], v[230:233], v[214:217], v[64:67]
	s_mov_b32 m0, s47
	v_lshl_add_u64 v[208:209], s[2:3], 0, v[156:157]
	s_barrier
	ds_read_b128 v[162:165], v141 offset:16384
	ds_read_b128 v[170:173], v141 offset:18432
	ds_read_b128 v[178:181], v141 offset:20480
	ds_read_b128 v[186:189], v141 offset:22528
	ds_read_b128 v[166:169], v141 offset:17408
	ds_read_b128 v[174:177], v141 offset:19456
	ds_read_b128 v[182:185], v141 offset:21504
	ds_read_b128 v[214:217], v141 offset:23552
	global_load_lds_dwordx4 v[208:209], off
	v_lshl_add_u64 v[234:235], s[2:3], 0, v[128:129]
	s_mov_b32 m0, s49
	s_nop 0
	global_load_lds_dwordx4 v[234:235], off
	s_barrier
	s_waitcnt lgkmcnt(7)
	v_mfma_f32_16x16x32_bf16 v[60:63], v[134:137], v[162:165], v[60:63]
	v_mfma_f32_16x16x32_bf16 v[52:55], v[146:149], v[162:165], v[52:55]
	s_waitcnt lgkmcnt(6)
	v_mfma_f32_16x16x32_bf16 v[44:47], v[134:137], v[170:173], v[44:47]
	v_mfma_f32_16x16x32_bf16 v[36:39], v[146:149], v[170:173], v[36:39]
	s_waitcnt lgkmcnt(5)
	v_mfma_f32_16x16x32_bf16 v[28:31], v[134:137], v[178:181], v[28:31]
	v_mfma_f32_16x16x32_bf16 v[20:23], v[146:149], v[178:181], v[20:23]
	s_waitcnt lgkmcnt(4)
	v_mfma_f32_16x16x32_bf16 v[12:15], v[134:137], v[186:189], v[12:15]
	v_mfma_f32_16x16x32_bf16 v[4:7], v[146:149], v[186:189], v[4:7]
	s_waitcnt lgkmcnt(3)
	v_mfma_f32_16x16x32_bf16 v[60:63], v[142:145], v[166:169], v[60:63]
	v_mfma_f32_16x16x32_bf16 v[52:55], v[150:153], v[166:169], v[52:55]
	s_waitcnt lgkmcnt(2)
	v_mfma_f32_16x16x32_bf16 v[44:47], v[142:145], v[174:177], v[44:47]
	v_mfma_f32_16x16x32_bf16 v[36:39], v[150:153], v[174:177], v[36:39]
	s_waitcnt lgkmcnt(1)
	v_mfma_f32_16x16x32_bf16 v[28:31], v[142:145], v[182:185], v[28:31]
	v_mfma_f32_16x16x32_bf16 v[20:23], v[150:153], v[182:185], v[20:23]
	s_waitcnt lgkmcnt(0)
	v_mfma_f32_16x16x32_bf16 v[12:15], v[142:145], v[214:217], v[12:15]
	v_mfma_f32_16x16x32_bf16 v[4:7], v[150:153], v[214:217], v[4:7]
	s_barrier
	s_add_u32 s78, s54, 0x40000
	s_addc_u32 s79, s55, 0
	s_add_i32 s77, s80, s53
	v_lshl_add_u64 v[134:135], s[78:79], 0, v[156:157]
	s_mov_b32 m0, s77
	s_nop 0
	global_load_lds_dwordx4 v[134:135], off
	v_lshl_add_u64 v[134:135], s[78:79], 0, v[128:129]
	s_add_i32 m0, s77, 0x2000
	s_nop 0
	global_load_lds_dwordx4 v[134:135], off
	s_waitcnt vmcnt(6)
	s_barrier
	v_mfma_f32_16x16x32_bf16 v[56:59], v[218:221], v[162:165], v[56:59]
	v_mfma_f32_16x16x32_bf16 v[48:51], v[226:229], v[162:165], v[48:51]
	v_mfma_f32_16x16x32_bf16 v[40:43], v[218:221], v[170:173], v[40:43]
	v_mfma_f32_16x16x32_bf16 v[32:35], v[226:229], v[170:173], v[32:35]
	v_mfma_f32_16x16x32_bf16 v[24:27], v[218:221], v[178:181], v[24:27]
	v_mfma_f32_16x16x32_bf16 v[16:19], v[226:229], v[178:181], v[16:19]
	v_mfma_f32_16x16x32_bf16 v[8:11], v[218:221], v[186:189], v[8:11]
	v_mfma_f32_16x16x32_bf16 v[0:3], v[226:229], v[186:189], v[0:3]
	v_mfma_f32_16x16x32_bf16 v[56:59], v[222:225], v[166:169], v[56:59]
	v_mfma_f32_16x16x32_bf16 v[48:51], v[230:233], v[166:169], v[48:51]
	v_mfma_f32_16x16x32_bf16 v[40:43], v[222:225], v[174:177], v[40:43]
	v_mfma_f32_16x16x32_bf16 v[32:35], v[230:233], v[174:177], v[32:35]
	v_mfma_f32_16x16x32_bf16 v[24:27], v[222:225], v[182:185], v[24:27]
	v_mfma_f32_16x16x32_bf16 v[16:19], v[230:233], v[182:185], v[16:19]
	v_mfma_f32_16x16x32_bf16 v[8:11], v[222:225], v[214:217], v[8:11]
	v_mfma_f32_16x16x32_bf16 v[0:3], v[230:233], v[214:217], v[0:3]
	s_add_i32 s77, 0, 0x18000
	v_add_u32_e32 v150, s77, v139
	s_barrier
	ds_read_b128 v[134:137], v150
	ds_read_b128 v[146:149], v150 offset:2048
	ds_read_b128 v[142:145], v150 offset:1024
	ds_read_b128 v[150:153], v150 offset:3072
	s_add_u32 s2, s2, 0x40000
	s_addc_u32 s3, s3, 0
	s_mov_b32 m0, s62
	v_lshl_add_u64 v[218:219], s[2:3], 0, v[156:157]
	ds_read_b128 v[162:165], v141 offset:32768
	ds_read_b128 v[170:173], v141 offset:34816
	ds_read_b128 v[178:181], v141 offset:36864
	ds_read_b128 v[186:189], v141 offset:38912
	ds_read_b128 v[166:169], v141 offset:33792
	ds_read_b128 v[174:177], v141 offset:35840
	ds_read_b128 v[182:185], v141 offset:37888
	ds_read_b128 v[214:217], v141 offset:39936
	global_load_lds_dwordx4 v[218:219], off
	v_lshl_add_u64 v[218:219], s[2:3], 0, v[128:129]
	s_mov_b32 m0, s63
	s_nop 0
	global_load_lds_dwordx4 v[218:219], off
	s_waitcnt lgkmcnt(8)
	s_barrier
	s_waitcnt lgkmcnt(7)
	v_mfma_f32_16x16x32_bf16 v[124:127], v[134:137], v[162:165], v[124:127]
	v_mfma_f32_16x16x32_bf16 v[116:119], v[146:149], v[162:165], v[116:119]
	s_waitcnt lgkmcnt(6)
	v_mfma_f32_16x16x32_bf16 v[108:111], v[134:137], v[170:173], v[108:111]
	v_mfma_f32_16x16x32_bf16 v[100:103], v[146:149], v[170:173], v[100:103]
	s_waitcnt lgkmcnt(5)
	v_mfma_f32_16x16x32_bf16 v[92:95], v[134:137], v[178:181], v[92:95]
	v_mfma_f32_16x16x32_bf16 v[84:87], v[146:149], v[178:181], v[84:87]
	s_waitcnt lgkmcnt(4)
	v_mfma_f32_16x16x32_bf16 v[76:79], v[134:137], v[186:189], v[76:79]
	v_mfma_f32_16x16x32_bf16 v[68:71], v[146:149], v[186:189], v[68:71]
	s_waitcnt lgkmcnt(3)
	v_mfma_f32_16x16x32_bf16 v[124:127], v[142:145], v[166:169], v[124:127]
	v_mfma_f32_16x16x32_bf16 v[116:119], v[150:153], v[166:169], v[116:119]
	s_waitcnt lgkmcnt(2)
	v_mfma_f32_16x16x32_bf16 v[108:111], v[142:145], v[174:177], v[108:111]
	v_mfma_f32_16x16x32_bf16 v[100:103], v[150:153], v[174:177], v[100:103]
	s_waitcnt lgkmcnt(1)
	v_mfma_f32_16x16x32_bf16 v[92:95], v[142:145], v[182:185], v[92:95]
	v_mfma_f32_16x16x32_bf16 v[84:87], v[150:153], v[182:185], v[84:87]
	s_waitcnt lgkmcnt(0)
	v_mfma_f32_16x16x32_bf16 v[76:79], v[142:145], v[214:217], v[76:79]
	v_mfma_f32_16x16x32_bf16 v[68:71], v[150:153], v[214:217], v[68:71]
	s_barrier
	s_add_i32 s78, 0, 0x1c000
	s_add_i32 s2, s77, s53
	v_add_u32_e32 v161, s78, v139
	v_lshl_add_u64 v[154:155], v[154:155], 0, s[50:51]
	s_mov_b32 m0, s2
	ds_read_b128 v[218:221], v161
	ds_read_b128 v[226:229], v161 offset:2048
	ds_read_b128 v[222:225], v161 offset:1024
	ds_read_b128 v[230:233], v161 offset:3072
	global_load_lds_dwordx4 v[154:155], off
	v_lshl_add_u64 v[154:155], v[206:207], 0, s[50:51]
	s_add_i32 m0, s2, 0x2000
	s_nop 0
	global_load_lds_dwordx4 v[154:155], off
	s_barrier
	s_waitcnt lgkmcnt(3)
	v_mfma_f32_16x16x32_bf16 v[120:123], v[218:221], v[162:165], v[120:123]
	s_waitcnt lgkmcnt(2)
	v_mfma_f32_16x16x32_bf16 v[112:115], v[226:229], v[162:165], v[112:115]
	v_mfma_f32_16x16x32_bf16 v[104:107], v[218:221], v[170:173], v[104:107]
	v_mfma_f32_16x16x32_bf16 v[96:99], v[226:229], v[170:173], v[96:99]
	v_mfma_f32_16x16x32_bf16 v[88:91], v[218:221], v[178:181], v[88:91]
	v_mfma_f32_16x16x32_bf16 v[80:83], v[226:229], v[178:181], v[80:83]
	v_mfma_f32_16x16x32_bf16 v[72:75], v[218:221], v[186:189], v[72:75]
	v_mfma_f32_16x16x32_bf16 v[64:67], v[226:229], v[186:189], v[64:67]
	s_waitcnt lgkmcnt(1)
	v_mfma_f32_16x16x32_bf16 v[120:123], v[222:225], v[166:169], v[120:123]
	s_waitcnt lgkmcnt(0)
	v_mfma_f32_16x16x32_bf16 v[112:115], v[230:233], v[166:169], v[112:115]
	v_mfma_f32_16x16x32_bf16 v[104:107], v[222:225], v[174:177], v[104:107]
	v_mfma_f32_16x16x32_bf16 v[96:99], v[230:233], v[174:177], v[96:99]
	v_mfma_f32_16x16x32_bf16 v[88:91], v[222:225], v[182:185], v[88:91]
	v_mfma_f32_16x16x32_bf16 v[80:83], v[230:233], v[182:185], v[80:83]
	v_mfma_f32_16x16x32_bf16 v[72:75], v[222:225], v[214:217], v[72:75]
	v_mfma_f32_16x16x32_bf16 v[64:67], v[230:233], v[214:217], v[64:67]
	s_mov_b32 m0, s66
	v_lshl_add_u64 v[154:155], v[208:209], 0, s[50:51]
	s_barrier
	ds_read_b128 v[162:165], v141 offset:49152
	ds_read_b128 v[170:173], v141 offset:51200
	ds_read_b128 v[178:181], v141 offset:53248
	ds_read_b128 v[186:189], v141 offset:55296
	ds_read_b128 v[166:169], v141 offset:50176
	ds_read_b128 v[174:177], v141 offset:52224
	ds_read_b128 v[182:185], v141 offset:54272
	ds_read_b128 v[214:217], v141 offset:56320
	global_load_lds_dwordx4 v[154:155], off
	v_lshl_add_u64 v[154:155], v[234:235], 0, s[50:51]
	s_mov_b32 m0, s67
	s_nop 0
	global_load_lds_dwordx4 v[154:155], off
	s_barrier
	s_waitcnt lgkmcnt(7)
	v_mfma_f32_16x16x32_bf16 v[60:63], v[134:137], v[162:165], v[60:63]
	v_mfma_f32_16x16x32_bf16 v[52:55], v[146:149], v[162:165], v[52:55]
	s_waitcnt lgkmcnt(6)
	v_mfma_f32_16x16x32_bf16 v[44:47], v[134:137], v[170:173], v[44:47]
	v_mfma_f32_16x16x32_bf16 v[36:39], v[146:149], v[170:173], v[36:39]
	s_waitcnt lgkmcnt(5)
	v_mfma_f32_16x16x32_bf16 v[28:31], v[134:137], v[178:181], v[28:31]
	v_mfma_f32_16x16x32_bf16 v[20:23], v[146:149], v[178:181], v[20:23]
	s_waitcnt lgkmcnt(4)
	v_mfma_f32_16x16x32_bf16 v[12:15], v[134:137], v[186:189], v[12:15]
	v_mfma_f32_16x16x32_bf16 v[4:7], v[146:149], v[186:189], v[4:7]
	s_waitcnt lgkmcnt(3)
	v_mfma_f32_16x16x32_bf16 v[60:63], v[142:145], v[166:169], v[60:63]
	v_mfma_f32_16x16x32_bf16 v[52:55], v[150:153], v[166:169], v[52:55]
	s_waitcnt lgkmcnt(2)
	v_mfma_f32_16x16x32_bf16 v[44:47], v[142:145], v[174:177], v[44:47]
	v_mfma_f32_16x16x32_bf16 v[36:39], v[150:153], v[174:177], v[36:39]
	s_waitcnt lgkmcnt(1)
	v_mfma_f32_16x16x32_bf16 v[28:31], v[142:145], v[182:185], v[28:31]
	v_mfma_f32_16x16x32_bf16 v[20:23], v[150:153], v[182:185], v[20:23]
	s_waitcnt lgkmcnt(0)
	v_mfma_f32_16x16x32_bf16 v[12:15], v[142:145], v[214:217], v[12:15]
	v_mfma_f32_16x16x32_bf16 v[4:7], v[150:153], v[214:217], v[4:7]
	s_barrier
	s_add_u32 s2, s54, 0x40080
	s_addc_u32 s3, s55, 0
	s_add_i32 s54, s78, s53
	v_lshl_add_u64 v[134:135], s[2:3], 0, v[156:157]
	s_mov_b32 m0, s54
	s_nop 0
	global_load_lds_dwordx4 v[134:135], off
	v_lshl_add_u64 v[134:135], s[2:3], 0, v[128:129]
	s_add_i32 m0, s54, 0x2000
	s_nop 0
	global_load_lds_dwordx4 v[134:135], off
	s_waitcnt vmcnt(6)
	s_barrier
	v_mfma_f32_16x16x32_bf16 v[56:59], v[218:221], v[162:165], v[56:59]
	v_mfma_f32_16x16x32_bf16 v[48:51], v[226:229], v[162:165], v[48:51]
	v_mfma_f32_16x16x32_bf16 v[40:43], v[218:221], v[170:173], v[40:43]
	v_mfma_f32_16x16x32_bf16 v[32:35], v[226:229], v[170:173], v[32:35]
	v_mfma_f32_16x16x32_bf16 v[24:27], v[218:221], v[178:181], v[24:27]
	v_mfma_f32_16x16x32_bf16 v[16:19], v[226:229], v[178:181], v[16:19]
	v_mfma_f32_16x16x32_bf16 v[8:11], v[218:221], v[186:189], v[8:11]
	v_mfma_f32_16x16x32_bf16 v[0:3], v[226:229], v[186:189], v[0:3]
	v_mfma_f32_16x16x32_bf16 v[56:59], v[222:225], v[166:169], v[56:59]
	v_mfma_f32_16x16x32_bf16 v[48:51], v[230:233], v[166:169], v[48:51]
	v_mfma_f32_16x16x32_bf16 v[40:43], v[222:225], v[174:177], v[40:43]
	v_mfma_f32_16x16x32_bf16 v[32:35], v[230:233], v[174:177], v[32:35]
	v_mfma_f32_16x16x32_bf16 v[24:27], v[222:225], v[182:185], v[24:27]
	v_mfma_f32_16x16x32_bf16 v[16:19], v[230:233], v[182:185], v[16:19]
	v_mfma_f32_16x16x32_bf16 v[8:11], v[222:225], v[214:217], v[8:11]
	v_mfma_f32_16x16x32_bf16 v[0:3], v[230:233], v[214:217], v[0:3]
	s_add_i32 s73, s73, 2
	s_add_u32 s43, s43, 0x100
	s_addc_u32 s69, s69, 0
	s_add_u32 s6, s6, 0x100
	s_addc_u32 s7, s7, 0
	s_cmp_gt_u32 s73, 13
	s_barrier
	s_cbranch_scc0 .LBB0_555
